# combination: first K-iteration peeled with C=0 (no accumulator zeroing), relaxed first-iteration waits in all six GEMM loops, 8-byte aligned MFMA blocks, single-XCD barriers without L2 writeback
# speedup vs baseline: 1.0051x; 1.0051x over previous
; #define PG8_STAGE(bufoff, gbase, voff) do { _Pragma("unroll") for (int _i = 0; _i < 2; ++_i) \
;         __builtin_amdgcn_global_load_lds((const unsigned*)((const char*)(gbase) + (voff)[_i]), (PG8_LAS unsigned*)(lds + (bufoff) + ldsw + _i * 8192), 16, 0, 0); } while (0)
; #define PG8_LDA(dst, b, h) do { _Pragma("unroll") for (int m = 0; m < 4; ++m) _Pragma("unroll") for (int k = 0; k < 2; ++k) dst[m][k] = *(const PG8_LAS bf16x8*)(lds + PG8_SA(b, h) + aoff + m * 2048 + k * 1024); } while (0)
; #define PG8_LDB(dst, b, h) do { _Pragma("unroll") for (int n = 0; n < 2; ++n) _Pragma("unroll") for (int k = 0; k < 2; ++k) dst[n][k] = *(const PG8_LAS bf16x8*)(lds + PG8_SB(b, h) + boff + n * 2048 + k * 1024); } while (0)
; #define PG8_WAIT_L(n) asm volatile("s_waitcnt lgkmcnt(" #n ")" ::: "memory")
; #define PG8_WAIT_V_SEL(sel) asm volatile("s_cmp_eq_u32 %0, 0\n\ts_cbranch_scc1 .Lw8_%=\n\ts_waitcnt vmcnt(22)\n\ts_branch .Lwd_%=\n.Lw8_%=:\n\ts_waitcnt vmcnt(8)\n.Lwd_%=:" :: "s"(sel) : "memory", "scc")
;     ...
;         const char* nA = has_next ? (const char*)g.A + (size_t)nxt.pm * tstep : cA; const char* nB = has_next ? (const char*)g.Bt + (size_t)nxt.pn * tstep : cB;
;         for (int t = 0; t < nt * KREP; t += 2) {
;             const bool last = (t == nt * KREP - 2);
;             const int t1w = KREP > 1 ? ((t + 1) & (nt - 1)) : t + 1, t2w = KREP > 1 ? ((t + 2) & (nt - 1)) : t + 2;
;             const char* a1 = cA + (size_t)t1w * kstep;
;             const char* a2 = last ? nA : cA + (size_t)t2w * kstep; const char* b2 = last ? nB : cB + (size_t)t2w * kstep;
;             const char* a3 = a2 + kstep; const char* b3 = b2 + kstep;
;             if (last && has_next) S.a_ready(nxt);
;             const int relax = __builtin_amdgcn_readfirstlane((MK_RELAXW && t == 0 && ui > 0) ? 1 : 0);
;             if constexpr (SP2) {
;             PG8_LDB(B0, 0, 0); PG8_LDB(B1, 0, 1); PG8_SCHED; PG8_LDA(At, 0, 0); PG8_STAGE(PG8_SA(1, 1), a1 + hstep, voffA);
;             PG8_WAIT_V_SEL(relax);
;             PG8_WAIT_L(0); PG8_BAR; PG8_MMA(0, 0, At, B0); PG8_MMA(0, 1, At, B1); PG8_BAR; PG8_SCHED;
;             PG8_LDA(At, 0, 1); PG8_STAGE(PG8_SB(0, 0), b2, voffB); PG8_STAGE(PG8_SB(0, 1), b2 + hstep, voffB); PG8_STAGE(PG8_SA(0, 0), a2, voffA);
;             PG8_WAIT_V_SEL(relax);
;             PG8_WAIT_L(0); PG8_BAR; PG8_MMA(1, 0, At, B0); PG8_MMA(1, 1, At, B1); PG8_BAR; PG8_SCHED;
.LBB0_233:
	s_ashr_i32 s69, s68, 31
	s_lshl_b64 s[0:1], s[68:69], 20
	s_add_u32 s70, s51, s0
	s_addc_u32 s71, s84, s1
	s_and_b64 s[0:1], s[6:7], exec
	s_cselect_b32 s19, s71, s79
	s_cselect_b32 s20, s70, s78
	s_ashr_i32 s67, s66, 31
	s_lshl_b64 s[0:1], s[66:67], 20
	s_add_u32 s72, s85, s0
	s_addc_u32 s73, s86, s1
	s_and_b64 s[0:1], s[6:7], exec
	s_cselect_b32 s24, s73, s81
	s_cselect_b32 s31, s72, s80
	s_add_u32 s78, s78, 0x80080
	s_addc_u32 s79, s79, 0
	s_add_u32 s33, s80, 0x100
	s_addc_u32 s35, s81, 0
	s_mov_b32 s37, -2
	s_waitcnt lgkmcnt(0)
	v_add_u32_e32 v168, 0x10000, v181
	s_add_u32 s0, s78, 0xfff80080
	s_addc_u32 s1, s79, -1
	s_add_i32 s40, 0, 0x10000
	s_cmp_eq_u32 s37, 28
	s_cselect_b32 s83, s19, s1
	s_cselect_b32 s82, s20, s0
	s_cselect_b32 s81, s24, s35
	s_cselect_b32 s80, s31, s33
	s_add_i32 s41, 0, 0x14000
	ds_read_b128 v[142:145], v168
	ds_read_b128 v[146:149], v168 offset:1024
	ds_read_b128 v[150:153], v168 offset:2048
	ds_read_b128 v[154:157], v168 offset:3072
	ds_read_b128 v[158:161], v168 offset:16384
	ds_read_b128 v[162:165], v168 offset:17408
	ds_read_b128 v[174:177], v168 offset:18432
	ds_read_b128 v[188:191], v168 offset:19456
	s_add_i32 m0, s75, 0xc000
	ds_read_b128 v[198:201], v196
	ds_read_b128 v[202:205], v196 offset:1024
	ds_read_b128 v[206:209], v196 offset:2048
	ds_read_b128 v[210:213], v196 offset:3072
	ds_read_b128 v[214:217], v196 offset:4096
	ds_read_b128 v[218:221], v196 offset:5120
	ds_read_b128 v[222:225], v196 offset:6144
	ds_read_b128 v[226:229], v196 offset:7168
	global_load_lds_dwordx4 v138, s[78:79]
	s_add_i32 m0, s75, 0xe000
	s_nop 0
	global_load_lds_dwordx4 v140, s[78:79]
	s_cmp_lg_u32 s18, 0
	s_cbranch_scc1 .Lrlx_gi_0
	s_waitcnt vmcnt(8)
.Lrlx_gi_0_b:
	s_waitcnt lgkmcnt(0)
	.p2align 3
	s_setprio 1
	s_barrier
	v_mfma_f32_16x16x32_bf16 v[126:129], v[142:145], v[198:201], 0
	v_mfma_f32_16x16x32_bf16 v[126:129], v[146:149], v[202:205], v[126:129]
	v_mfma_f32_16x16x32_bf16 v[122:125], v[142:145], v[206:209], 0
	v_mfma_f32_16x16x32_bf16 v[122:125], v[146:149], v[210:213], v[122:125]
	v_mfma_f32_16x16x32_bf16 v[118:121], v[142:145], v[214:217], 0
	v_mfma_f32_16x16x32_bf16 v[118:121], v[146:149], v[218:221], v[118:121]
	v_mfma_f32_16x16x32_bf16 v[114:117], v[142:145], v[222:225], 0
	v_mfma_f32_16x16x32_bf16 v[114:117], v[146:149], v[226:229], v[114:117]
	v_mfma_f32_16x16x32_bf16 v[98:101], v[150:153], v[222:225], 0
	v_mfma_f32_16x16x32_bf16 v[98:101], v[154:157], v[226:229], v[98:101]
	v_mfma_f32_16x16x32_bf16 v[102:105], v[150:153], v[214:217], 0
	v_mfma_f32_16x16x32_bf16 v[102:105], v[154:157], v[218:221], v[102:105]
	v_mfma_f32_16x16x32_bf16 v[106:109], v[150:153], v[206:209], 0
	v_mfma_f32_16x16x32_bf16 v[106:109], v[154:157], v[210:213], v[106:109]
	v_mfma_f32_16x16x32_bf16 v[110:113], v[150:153], v[198:201], 0
	v_mfma_f32_16x16x32_bf16 v[110:113], v[154:157], v[202:205], v[110:113]
	v_mfma_f32_16x16x32_bf16 v[82:85], v[158:161], v[198:201], 0
	v_mfma_f32_16x16x32_bf16 v[82:85], v[162:165], v[202:205], v[82:85]
	v_mfma_f32_16x16x32_bf16 v[70:73], v[158:161], v[206:209], 0
	v_mfma_f32_16x16x32_bf16 v[70:73], v[162:165], v[210:213], v[70:73]
	v_mfma_f32_16x16x32_bf16 v[66:69], v[158:161], v[214:217], 0
	v_mfma_f32_16x16x32_bf16 v[66:69], v[162:165], v[218:221], v[66:69]
	v_mfma_f32_16x16x32_bf16 v[58:61], v[158:161], v[222:225], 0
	v_mfma_f32_16x16x32_bf16 v[58:61], v[162:165], v[226:229], v[58:61]
	v_mfma_f32_16x16x32_bf16 v[18:21], v[174:177], v[222:225], 0
	v_mfma_f32_16x16x32_bf16 v[18:21], v[188:191], v[226:229], v[18:21]
	v_mfma_f32_16x16x32_bf16 v[22:25], v[174:177], v[214:217], 0
	v_mfma_f32_16x16x32_bf16 v[22:25], v[188:191], v[218:221], v[22:25]
	v_mfma_f32_16x16x32_bf16 v[26:29], v[174:177], v[206:209], 0
	v_mfma_f32_16x16x32_bf16 v[26:29], v[188:191], v[210:213], v[26:29]
	v_mfma_f32_16x16x32_bf16 v[30:33], v[174:177], v[198:201], 0
	v_mfma_f32_16x16x32_bf16 v[30:33], v[188:191], v[202:205], v[30:33]
	s_barrier
	s_setprio 0
	s_add_i32 s0, s40, s87
	s_mov_b32 m0, s0
	ds_read_b128 v[198:201], v196 offset:16384
	ds_read_b128 v[202:205], v196 offset:17408
	ds_read_b128 v[206:209], v196 offset:18432
	ds_read_b128 v[210:213], v196 offset:19456
	ds_read_b128 v[214:217], v196 offset:20480
	ds_read_b128 v[218:221], v196 offset:21504
	ds_read_b128 v[222:225], v196 offset:22528
	ds_read_b128 v[226:229], v196 offset:23552
	global_load_lds_dwordx4 v182, s[80:81]
	s_add_i32 m0, s0, 0x2000
	s_add_u32 s0, s80, 0x80000
	s_addc_u32 s1, s81, 0
	s_add_i32 s40, s41, s87
	global_load_lds_dwordx4 v134, s[80:81]
	s_mov_b32 m0, s40
	s_nop 0
	global_load_lds_dwordx4 v182, s[0:1]
	s_add_i32 m0, s40, 0x2000
	s_nop 0
	global_load_lds_dwordx4 v134, s[0:1]
	s_mov_b32 m0, s75
	s_nop 0
	global_load_lds_dwordx4 v130, s[82:83]
	s_mov_b32 m0, s88
	s_nop 0
	global_load_lds_dwordx4 v132, s[82:83]
	s_cmp_lg_u32 s18, 0
	s_cbranch_scc1 .Lrlx_gi_1
	s_waitcnt vmcnt(8)
; #define PG8_STAGE(bufoff, gbase, voff) do { _Pragma("unroll") for (int _i = 0; _i < 2; ++_i) \
;         __builtin_amdgcn_global_load_lds((const unsigned*)((const char*)(gbase) + (voff)[_i]), (PG8_LAS unsigned*)(lds + (bufoff) + ldsw + _i * 8192), 16, 0, 0); } while (0)
; #define PG8_LDA(dst, b, h) do { _Pragma("unroll") for (int m = 0; m < 4; ++m) _Pragma("unroll") for (int k = 0; k < 2; ++k) dst[m][k] = *(const PG8_LAS bf16x8*)(lds + PG8_SA(b, h) + aoff + m * 2048 + k * 1024); } while (0)
; #define PG8_LDB(dst, b, h) do { _Pragma("unroll") for (int n = 0; n < 2; ++n) _Pragma("unroll") for (int k = 0; k < 2; ++k) dst[n][k] = *(const PG8_LAS bf16x8*)(lds + PG8_SB(b, h) + boff + n * 2048 + k * 1024); } while (0)
; #define PG8_WAIT_V(n) asm volatile("s_waitcnt vmcnt(" #n ")" ::: "memory")
; #define PG8_WAIT_L(n) asm volatile("s_waitcnt lgkmcnt(" #n ")" ::: "memory")
; #define PG8_WAIT_V_SEL(sel) asm volatile("s_cmp_eq_u32 %0, 0\n\ts_cbranch_scc1 .Lw8_%=\n\ts_waitcnt vmcnt(22)\n\ts_branch .Lwd_%=\n.Lw8_%=:\n\ts_waitcnt vmcnt(8)\n.Lwd_%=:" :: "s"(sel) : "memory", "scc")
; #define PG8_BAR __builtin_amdgcn_s_barrier()
; #define PG8_SCHED __builtin_amdgcn_sched_barrier(0)
;     ...
;             PG8_WAIT_L(0); PG8_BAR; PG8_MMA(0, 0, At, B0); PG8_MMA(0, 1, At, B1); PG8_BAR; PG8_SCHED;
;             PG8_LDA(At, 0, 1); PG8_STAGE(PG8_SB(0, 0), b2, voffB); PG8_STAGE(PG8_SB(0, 1), b2 + hstep, voffB); PG8_STAGE(PG8_SA(0, 0), a2, voffA);
;             PG8_WAIT_V_SEL(relax);
;             PG8_WAIT_L(0); PG8_BAR; PG8_MMA(1, 0, At, B0); PG8_MMA(1, 1, At, B1); PG8_BAR; PG8_SCHED;
;             PG8_LDB(B0, 1, 0); PG8_LDB(B1, 1, 1); PG8_SCHED; PG8_LDA(At, 1, 0); PG8_STAGE(PG8_SA(0, 1), a2 + hstep, voffA);
;             PG8_WAIT_V(8); PG8_WAIT_L(0); PG8_BAR; PG8_MMA(0, 0, At, B0); PG8_MMA(0, 1, At, B1); PG8_BAR; PG8_SCHED;
.Lrlx_gi_1_b:
	s_waitcnt lgkmcnt(0)
	.p2align 3
	s_setprio 1
	s_barrier
	v_mfma_f32_16x16x32_bf16 v[94:97], v[142:145], v[198:201], 0
	v_mfma_f32_16x16x32_bf16 v[94:97], v[146:149], v[202:205], v[94:97]
	v_mfma_f32_16x16x32_bf16 v[90:93], v[142:145], v[206:209], 0
	v_mfma_f32_16x16x32_bf16 v[90:93], v[146:149], v[210:213], v[90:93]
	v_mfma_f32_16x16x32_bf16 v[86:89], v[142:145], v[214:217], 0
	v_mfma_f32_16x16x32_bf16 v[86:89], v[146:149], v[218:221], v[86:89]
	v_mfma_f32_16x16x32_bf16 v[78:81], v[142:145], v[222:225], 0
	v_mfma_f32_16x16x32_bf16 v[78:81], v[146:149], v[226:229], v[78:81]
	v_mfma_f32_16x16x32_bf16 v[50:53], v[150:153], v[222:225], 0
	v_mfma_f32_16x16x32_bf16 v[50:53], v[154:157], v[226:229], v[50:53]
	v_mfma_f32_16x16x32_bf16 v[54:57], v[150:153], v[214:217], 0
	v_mfma_f32_16x16x32_bf16 v[54:57], v[154:157], v[218:221], v[54:57]
	v_mfma_f32_16x16x32_bf16 v[62:65], v[150:153], v[206:209], 0
	v_mfma_f32_16x16x32_bf16 v[62:65], v[154:157], v[210:213], v[62:65]
	v_mfma_f32_16x16x32_bf16 v[74:77], v[150:153], v[198:201], 0
	v_mfma_f32_16x16x32_bf16 v[74:77], v[154:157], v[202:205], v[74:77]
	v_mfma_f32_16x16x32_bf16 v[46:49], v[158:161], v[198:201], 0
	v_mfma_f32_16x16x32_bf16 v[46:49], v[162:165], v[202:205], v[46:49]
	v_mfma_f32_16x16x32_bf16 v[42:45], v[158:161], v[206:209], 0
	v_mfma_f32_16x16x32_bf16 v[42:45], v[162:165], v[210:213], v[42:45]
	v_mfma_f32_16x16x32_bf16 v[38:41], v[158:161], v[214:217], 0
	v_mfma_f32_16x16x32_bf16 v[38:41], v[162:165], v[218:221], v[38:41]
	v_mfma_f32_16x16x32_bf16 v[34:37], v[158:161], v[222:225], 0
	v_mfma_f32_16x16x32_bf16 v[34:37], v[162:165], v[226:229], v[34:37]
	v_mfma_f32_16x16x32_bf16 v[2:5], v[174:177], v[222:225], 0
	v_mfma_f32_16x16x32_bf16 v[2:5], v[188:191], v[226:229], v[2:5]
	v_mfma_f32_16x16x32_bf16 v[6:9], v[174:177], v[214:217], 0
	v_mfma_f32_16x16x32_bf16 v[6:9], v[188:191], v[218:221], v[6:9]
	v_mfma_f32_16x16x32_bf16 v[10:13], v[174:177], v[206:209], 0
	v_mfma_f32_16x16x32_bf16 v[10:13], v[188:191], v[210:213], v[10:13]
	v_mfma_f32_16x16x32_bf16 v[14:17], v[174:177], v[198:201], 0
	v_mfma_f32_16x16x32_bf16 v[14:17], v[188:191], v[202:205], v[14:17]
	s_barrier
	s_setprio 0
	s_add_i32 s40, 0, 0x18000
	s_add_i32 s41, 0, 0x1c000
	ds_read_b128 v[142:145], v168 offset:32768
	ds_read_b128 v[146:149], v168 offset:33792
	ds_read_b128 v[150:153], v168 offset:34816
	ds_read_b128 v[154:157], v168 offset:35840
	ds_read_b128 v[158:161], v168 offset:49152
	ds_read_b128 v[162:165], v168 offset:50176
	ds_read_b128 v[174:177], v168 offset:51200
	ds_read_b128 v[188:191], v168 offset:52224
	s_add_u32 s0, s82, 0x80000
	s_addc_u32 s1, s83, 0
	s_mov_b32 m0, s89
	ds_read_b128 v[198:201], v196 offset:32768
	ds_read_b128 v[202:205], v196 offset:33792
	ds_read_b128 v[206:209], v196 offset:34816
	ds_read_b128 v[210:213], v196 offset:35840
	ds_read_b128 v[214:217], v196 offset:36864
	ds_read_b128 v[218:221], v196 offset:37888
	ds_read_b128 v[222:225], v196 offset:38912
	ds_read_b128 v[226:229], v196 offset:39936
	global_load_lds_dwordx4 v130, s[0:1]
	s_mov_b32 m0, s90
	s_nop 0
	global_load_lds_dwordx4 v132, s[0:1]
	s_waitcnt vmcnt(8)
	s_waitcnt lgkmcnt(0)
	.p2align 3
	s_setprio 1
	s_barrier
	v_mfma_f32_16x16x32_bf16 v[126:129], v[142:145], v[198:201], v[126:129]
	v_mfma_f32_16x16x32_bf16 v[126:129], v[146:149], v[202:205], v[126:129]
	v_mfma_f32_16x16x32_bf16 v[122:125], v[142:145], v[206:209], v[122:125]
	v_mfma_f32_16x16x32_bf16 v[122:125], v[146:149], v[210:213], v[122:125]
	v_mfma_f32_16x16x32_bf16 v[118:121], v[142:145], v[214:217], v[118:121]
	v_mfma_f32_16x16x32_bf16 v[118:121], v[146:149], v[218:221], v[118:121]
	v_mfma_f32_16x16x32_bf16 v[114:117], v[142:145], v[222:225], v[114:117]
	v_mfma_f32_16x16x32_bf16 v[114:117], v[146:149], v[226:229], v[114:117]
	v_mfma_f32_16x16x32_bf16 v[98:101], v[150:153], v[222:225], v[98:101]
	v_mfma_f32_16x16x32_bf16 v[98:101], v[154:157], v[226:229], v[98:101]
	v_mfma_f32_16x16x32_bf16 v[102:105], v[150:153], v[214:217], v[102:105]
	v_mfma_f32_16x16x32_bf16 v[102:105], v[154:157], v[218:221], v[102:105]
	v_mfma_f32_16x16x32_bf16 v[106:109], v[150:153], v[206:209], v[106:109]
	v_mfma_f32_16x16x32_bf16 v[106:109], v[154:157], v[210:213], v[106:109]
	v_mfma_f32_16x16x32_bf16 v[110:113], v[150:153], v[198:201], v[110:113]
	v_mfma_f32_16x16x32_bf16 v[110:113], v[154:157], v[202:205], v[110:113]
	v_mfma_f32_16x16x32_bf16 v[82:85], v[158:161], v[198:201], v[82:85]
	v_mfma_f32_16x16x32_bf16 v[82:85], v[162:165], v[202:205], v[82:85]
	v_mfma_f32_16x16x32_bf16 v[70:73], v[158:161], v[206:209], v[70:73]
	v_mfma_f32_16x16x32_bf16 v[70:73], v[162:165], v[210:213], v[70:73]
	v_mfma_f32_16x16x32_bf16 v[66:69], v[158:161], v[214:217], v[66:69]
	v_mfma_f32_16x16x32_bf16 v[66:69], v[162:165], v[218:221], v[66:69]
	v_mfma_f32_16x16x32_bf16 v[58:61], v[158:161], v[222:225], v[58:61]
	v_mfma_f32_16x16x32_bf16 v[58:61], v[162:165], v[226:229], v[58:61]
	v_mfma_f32_16x16x32_bf16 v[18:21], v[174:177], v[222:225], v[18:21]
	v_mfma_f32_16x16x32_bf16 v[18:21], v[188:191], v[226:229], v[18:21]
	v_mfma_f32_16x16x32_bf16 v[22:25], v[174:177], v[214:217], v[22:25]
	v_mfma_f32_16x16x32_bf16 v[22:25], v[188:191], v[218:221], v[22:25]
	v_mfma_f32_16x16x32_bf16 v[26:29], v[174:177], v[206:209], v[26:29]
	v_mfma_f32_16x16x32_bf16 v[26:29], v[188:191], v[210:213], v[26:29]
	v_mfma_f32_16x16x32_bf16 v[30:33], v[174:177], v[198:201], v[30:33]
	v_mfma_f32_16x16x32_bf16 v[30:33], v[188:191], v[202:205], v[30:33]
	s_barrier
; #define PG8_STAGE(bufoff, gbase, voff) do { _Pragma("unroll") for (int _i = 0; _i < 2; ++_i) \
;         __builtin_amdgcn_global_load_lds((const unsigned*)((const char*)(gbase) + (voff)[_i]), (PG8_LAS unsigned*)(lds + (bufoff) + ldsw + _i * 8192), 16, 0, 0); } while (0)
; #define PG8_LDA(dst, b, h) do { _Pragma("unroll") for (int m = 0; m < 4; ++m) _Pragma("unroll") for (int k = 0; k < 2; ++k) dst[m][k] = *(const PG8_LAS bf16x8*)(lds + PG8_SA(b, h) + aoff + m * 2048 + k * 1024); } while (0)
; #define PG8_WAIT_V(n) asm volatile("s_waitcnt vmcnt(" #n ")" ::: "memory")
; #define PG8_WAIT_L(n) asm volatile("s_waitcnt lgkmcnt(" #n ")" ::: "memory")
;     ...
;         for (int t = 0; t < nt * KREP; t += 2) {
;             const bool last = (t == nt * KREP - 2);
;             const int t1w = KREP > 1 ? ((t + 1) & (nt - 1)) : t + 1, t2w = KREP > 1 ? ((t + 2) & (nt - 1)) : t + 2;
;             const char* a1 = cA + (size_t)t1w * kstep;
;             const char* a2 = last ? nA : cA + (size_t)t2w * kstep; const char* b2 = last ? nB : cB + (size_t)t2w * kstep;
;             const char* a3 = a2 + kstep; const char* b3 = b2 + kstep;
;             if (last && has_next) S.a_ready(nxt);
;             const int relax = __builtin_amdgcn_readfirstlane((MK_RELAXW && t == 0 && ui > 0) ? 1 : 0);
;             if constexpr (SP2) {
;             PG8_LDB(B0, 0, 0); PG8_LDB(B1, 0, 1); PG8_SCHED; PG8_LDA(At, 0, 0); PG8_STAGE(PG8_SA(1, 1), a1 + hstep, voffA);
;             PG8_WAIT_V_SEL(relax);
;             PG8_WAIT_L(0); PG8_BAR; PG8_MMA(0, 0, At, B0); PG8_MMA(0, 1, At, B1); PG8_BAR; PG8_SCHED;
;             PG8_LDA(At, 0, 1); PG8_STAGE(PG8_SB(0, 0), b2, voffB); PG8_STAGE(PG8_SB(0, 1), b2 + hstep, voffB); PG8_STAGE(PG8_SA(0, 0), a2, voffA);
;             PG8_WAIT_V_SEL(relax);
;             PG8_WAIT_L(0); PG8_BAR; PG8_MMA(1, 0, At, B0); PG8_MMA(1, 1, At, B1); PG8_BAR; PG8_SCHED;
;             PG8_LDB(B0, 1, 0); PG8_LDB(B1, 1, 1); PG8_SCHED; PG8_LDA(At, 1, 0); PG8_STAGE(PG8_SA(0, 1), a2 + hstep, voffA);
;             PG8_WAIT_V(8); PG8_WAIT_L(0); PG8_BAR; PG8_MMA(0, 0, At, B0); PG8_MMA(0, 1, At, B1); PG8_BAR; PG8_SCHED;
;             PG8_LDA(At, 1, 1); PG8_STAGE(PG8_SB(1, 0), b3, voffB); PG8_STAGE(PG8_SB(1, 1), b3 + hstep, voffB); PG8_STAGE(PG8_SA(1, 0), a3, voffA);
;             PG8_WAIT_V(8); PG8_WAIT_L(0); PG8_BAR; PG8_MMA(1, 0, At, B0); PG8_MMA(1, 1, At, B1); PG8_BAR; PG8_SCHED;
	s_setprio 0
	s_add_i32 s0, s40, s87
	s_mov_b32 m0, s0
	ds_read_b128 v[198:201], v196 offset:49152
	ds_read_b128 v[202:205], v196 offset:50176
	ds_read_b128 v[206:209], v196 offset:51200
	ds_read_b128 v[210:213], v196 offset:52224
	ds_read_b128 v[214:217], v196 offset:53248
	ds_read_b128 v[218:221], v196 offset:54272
	ds_read_b128 v[222:225], v196 offset:55296
	ds_read_b128 v[226:229], v196 offset:56320
	s_add_u32 s100, s80, 0x80
	s_addc_u32 s101, s81, 0
	global_load_lds_dwordx4 v182, s[100:101]
	s_add_i32 m0, s0, 0x2000
	s_add_u32 s0, s80, 0x80080
	s_addc_u32 s1, s81, 0
	s_add_i32 s40, s41, s87
	global_load_lds_dwordx4 v134, s[100:101]
	s_mov_b32 m0, s40
	s_nop 0
	global_load_lds_dwordx4 v182, s[0:1]
	s_add_i32 m0, s40, 0x2000
	s_nop 0
	global_load_lds_dwordx4 v134, s[0:1]
	s_mov_b32 m0, s94
	s_nop 0
	s_add_u32 s100, s82, 0x80
	s_addc_u32 s101, s83, 0
	global_load_lds_dwordx4 v130, s[100:101]
	s_mov_b32 m0, s95
	s_nop 0
	global_load_lds_dwordx4 v132, s[100:101]
	s_waitcnt vmcnt(8)
	s_waitcnt lgkmcnt(0)
	.p2align 3
	s_setprio 1
	s_barrier
	v_mfma_f32_16x16x32_bf16 v[94:97], v[142:145], v[198:201], v[94:97]
	v_mfma_f32_16x16x32_bf16 v[94:97], v[146:149], v[202:205], v[94:97]
	v_mfma_f32_16x16x32_bf16 v[90:93], v[142:145], v[206:209], v[90:93]
	v_mfma_f32_16x16x32_bf16 v[90:93], v[146:149], v[210:213], v[90:93]
	v_mfma_f32_16x16x32_bf16 v[86:89], v[142:145], v[214:217], v[86:89]
	v_mfma_f32_16x16x32_bf16 v[86:89], v[146:149], v[218:221], v[86:89]
	v_mfma_f32_16x16x32_bf16 v[78:81], v[142:145], v[222:225], v[78:81]
	v_mfma_f32_16x16x32_bf16 v[78:81], v[146:149], v[226:229], v[78:81]
	v_mfma_f32_16x16x32_bf16 v[50:53], v[150:153], v[222:225], v[50:53]
	v_mfma_f32_16x16x32_bf16 v[50:53], v[154:157], v[226:229], v[50:53]
	v_mfma_f32_16x16x32_bf16 v[54:57], v[150:153], v[214:217], v[54:57]
	v_mfma_f32_16x16x32_bf16 v[54:57], v[154:157], v[218:221], v[54:57]
	v_mfma_f32_16x16x32_bf16 v[62:65], v[150:153], v[206:209], v[62:65]
	v_mfma_f32_16x16x32_bf16 v[62:65], v[154:157], v[210:213], v[62:65]
	v_mfma_f32_16x16x32_bf16 v[74:77], v[150:153], v[198:201], v[74:77]
	v_mfma_f32_16x16x32_bf16 v[74:77], v[154:157], v[202:205], v[74:77]
	v_mfma_f32_16x16x32_bf16 v[46:49], v[158:161], v[198:201], v[46:49]
	v_mfma_f32_16x16x32_bf16 v[46:49], v[162:165], v[202:205], v[46:49]
	v_mfma_f32_16x16x32_bf16 v[42:45], v[158:161], v[206:209], v[42:45]
	v_mfma_f32_16x16x32_bf16 v[42:45], v[162:165], v[210:213], v[42:45]
	v_mfma_f32_16x16x32_bf16 v[38:41], v[158:161], v[214:217], v[38:41]
	v_mfma_f32_16x16x32_bf16 v[38:41], v[162:165], v[218:221], v[38:41]
	v_mfma_f32_16x16x32_bf16 v[34:37], v[158:161], v[222:225], v[34:37]
	v_mfma_f32_16x16x32_bf16 v[34:37], v[162:165], v[226:229], v[34:37]
	v_mfma_f32_16x16x32_bf16 v[2:5], v[174:177], v[222:225], v[2:5]
	v_mfma_f32_16x16x32_bf16 v[2:5], v[188:191], v[226:229], v[2:5]
	v_mfma_f32_16x16x32_bf16 v[6:9], v[174:177], v[214:217], v[6:9]
	v_mfma_f32_16x16x32_bf16 v[6:9], v[188:191], v[218:221], v[6:9]
	v_mfma_f32_16x16x32_bf16 v[10:13], v[174:177], v[206:209], v[10:13]
	v_mfma_f32_16x16x32_bf16 v[10:13], v[188:191], v[210:213], v[10:13]
	v_mfma_f32_16x16x32_bf16 v[14:17], v[174:177], v[198:201], v[14:17]
	v_mfma_f32_16x16x32_bf16 v[14:17], v[188:191], v[202:205], v[14:17]
	s_barrier
	s_setprio 0
	s_add_i32 s37, s37, 2
	s_add_u32 s78, s78, 0x100
	s_addc_u32 s79, s79, 0
	s_add_u32 s33, s33, 0x100
	s_addc_u32 s35, s35, 0
	s_cmp_gt_u32 s37, 29
	s_cbranch_scc0 .LBB0_234
	s_branch .Lpeel_234_x
.LBB0_234:
	s_add_u32 s0, s78, 0xfff80080
	s_addc_u32 s1, s79, -1
	s_add_i32 s40, 0, 0x10000
	s_cmp_eq_u32 s37, 28
	s_cselect_b32 s83, s19, s1
	s_cselect_b32 s82, s20, s0
	s_cselect_b32 s81, s24, s35
	s_cselect_b32 s80, s31, s33
	s_add_i32 s41, 0, 0x14000
	ds_read_b128 v[142:145], v168
	ds_read_b128 v[146:149], v168 offset:1024
	ds_read_b128 v[150:153], v168 offset:2048
	ds_read_b128 v[154:157], v168 offset:3072
	ds_read_b128 v[158:161], v168 offset:16384
	ds_read_b128 v[162:165], v168 offset:17408
	ds_read_b128 v[174:177], v168 offset:18432
	ds_read_b128 v[188:191], v168 offset:19456
	s_add_i32 m0, s75, 0xc000
	ds_read_b128 v[198:201], v196
	ds_read_b128 v[202:205], v196 offset:1024
	ds_read_b128 v[206:209], v196 offset:2048
	ds_read_b128 v[210:213], v196 offset:3072
	ds_read_b128 v[214:217], v196 offset:4096
	ds_read_b128 v[218:221], v196 offset:5120
	ds_read_b128 v[222:225], v196 offset:6144
	ds_read_b128 v[226:229], v196 offset:7168
	global_load_lds_dwordx4 v138, s[78:79]
	s_add_i32 m0, s75, 0xe000
	s_nop 0
	global_load_lds_dwordx4 v140, s[78:79]
	s_waitcnt vmcnt(8)
	s_waitcnt lgkmcnt(0)
	.p2align 3
	s_setprio 1
	s_barrier
; #define PG8_STAGE(bufoff, gbase, voff) do { _Pragma("unroll") for (int _i = 0; _i < 2; ++_i) \
;         __builtin_amdgcn_global_load_lds((const unsigned*)((const char*)(gbase) + (voff)[_i]), (PG8_LAS unsigned*)(lds + (bufoff) + ldsw + _i * 8192), 16, 0, 0); } while (0)
; #define PG8_LDA(dst, b, h) do { _Pragma("unroll") for (int m = 0; m < 4; ++m) _Pragma("unroll") for (int k = 0; k < 2; ++k) dst[m][k] = *(const PG8_LAS bf16x8*)(lds + PG8_SA(b, h) + aoff + m * 2048 + k * 1024); } while (0)
; #define PG8_LDB(dst, b, h) do { _Pragma("unroll") for (int n = 0; n < 2; ++n) _Pragma("unroll") for (int k = 0; k < 2; ++k) dst[n][k] = *(const PG8_LAS bf16x8*)(lds + PG8_SB(b, h) + boff + n * 2048 + k * 1024); } while (0)
; #define PG8_WAIT_V(n) asm volatile("s_waitcnt vmcnt(" #n ")" ::: "memory")
; #define PG8_WAIT_L(n) asm volatile("s_waitcnt lgkmcnt(" #n ")" ::: "memory")
; #define PG8_WAIT_V_SEL(sel) asm volatile("s_cmp_eq_u32 %0, 0\n\ts_cbranch_scc1 .Lw8_%=\n\ts_waitcnt vmcnt(22)\n\ts_branch .Lwd_%=\n.Lw8_%=:\n\ts_waitcnt vmcnt(8)\n.Lwd_%=:" :: "s"(sel) : "memory", "scc")
; #define PG8_BAR __builtin_amdgcn_s_barrier()
; #define PG8_SCHED __builtin_amdgcn_sched_barrier(0)
;     ...
;             PG8_WAIT_L(0); PG8_BAR; PG8_MMA(0, 0, At, B0); PG8_MMA(0, 1, At, B1); PG8_BAR; PG8_SCHED;
;             PG8_LDA(At, 0, 1); PG8_STAGE(PG8_SB(0, 0), b2, voffB); PG8_STAGE(PG8_SB(0, 1), b2 + hstep, voffB); PG8_STAGE(PG8_SA(0, 0), a2, voffA);
;             PG8_WAIT_V_SEL(relax);
;             PG8_WAIT_L(0); PG8_BAR; PG8_MMA(1, 0, At, B0); PG8_MMA(1, 1, At, B1); PG8_BAR; PG8_SCHED;
;             PG8_LDB(B0, 1, 0); PG8_LDB(B1, 1, 1); PG8_SCHED; PG8_LDA(At, 1, 0); PG8_STAGE(PG8_SA(0, 1), a2 + hstep, voffA);
;             PG8_WAIT_V(8); PG8_WAIT_L(0); PG8_BAR; PG8_MMA(0, 0, At, B0); PG8_MMA(0, 1, At, B1); PG8_BAR; PG8_SCHED;
	v_mfma_f32_16x16x32_bf16 v[126:129], v[142:145], v[198:201], v[126:129]
	v_mfma_f32_16x16x32_bf16 v[126:129], v[146:149], v[202:205], v[126:129]
	v_mfma_f32_16x16x32_bf16 v[122:125], v[142:145], v[206:209], v[122:125]
	v_mfma_f32_16x16x32_bf16 v[122:125], v[146:149], v[210:213], v[122:125]
	v_mfma_f32_16x16x32_bf16 v[118:121], v[142:145], v[214:217], v[118:121]
	v_mfma_f32_16x16x32_bf16 v[118:121], v[146:149], v[218:221], v[118:121]
	v_mfma_f32_16x16x32_bf16 v[114:117], v[142:145], v[222:225], v[114:117]
	v_mfma_f32_16x16x32_bf16 v[114:117], v[146:149], v[226:229], v[114:117]
	v_mfma_f32_16x16x32_bf16 v[98:101], v[150:153], v[222:225], v[98:101]
	v_mfma_f32_16x16x32_bf16 v[98:101], v[154:157], v[226:229], v[98:101]
	v_mfma_f32_16x16x32_bf16 v[102:105], v[150:153], v[214:217], v[102:105]
	v_mfma_f32_16x16x32_bf16 v[102:105], v[154:157], v[218:221], v[102:105]
	v_mfma_f32_16x16x32_bf16 v[106:109], v[150:153], v[206:209], v[106:109]
	v_mfma_f32_16x16x32_bf16 v[106:109], v[154:157], v[210:213], v[106:109]
	v_mfma_f32_16x16x32_bf16 v[110:113], v[150:153], v[198:201], v[110:113]
	v_mfma_f32_16x16x32_bf16 v[110:113], v[154:157], v[202:205], v[110:113]
	v_mfma_f32_16x16x32_bf16 v[82:85], v[158:161], v[198:201], v[82:85]
	v_mfma_f32_16x16x32_bf16 v[82:85], v[162:165], v[202:205], v[82:85]
	v_mfma_f32_16x16x32_bf16 v[70:73], v[158:161], v[206:209], v[70:73]
	v_mfma_f32_16x16x32_bf16 v[70:73], v[162:165], v[210:213], v[70:73]
	v_mfma_f32_16x16x32_bf16 v[66:69], v[158:161], v[214:217], v[66:69]
	v_mfma_f32_16x16x32_bf16 v[66:69], v[162:165], v[218:221], v[66:69]
	v_mfma_f32_16x16x32_bf16 v[58:61], v[158:161], v[222:225], v[58:61]
	v_mfma_f32_16x16x32_bf16 v[58:61], v[162:165], v[226:229], v[58:61]
	v_mfma_f32_16x16x32_bf16 v[18:21], v[174:177], v[222:225], v[18:21]
	v_mfma_f32_16x16x32_bf16 v[18:21], v[188:191], v[226:229], v[18:21]
	v_mfma_f32_16x16x32_bf16 v[22:25], v[174:177], v[214:217], v[22:25]
	v_mfma_f32_16x16x32_bf16 v[22:25], v[188:191], v[218:221], v[22:25]
	v_mfma_f32_16x16x32_bf16 v[26:29], v[174:177], v[206:209], v[26:29]
	v_mfma_f32_16x16x32_bf16 v[26:29], v[188:191], v[210:213], v[26:29]
	v_mfma_f32_16x16x32_bf16 v[30:33], v[174:177], v[198:201], v[30:33]
	v_mfma_f32_16x16x32_bf16 v[30:33], v[188:191], v[202:205], v[30:33]
	s_barrier
	s_setprio 0
	s_add_i32 s0, s40, s87
	s_mov_b32 m0, s0
	ds_read_b128 v[198:201], v196 offset:16384
	ds_read_b128 v[202:205], v196 offset:17408
	ds_read_b128 v[206:209], v196 offset:18432
	ds_read_b128 v[210:213], v196 offset:19456
	ds_read_b128 v[214:217], v196 offset:20480
	ds_read_b128 v[218:221], v196 offset:21504
	ds_read_b128 v[222:225], v196 offset:22528
	ds_read_b128 v[226:229], v196 offset:23552
	global_load_lds_dwordx4 v182, s[80:81]
	s_add_i32 m0, s0, 0x2000
	s_add_u32 s0, s80, 0x80000
	s_addc_u32 s1, s81, 0
	s_add_i32 s40, s41, s87
	global_load_lds_dwordx4 v134, s[80:81]
	s_mov_b32 m0, s40
	s_nop 0
	global_load_lds_dwordx4 v182, s[0:1]
	s_add_i32 m0, s40, 0x2000
	s_nop 0
	global_load_lds_dwordx4 v134, s[0:1]
	s_mov_b32 m0, s75
	s_nop 0
	global_load_lds_dwordx4 v130, s[82:83]
	s_mov_b32 m0, s88
	s_nop 0
	global_load_lds_dwordx4 v132, s[82:83]
	s_waitcnt vmcnt(8)
	s_waitcnt lgkmcnt(0)
	.p2align 3
	s_setprio 1
	s_barrier
	v_mfma_f32_16x16x32_bf16 v[94:97], v[142:145], v[198:201], v[94:97]
	v_mfma_f32_16x16x32_bf16 v[94:97], v[146:149], v[202:205], v[94:97]
	v_mfma_f32_16x16x32_bf16 v[90:93], v[142:145], v[206:209], v[90:93]
	v_mfma_f32_16x16x32_bf16 v[90:93], v[146:149], v[210:213], v[90:93]
	v_mfma_f32_16x16x32_bf16 v[86:89], v[142:145], v[214:217], v[86:89]
	v_mfma_f32_16x16x32_bf16 v[86:89], v[146:149], v[218:221], v[86:89]
	v_mfma_f32_16x16x32_bf16 v[78:81], v[142:145], v[222:225], v[78:81]
	v_mfma_f32_16x16x32_bf16 v[78:81], v[146:149], v[226:229], v[78:81]
	v_mfma_f32_16x16x32_bf16 v[50:53], v[150:153], v[222:225], v[50:53]
	v_mfma_f32_16x16x32_bf16 v[50:53], v[154:157], v[226:229], v[50:53]
	v_mfma_f32_16x16x32_bf16 v[54:57], v[150:153], v[214:217], v[54:57]
	v_mfma_f32_16x16x32_bf16 v[54:57], v[154:157], v[218:221], v[54:57]
	v_mfma_f32_16x16x32_bf16 v[62:65], v[150:153], v[206:209], v[62:65]
	v_mfma_f32_16x16x32_bf16 v[62:65], v[154:157], v[210:213], v[62:65]
	v_mfma_f32_16x16x32_bf16 v[74:77], v[150:153], v[198:201], v[74:77]
	v_mfma_f32_16x16x32_bf16 v[74:77], v[154:157], v[202:205], v[74:77]
	v_mfma_f32_16x16x32_bf16 v[46:49], v[158:161], v[198:201], v[46:49]
	v_mfma_f32_16x16x32_bf16 v[46:49], v[162:165], v[202:205], v[46:49]
	v_mfma_f32_16x16x32_bf16 v[42:45], v[158:161], v[206:209], v[42:45]
	v_mfma_f32_16x16x32_bf16 v[42:45], v[162:165], v[210:213], v[42:45]
	v_mfma_f32_16x16x32_bf16 v[38:41], v[158:161], v[214:217], v[38:41]
	v_mfma_f32_16x16x32_bf16 v[38:41], v[162:165], v[218:221], v[38:41]
	v_mfma_f32_16x16x32_bf16 v[34:37], v[158:161], v[222:225], v[34:37]
	v_mfma_f32_16x16x32_bf16 v[34:37], v[162:165], v[226:229], v[34:37]
	v_mfma_f32_16x16x32_bf16 v[2:5], v[174:177], v[222:225], v[2:5]
	v_mfma_f32_16x16x32_bf16 v[2:5], v[188:191], v[226:229], v[2:5]
	v_mfma_f32_16x16x32_bf16 v[6:9], v[174:177], v[214:217], v[6:9]
	v_mfma_f32_16x16x32_bf16 v[6:9], v[188:191], v[218:221], v[6:9]
	v_mfma_f32_16x16x32_bf16 v[10:13], v[174:177], v[206:209], v[10:13]
	v_mfma_f32_16x16x32_bf16 v[10:13], v[188:191], v[210:213], v[10:13]
	v_mfma_f32_16x16x32_bf16 v[14:17], v[174:177], v[198:201], v[14:17]
	v_mfma_f32_16x16x32_bf16 v[14:17], v[188:191], v[202:205], v[14:17]
	s_barrier
; #define PG8_STAGE(bufoff, gbase, voff) do { _Pragma("unroll") for (int _i = 0; _i < 2; ++_i) \
;         __builtin_amdgcn_global_load_lds((const unsigned*)((const char*)(gbase) + (voff)[_i]), (PG8_LAS unsigned*)(lds + (bufoff) + ldsw + _i * 8192), 16, 0, 0); } while (0)
; #define PG8_LDA(dst, b, h) do { _Pragma("unroll") for (int m = 0; m < 4; ++m) _Pragma("unroll") for (int k = 0; k < 2; ++k) dst[m][k] = *(const PG8_LAS bf16x8*)(lds + PG8_SA(b, h) + aoff + m * 2048 + k * 1024); } while (0)
; #define PG8_LDB(dst, b, h) do { _Pragma("unroll") for (int n = 0; n < 2; ++n) _Pragma("unroll") for (int k = 0; k < 2; ++k) dst[n][k] = *(const PG8_LAS bf16x8*)(lds + PG8_SB(b, h) + boff + n * 2048 + k * 1024); } while (0)
; #define PG8_WAIT_V(n) asm volatile("s_waitcnt vmcnt(" #n ")" ::: "memory")
; #define PG8_WAIT_L(n) asm volatile("s_waitcnt lgkmcnt(" #n ")" ::: "memory")
; #define PG8_BAR __builtin_amdgcn_s_barrier()
; #define PG8_SCHED __builtin_amdgcn_sched_barrier(0)
;     ...
;             PG8_WAIT_L(0); PG8_BAR; PG8_MMA(1, 0, At, B0); PG8_MMA(1, 1, At, B1); PG8_BAR; PG8_SCHED;
;             PG8_LDB(B0, 1, 0); PG8_LDB(B1, 1, 1); PG8_SCHED; PG8_LDA(At, 1, 0); PG8_STAGE(PG8_SA(0, 1), a2 + hstep, voffA);
;             PG8_WAIT_V(8); PG8_WAIT_L(0); PG8_BAR; PG8_MMA(0, 0, At, B0); PG8_MMA(0, 1, At, B1); PG8_BAR; PG8_SCHED;
;             PG8_LDA(At, 1, 1); PG8_STAGE(PG8_SB(1, 0), b3, voffB); PG8_STAGE(PG8_SB(1, 1), b3 + hstep, voffB); PG8_STAGE(PG8_SA(1, 0), a3, voffA);
;             PG8_WAIT_V(8); PG8_WAIT_L(0); PG8_BAR; PG8_MMA(1, 0, At, B0); PG8_MMA(1, 1, At, B1); PG8_BAR; PG8_SCHED;
	s_setprio 0
	s_add_i32 s40, 0, 0x18000
	s_add_i32 s41, 0, 0x1c000
	ds_read_b128 v[142:145], v168 offset:32768
	ds_read_b128 v[146:149], v168 offset:33792
	ds_read_b128 v[150:153], v168 offset:34816
	ds_read_b128 v[154:157], v168 offset:35840
	ds_read_b128 v[158:161], v168 offset:49152
	ds_read_b128 v[162:165], v168 offset:50176
	ds_read_b128 v[174:177], v168 offset:51200
	ds_read_b128 v[188:191], v168 offset:52224
	s_add_u32 s0, s82, 0x80000
	s_addc_u32 s1, s83, 0
	s_mov_b32 m0, s89
	ds_read_b128 v[198:201], v196 offset:32768
	ds_read_b128 v[202:205], v196 offset:33792
	ds_read_b128 v[206:209], v196 offset:34816
	ds_read_b128 v[210:213], v196 offset:35840
	ds_read_b128 v[214:217], v196 offset:36864
	ds_read_b128 v[218:221], v196 offset:37888
	ds_read_b128 v[222:225], v196 offset:38912
	ds_read_b128 v[226:229], v196 offset:39936
	global_load_lds_dwordx4 v130, s[0:1]
	s_mov_b32 m0, s90
	s_nop 0
	global_load_lds_dwordx4 v132, s[0:1]
	s_waitcnt vmcnt(8)
	s_waitcnt lgkmcnt(0)
	.p2align 3
	s_setprio 1
	s_barrier
	v_mfma_f32_16x16x32_bf16 v[126:129], v[142:145], v[198:201], v[126:129]
	v_mfma_f32_16x16x32_bf16 v[126:129], v[146:149], v[202:205], v[126:129]
	v_mfma_f32_16x16x32_bf16 v[122:125], v[142:145], v[206:209], v[122:125]
	v_mfma_f32_16x16x32_bf16 v[122:125], v[146:149], v[210:213], v[122:125]
	v_mfma_f32_16x16x32_bf16 v[118:121], v[142:145], v[214:217], v[118:121]
	v_mfma_f32_16x16x32_bf16 v[118:121], v[146:149], v[218:221], v[118:121]
	v_mfma_f32_16x16x32_bf16 v[114:117], v[142:145], v[222:225], v[114:117]
	v_mfma_f32_16x16x32_bf16 v[114:117], v[146:149], v[226:229], v[114:117]
	v_mfma_f32_16x16x32_bf16 v[98:101], v[150:153], v[222:225], v[98:101]
	v_mfma_f32_16x16x32_bf16 v[98:101], v[154:157], v[226:229], v[98:101]
	v_mfma_f32_16x16x32_bf16 v[102:105], v[150:153], v[214:217], v[102:105]
	v_mfma_f32_16x16x32_bf16 v[102:105], v[154:157], v[218:221], v[102:105]
	v_mfma_f32_16x16x32_bf16 v[106:109], v[150:153], v[206:209], v[106:109]
	v_mfma_f32_16x16x32_bf16 v[106:109], v[154:157], v[210:213], v[106:109]
	v_mfma_f32_16x16x32_bf16 v[110:113], v[150:153], v[198:201], v[110:113]
	v_mfma_f32_16x16x32_bf16 v[110:113], v[154:157], v[202:205], v[110:113]
	v_mfma_f32_16x16x32_bf16 v[82:85], v[158:161], v[198:201], v[82:85]
	v_mfma_f32_16x16x32_bf16 v[82:85], v[162:165], v[202:205], v[82:85]
	v_mfma_f32_16x16x32_bf16 v[70:73], v[158:161], v[206:209], v[70:73]
	v_mfma_f32_16x16x32_bf16 v[70:73], v[162:165], v[210:213], v[70:73]
	v_mfma_f32_16x16x32_bf16 v[66:69], v[158:161], v[214:217], v[66:69]
	v_mfma_f32_16x16x32_bf16 v[66:69], v[162:165], v[218:221], v[66:69]
	v_mfma_f32_16x16x32_bf16 v[58:61], v[158:161], v[222:225], v[58:61]
	v_mfma_f32_16x16x32_bf16 v[58:61], v[162:165], v[226:229], v[58:61]
	v_mfma_f32_16x16x32_bf16 v[18:21], v[174:177], v[222:225], v[18:21]
	v_mfma_f32_16x16x32_bf16 v[18:21], v[188:191], v[226:229], v[18:21]
	v_mfma_f32_16x16x32_bf16 v[22:25], v[174:177], v[214:217], v[22:25]
	v_mfma_f32_16x16x32_bf16 v[22:25], v[188:191], v[218:221], v[22:25]
	v_mfma_f32_16x16x32_bf16 v[26:29], v[174:177], v[206:209], v[26:29]
	v_mfma_f32_16x16x32_bf16 v[26:29], v[188:191], v[210:213], v[26:29]
	v_mfma_f32_16x16x32_bf16 v[30:33], v[174:177], v[198:201], v[30:33]
	v_mfma_f32_16x16x32_bf16 v[30:33], v[188:191], v[202:205], v[30:33]
	s_barrier
	s_setprio 0
	s_add_i32 s0, s40, s87
	s_mov_b32 m0, s0
	ds_read_b128 v[198:201], v196 offset:49152
	ds_read_b128 v[202:205], v196 offset:50176
	ds_read_b128 v[206:209], v196 offset:51200
	ds_read_b128 v[210:213], v196 offset:52224
	ds_read_b128 v[214:217], v196 offset:53248
	ds_read_b128 v[218:221], v196 offset:54272
	ds_read_b128 v[222:225], v196 offset:55296
	ds_read_b128 v[226:229], v196 offset:56320
	s_add_u32 s100, s80, 0x80
	s_addc_u32 s101, s81, 0
	global_load_lds_dwordx4 v182, s[100:101]
	s_add_i32 m0, s0, 0x2000
	s_add_u32 s0, s80, 0x80080
	s_addc_u32 s1, s81, 0
	s_add_i32 s40, s41, s87
	global_load_lds_dwordx4 v134, s[100:101]
	s_mov_b32 m0, s40
	s_nop 0
	global_load_lds_dwordx4 v182, s[0:1]
	s_add_i32 m0, s40, 0x2000
	s_nop 0
	global_load_lds_dwordx4 v134, s[0:1]
	s_mov_b32 m0, s94
	s_nop 0
	s_add_u32 s100, s82, 0x80
	s_addc_u32 s101, s83, 0
	global_load_lds_dwordx4 v130, s[100:101]
	s_mov_b32 m0, s95
	s_nop 0
	global_load_lds_dwordx4 v132, s[100:101]
	s_waitcnt vmcnt(8)
	s_waitcnt lgkmcnt(0)
	.p2align 3
	s_setprio 1
	s_barrier
	v_mfma_f32_16x16x32_bf16 v[94:97], v[142:145], v[198:201], v[94:97]
	v_mfma_f32_16x16x32_bf16 v[94:97], v[146:149], v[202:205], v[94:97]
	v_mfma_f32_16x16x32_bf16 v[90:93], v[142:145], v[206:209], v[90:93]
	v_mfma_f32_16x16x32_bf16 v[90:93], v[146:149], v[210:213], v[90:93]
	v_mfma_f32_16x16x32_bf16 v[86:89], v[142:145], v[214:217], v[86:89]
	v_mfma_f32_16x16x32_bf16 v[86:89], v[146:149], v[218:221], v[86:89]
	v_mfma_f32_16x16x32_bf16 v[78:81], v[142:145], v[222:225], v[78:81]
	v_mfma_f32_16x16x32_bf16 v[78:81], v[146:149], v[226:229], v[78:81]
	v_mfma_f32_16x16x32_bf16 v[50:53], v[150:153], v[222:225], v[50:53]
	v_mfma_f32_16x16x32_bf16 v[50:53], v[154:157], v[226:229], v[50:53]
	v_mfma_f32_16x16x32_bf16 v[54:57], v[150:153], v[214:217], v[54:57]
	v_mfma_f32_16x16x32_bf16 v[54:57], v[154:157], v[218:221], v[54:57]
	v_mfma_f32_16x16x32_bf16 v[62:65], v[150:153], v[206:209], v[62:65]
	v_mfma_f32_16x16x32_bf16 v[62:65], v[154:157], v[210:213], v[62:65]
	v_mfma_f32_16x16x32_bf16 v[74:77], v[150:153], v[198:201], v[74:77]
	v_mfma_f32_16x16x32_bf16 v[74:77], v[154:157], v[202:205], v[74:77]
	v_mfma_f32_16x16x32_bf16 v[46:49], v[158:161], v[198:201], v[46:49]
	v_mfma_f32_16x16x32_bf16 v[46:49], v[162:165], v[202:205], v[46:49]
	v_mfma_f32_16x16x32_bf16 v[42:45], v[158:161], v[206:209], v[42:45]
	v_mfma_f32_16x16x32_bf16 v[42:45], v[162:165], v[210:213], v[42:45]
	v_mfma_f32_16x16x32_bf16 v[38:41], v[158:161], v[214:217], v[38:41]
	v_mfma_f32_16x16x32_bf16 v[38:41], v[162:165], v[218:221], v[38:41]
	v_mfma_f32_16x16x32_bf16 v[34:37], v[158:161], v[222:225], v[34:37]
	v_mfma_f32_16x16x32_bf16 v[34:37], v[162:165], v[226:229], v[34:37]
	v_mfma_f32_16x16x32_bf16 v[2:5], v[174:177], v[222:225], v[2:5]
	v_mfma_f32_16x16x32_bf16 v[2:5], v[188:191], v[226:229], v[2:5]
	v_mfma_f32_16x16x32_bf16 v[6:9], v[174:177], v[214:217], v[6:9]
	v_mfma_f32_16x16x32_bf16 v[6:9], v[188:191], v[218:221], v[6:9]
	v_mfma_f32_16x16x32_bf16 v[10:13], v[174:177], v[206:209], v[10:13]
	v_mfma_f32_16x16x32_bf16 v[10:13], v[188:191], v[210:213], v[10:13]
	v_mfma_f32_16x16x32_bf16 v[14:17], v[174:177], v[198:201], v[14:17]
	v_mfma_f32_16x16x32_bf16 v[14:17], v[188:191], v[202:205], v[14:17]
	s_barrier
	s_setprio 0
	s_add_i32 s37, s37, 2
	s_add_u32 s78, s78, 0x100
	s_addc_u32 s79, s79, 0
	s_add_u32 s33, s33, 0x100
	s_addc_u32 s35, s35, 0
	s_cmp_gt_u32 s37, 29
	s_cbranch_scc0 .LBB0_234
.Lpeel_234_x:
	s_branch .Lrlx_gi_x
.Lrlx_gi_0:
	s_waitcnt vmcnt(22)
	s_branch .Lrlx_gi_0_b

; #define PG8_STAGE(bufoff, gbase, voff) do { _Pragma("unroll") for (int _i = 0; _i < 2; ++_i) \
;         __builtin_amdgcn_global_load_lds((const unsigned*)((const char*)(gbase) + (voff)[_i]), (PG8_LAS unsigned*)(lds + (bufoff) + ldsw + _i * 8192), 16, 0, 0); } while (0)
; #define PG8_LDA(dst, b, h) do { _Pragma("unroll") for (int m = 0; m < 4; ++m) _Pragma("unroll") for (int k = 0; k < 2; ++k) dst[m][k] = *(const PG8_LAS bf16x8*)(lds + PG8_SA(b, h) + aoff + m * 2048 + k * 1024); } while (0)
; #define PG8_LDB(dst, b, h) do { _Pragma("unroll") for (int n = 0; n < 2; ++n) _Pragma("unroll") for (int k = 0; k < 2; ++k) dst[n][k] = *(const PG8_LAS bf16x8*)(lds + PG8_SB(b, h) + boff + n * 2048 + k * 1024); } while (0)
; #define PG8_WAIT_L(n) asm volatile("s_waitcnt lgkmcnt(" #n ")" ::: "memory")
; #define PG8_WAIT_V_SEL(sel) asm volatile("s_cmp_eq_u32 %0, 0\n\ts_cbranch_scc1 .Lw8_%=\n\ts_waitcnt vmcnt(22)\n\ts_branch .Lwd_%=\n.Lw8_%=:\n\ts_waitcnt vmcnt(8)\n.Lwd_%=:" :: "s"(sel) : "memory", "scc")
;     ...
;         const char* nA = has_next ? (const char*)g.A + (size_t)nxt.pm * tstep : cA; const char* nB = has_next ? (const char*)g.Bt + (size_t)nxt.pn * tstep : cB;
;         for (int t = 0; t < nt * KREP; t += 2) {
;             const bool last = (t == nt * KREP - 2);
;             const int t1w = KREP > 1 ? ((t + 1) & (nt - 1)) : t + 1, t2w = KREP > 1 ? ((t + 2) & (nt - 1)) : t + 2;
;             const char* a1 = cA + (size_t)t1w * kstep;
;             const char* a2 = last ? nA : cA + (size_t)t2w * kstep; const char* b2 = last ? nB : cB + (size_t)t2w * kstep;
;             const char* a3 = a2 + kstep; const char* b3 = b2 + kstep;
;             if (last && has_next) S.a_ready(nxt);
;             const int relax = __builtin_amdgcn_readfirstlane((MK_RELAXW && t == 0 && ui > 0) ? 1 : 0);
;             if constexpr (SP2) {
;             PG8_LDB(B0, 0, 0); PG8_LDB(B1, 0, 1); PG8_SCHED; PG8_LDA(At, 0, 0); PG8_STAGE(PG8_SA(1, 1), a1 + hstep, voffA);
;             PG8_WAIT_V_SEL(relax);
;             PG8_WAIT_L(0); PG8_BAR; PG8_MMA(0, 0, At, B0); PG8_MMA(0, 1, At, B1); PG8_BAR; PG8_SCHED;
;             PG8_LDA(At, 0, 1); PG8_STAGE(PG8_SB(0, 0), b2, voffB); PG8_STAGE(PG8_SB(0, 1), b2 + hstep, voffB); PG8_STAGE(PG8_SA(0, 0), a2, voffA);
;             PG8_WAIT_V_SEL(relax);
;             PG8_WAIT_L(0); PG8_BAR; PG8_MMA(1, 0, At, B0); PG8_MMA(1, 1, At, B1); PG8_BAR; PG8_SCHED;
.LBB0_540:
	s_ashr_i32 s73, s72, 31
	s_lshl_b64 s[0:1], s[72:73], 20
	s_add_u32 s74, s31, s0
	s_addc_u32 s75, s33, s1
	s_and_b64 s[0:1], s[6:7], exec
	s_cselect_b32 s40, s75, s83
	s_cselect_b32 s41, s74, s82
	s_ashr_i32 s71, s70, 31
	s_lshl_b64 s[0:1], s[70:71], 20
	s_add_u32 s76, s35, s0
	s_addc_u32 s77, s37, s1
	s_and_b64 s[0:1], s[6:7], exec
	s_cselect_b32 s57, s77, s85
	s_cselect_b32 s58, s76, s84
	s_add_u32 s82, s82, 0x80080
	s_addc_u32 s83, s83, 0
	s_add_u32 s59, s84, 0x100
	s_addc_u32 s71, s85, 0
	s_mov_b32 s73, -2
	s_waitcnt lgkmcnt(0)
	v_add_u32_e32 v210, 0x10000, v227
	s_add_u32 s0, s82, 0xfff80080
	s_addc_u32 s1, s83, -1
	s_add_i32 s79, 0, 0x10000
	s_cmp_eq_u32 s73, 28
	s_cselect_b32 s87, s40, s1
	s_cselect_b32 s86, s41, s0
	s_cselect_b32 s85, s57, s71
	s_cselect_b32 s84, s58, s59
	s_add_i32 s81, 0, 0x14000
	ds_read_b128 v[90:93], v210
	ds_read_b128 v[94:97], v210 offset:1024
	ds_read_b128 v[98:101], v210 offset:2048
	ds_read_b128 v[102:105], v210 offset:3072
	ds_read_b128 v[146:149], v210 offset:16384
	ds_read_b128 v[150:153], v210 offset:17408
	ds_read_b128 v[154:157], v210 offset:18432
	ds_read_b128 v[158:161], v210 offset:19456
	s_add_i32 m0, s44, 0xc000
	ds_read_b128 v[162:165], v230
	ds_read_b128 v[166:169], v230 offset:1024
	ds_read_b128 v[184:187], v230 offset:2048
	ds_read_b128 v[190:193], v230 offset:3072
	ds_read_b128 v[194:197], v230 offset:4096
	ds_read_b128 v[198:201], v230 offset:5120
	ds_read_b128 v[202:205], v230 offset:6144
	ds_read_b128 v[206:209], v230 offset:7168
	global_load_lds_dwordx4 v180, s[82:83]
	s_add_i32 m0, s44, 0xe000
	s_nop 0
	global_load_lds_dwordx4 v188, s[82:83]
	s_cmp_lg_u32 s56, 0
	s_cbranch_scc1 .Lrlx_go_0
	s_waitcnt vmcnt(8)
.Lrlx_go_0_b:
	s_waitcnt lgkmcnt(0)
	.p2align 3
	s_setprio 1
	s_barrier
	v_mfma_f32_16x16x32_bf16 v[142:145], v[90:93], v[162:165], 0
	v_mfma_f32_16x16x32_bf16 v[142:145], v[94:97], v[166:169], v[142:145]
	v_mfma_f32_16x16x32_bf16 v[126:129], v[90:93], v[184:187], 0
	v_mfma_f32_16x16x32_bf16 v[126:129], v[94:97], v[190:193], v[126:129]
	v_mfma_f32_16x16x32_bf16 v[110:113], v[90:93], v[194:197], 0
	v_mfma_f32_16x16x32_bf16 v[110:113], v[94:97], v[198:201], v[110:113]
	v_mfma_f32_16x16x32_bf16 v[78:81], v[90:93], v[202:205], 0
	v_mfma_f32_16x16x32_bf16 v[78:81], v[94:97], v[206:209], v[78:81]
	v_mfma_f32_16x16x32_bf16 v[74:77], v[98:101], v[202:205], 0
	v_mfma_f32_16x16x32_bf16 v[74:77], v[102:105], v[206:209], v[74:77]
	v_mfma_f32_16x16x32_bf16 v[106:109], v[98:101], v[194:197], 0
	v_mfma_f32_16x16x32_bf16 v[106:109], v[102:105], v[198:201], v[106:109]
	v_mfma_f32_16x16x32_bf16 v[122:125], v[98:101], v[184:187], 0
	v_mfma_f32_16x16x32_bf16 v[122:125], v[102:105], v[190:193], v[122:125]
	v_mfma_f32_16x16x32_bf16 v[138:141], v[98:101], v[162:165], 0
	v_mfma_f32_16x16x32_bf16 v[138:141], v[102:105], v[166:169], v[138:141]
	v_mfma_f32_16x16x32_bf16 v[134:137], v[146:149], v[162:165], 0
	v_mfma_f32_16x16x32_bf16 v[134:137], v[150:153], v[166:169], v[134:137]
	v_mfma_f32_16x16x32_bf16 v[118:121], v[146:149], v[184:187], 0
	v_mfma_f32_16x16x32_bf16 v[118:121], v[150:153], v[190:193], v[118:121]
	v_mfma_f32_16x16x32_bf16 v[86:89], v[146:149], v[194:197], 0
	v_mfma_f32_16x16x32_bf16 v[86:89], v[150:153], v[198:201], v[86:89]
	v_mfma_f32_16x16x32_bf16 v[70:73], v[146:149], v[202:205], 0
	v_mfma_f32_16x16x32_bf16 v[70:73], v[150:153], v[206:209], v[70:73]
	v_mfma_f32_16x16x32_bf16 v[66:69], v[154:157], v[202:205], 0
	v_mfma_f32_16x16x32_bf16 v[66:69], v[158:161], v[206:209], v[66:69]
	v_mfma_f32_16x16x32_bf16 v[82:85], v[154:157], v[194:197], 0
	v_mfma_f32_16x16x32_bf16 v[82:85], v[158:161], v[198:201], v[82:85]
	v_mfma_f32_16x16x32_bf16 v[114:117], v[154:157], v[184:187], 0
	v_mfma_f32_16x16x32_bf16 v[114:117], v[158:161], v[190:193], v[114:117]
	v_mfma_f32_16x16x32_bf16 v[130:133], v[154:157], v[162:165], 0
	v_mfma_f32_16x16x32_bf16 v[130:133], v[158:161], v[166:169], v[130:133]
	s_barrier
	s_setprio 0
	s_add_i32 s0, s79, s30
	s_mov_b32 m0, s0
	ds_read_b128 v[162:165], v230 offset:16384
	ds_read_b128 v[166:169], v230 offset:17408
	ds_read_b128 v[184:187], v230 offset:18432
	ds_read_b128 v[190:193], v230 offset:19456
	ds_read_b128 v[194:197], v230 offset:20480
	ds_read_b128 v[198:201], v230 offset:21504
	ds_read_b128 v[202:205], v230 offset:22528
	ds_read_b128 v[206:209], v230 offset:23552
	global_load_lds_dwordx4 v182, s[84:85]
	s_add_i32 m0, s0, 0x2000
	s_add_u32 s0, s84, 0x80000
	s_addc_u32 s1, s85, 0
	s_add_i32 s79, s81, s30
	global_load_lds_dwordx4 v178, s[84:85]
	s_mov_b32 m0, s79
	s_nop 0
	global_load_lds_dwordx4 v182, s[0:1]
	s_add_i32 m0, s79, 0x2000
	s_nop 0
	global_load_lds_dwordx4 v178, s[0:1]
	s_mov_b32 m0, s44
	s_nop 0
	global_load_lds_dwordx4 v174, s[86:87]
	s_mov_b32 m0, s45
	s_nop 0
	global_load_lds_dwordx4 v176, s[86:87]
	s_cmp_lg_u32 s56, 0
	s_cbranch_scc1 .Lrlx_go_1
	s_waitcnt vmcnt(8)
; #define PG8_STAGE(bufoff, gbase, voff) do { _Pragma("unroll") for (int _i = 0; _i < 2; ++_i) \
;         __builtin_amdgcn_global_load_lds((const unsigned*)((const char*)(gbase) + (voff)[_i]), (PG8_LAS unsigned*)(lds + (bufoff) + ldsw + _i * 8192), 16, 0, 0); } while (0)
; #define PG8_LDA(dst, b, h) do { _Pragma("unroll") for (int m = 0; m < 4; ++m) _Pragma("unroll") for (int k = 0; k < 2; ++k) dst[m][k] = *(const PG8_LAS bf16x8*)(lds + PG8_SA(b, h) + aoff + m * 2048 + k * 1024); } while (0)
; #define PG8_LDB(dst, b, h) do { _Pragma("unroll") for (int n = 0; n < 2; ++n) _Pragma("unroll") for (int k = 0; k < 2; ++k) dst[n][k] = *(const PG8_LAS bf16x8*)(lds + PG8_SB(b, h) + boff + n * 2048 + k * 1024); } while (0)
; #define PG8_WAIT_V(n) asm volatile("s_waitcnt vmcnt(" #n ")" ::: "memory")
; #define PG8_WAIT_L(n) asm volatile("s_waitcnt lgkmcnt(" #n ")" ::: "memory")
; #define PG8_WAIT_V_SEL(sel) asm volatile("s_cmp_eq_u32 %0, 0\n\ts_cbranch_scc1 .Lw8_%=\n\ts_waitcnt vmcnt(22)\n\ts_branch .Lwd_%=\n.Lw8_%=:\n\ts_waitcnt vmcnt(8)\n.Lwd_%=:" :: "s"(sel) : "memory", "scc")
; #define PG8_BAR __builtin_amdgcn_s_barrier()
; #define PG8_SCHED __builtin_amdgcn_sched_barrier(0)
;     ...
;             PG8_WAIT_L(0); PG8_BAR; PG8_MMA(0, 0, At, B0); PG8_MMA(0, 1, At, B1); PG8_BAR; PG8_SCHED;
;             PG8_LDA(At, 0, 1); PG8_STAGE(PG8_SB(0, 0), b2, voffB); PG8_STAGE(PG8_SB(0, 1), b2 + hstep, voffB); PG8_STAGE(PG8_SA(0, 0), a2, voffA);
;             PG8_WAIT_V_SEL(relax);
;             PG8_WAIT_L(0); PG8_BAR; PG8_MMA(1, 0, At, B0); PG8_MMA(1, 1, At, B1); PG8_BAR; PG8_SCHED;
;             PG8_LDB(B0, 1, 0); PG8_LDB(B1, 1, 1); PG8_SCHED; PG8_LDA(At, 1, 0); PG8_STAGE(PG8_SA(0, 1), a2 + hstep, voffA);
;             PG8_WAIT_V(8); PG8_WAIT_L(0); PG8_BAR; PG8_MMA(0, 0, At, B0); PG8_MMA(0, 1, At, B1); PG8_BAR; PG8_SCHED;
.Lrlx_go_1_b:
	s_waitcnt lgkmcnt(0)
	.p2align 3
	s_setprio 1
	s_barrier
	v_mfma_f32_16x16x32_bf16 v[62:65], v[90:93], v[162:165], 0
	v_mfma_f32_16x16x32_bf16 v[62:65], v[94:97], v[166:169], v[62:65]
	v_mfma_f32_16x16x32_bf16 v[46:49], v[90:93], v[184:187], 0
	v_mfma_f32_16x16x32_bf16 v[46:49], v[94:97], v[190:193], v[46:49]
	v_mfma_f32_16x16x32_bf16 v[30:33], v[90:93], v[194:197], 0
	v_mfma_f32_16x16x32_bf16 v[30:33], v[94:97], v[198:201], v[30:33]
	v_mfma_f32_16x16x32_bf16 v[14:17], v[90:93], v[202:205], 0
	v_mfma_f32_16x16x32_bf16 v[14:17], v[94:97], v[206:209], v[14:17]
	v_mfma_f32_16x16x32_bf16 v[10:13], v[98:101], v[202:205], 0
	v_mfma_f32_16x16x32_bf16 v[10:13], v[102:105], v[206:209], v[10:13]
	v_mfma_f32_16x16x32_bf16 v[26:29], v[98:101], v[194:197], 0
	v_mfma_f32_16x16x32_bf16 v[26:29], v[102:105], v[198:201], v[26:29]
	v_mfma_f32_16x16x32_bf16 v[42:45], v[98:101], v[184:187], 0
	v_mfma_f32_16x16x32_bf16 v[42:45], v[102:105], v[190:193], v[42:45]
	v_mfma_f32_16x16x32_bf16 v[58:61], v[98:101], v[162:165], 0
	v_mfma_f32_16x16x32_bf16 v[58:61], v[102:105], v[166:169], v[58:61]
	v_mfma_f32_16x16x32_bf16 v[54:57], v[146:149], v[162:165], 0
	v_mfma_f32_16x16x32_bf16 v[54:57], v[150:153], v[166:169], v[54:57]
	v_mfma_f32_16x16x32_bf16 v[38:41], v[146:149], v[184:187], 0
	v_mfma_f32_16x16x32_bf16 v[38:41], v[150:153], v[190:193], v[38:41]
	v_mfma_f32_16x16x32_bf16 v[22:25], v[146:149], v[194:197], 0
	v_mfma_f32_16x16x32_bf16 v[22:25], v[150:153], v[198:201], v[22:25]
	v_mfma_f32_16x16x32_bf16 v[6:9], v[146:149], v[202:205], 0
	v_mfma_f32_16x16x32_bf16 v[6:9], v[150:153], v[206:209], v[6:9]
	v_mfma_f32_16x16x32_bf16 v[2:5], v[154:157], v[202:205], 0
	v_mfma_f32_16x16x32_bf16 v[2:5], v[158:161], v[206:209], v[2:5]
	v_mfma_f32_16x16x32_bf16 v[18:21], v[154:157], v[194:197], 0
	v_mfma_f32_16x16x32_bf16 v[18:21], v[158:161], v[198:201], v[18:21]
	v_mfma_f32_16x16x32_bf16 v[34:37], v[154:157], v[184:187], 0
	v_mfma_f32_16x16x32_bf16 v[34:37], v[158:161], v[190:193], v[34:37]
	v_mfma_f32_16x16x32_bf16 v[50:53], v[154:157], v[162:165], 0
	v_mfma_f32_16x16x32_bf16 v[50:53], v[158:161], v[166:169], v[50:53]
	s_barrier
	s_setprio 0
	s_add_i32 s79, 0, 0x18000
	s_add_i32 s81, 0, 0x1c000
	ds_read_b128 v[90:93], v210 offset:32768
	ds_read_b128 v[94:97], v210 offset:33792
	ds_read_b128 v[98:101], v210 offset:34816
	ds_read_b128 v[102:105], v210 offset:35840
	ds_read_b128 v[146:149], v210 offset:49152
	ds_read_b128 v[150:153], v210 offset:50176
	ds_read_b128 v[154:157], v210 offset:51200
	ds_read_b128 v[158:161], v210 offset:52224
	s_add_u32 s0, s86, 0x80000
	s_addc_u32 s1, s87, 0
	s_mov_b32 m0, s46
	ds_read_b128 v[162:165], v230 offset:32768
	ds_read_b128 v[166:169], v230 offset:33792
	ds_read_b128 v[184:187], v230 offset:34816
	ds_read_b128 v[190:193], v230 offset:35840
	ds_read_b128 v[194:197], v230 offset:36864
	ds_read_b128 v[198:201], v230 offset:37888
	ds_read_b128 v[202:205], v230 offset:38912
	ds_read_b128 v[206:209], v230 offset:39936
	global_load_lds_dwordx4 v174, s[0:1]
	s_mov_b32 m0, s47
	s_nop 0
	global_load_lds_dwordx4 v176, s[0:1]
	s_waitcnt vmcnt(8)
	s_waitcnt lgkmcnt(0)
	.p2align 3
	s_setprio 1
	s_barrier
	v_mfma_f32_16x16x32_bf16 v[142:145], v[90:93], v[162:165], v[142:145]
	v_mfma_f32_16x16x32_bf16 v[142:145], v[94:97], v[166:169], v[142:145]
	v_mfma_f32_16x16x32_bf16 v[126:129], v[90:93], v[184:187], v[126:129]
	v_mfma_f32_16x16x32_bf16 v[126:129], v[94:97], v[190:193], v[126:129]
	v_mfma_f32_16x16x32_bf16 v[110:113], v[90:93], v[194:197], v[110:113]
	v_mfma_f32_16x16x32_bf16 v[110:113], v[94:97], v[198:201], v[110:113]
	v_mfma_f32_16x16x32_bf16 v[78:81], v[90:93], v[202:205], v[78:81]
	v_mfma_f32_16x16x32_bf16 v[78:81], v[94:97], v[206:209], v[78:81]
	v_mfma_f32_16x16x32_bf16 v[74:77], v[98:101], v[202:205], v[74:77]
	v_mfma_f32_16x16x32_bf16 v[74:77], v[102:105], v[206:209], v[74:77]
	v_mfma_f32_16x16x32_bf16 v[106:109], v[98:101], v[194:197], v[106:109]
	v_mfma_f32_16x16x32_bf16 v[106:109], v[102:105], v[198:201], v[106:109]
	v_mfma_f32_16x16x32_bf16 v[122:125], v[98:101], v[184:187], v[122:125]
	v_mfma_f32_16x16x32_bf16 v[122:125], v[102:105], v[190:193], v[122:125]
	v_mfma_f32_16x16x32_bf16 v[138:141], v[98:101], v[162:165], v[138:141]
	v_mfma_f32_16x16x32_bf16 v[138:141], v[102:105], v[166:169], v[138:141]
	v_mfma_f32_16x16x32_bf16 v[134:137], v[146:149], v[162:165], v[134:137]
	v_mfma_f32_16x16x32_bf16 v[134:137], v[150:153], v[166:169], v[134:137]
	v_mfma_f32_16x16x32_bf16 v[118:121], v[146:149], v[184:187], v[118:121]
	v_mfma_f32_16x16x32_bf16 v[118:121], v[150:153], v[190:193], v[118:121]
	v_mfma_f32_16x16x32_bf16 v[86:89], v[146:149], v[194:197], v[86:89]
	v_mfma_f32_16x16x32_bf16 v[86:89], v[150:153], v[198:201], v[86:89]
	v_mfma_f32_16x16x32_bf16 v[70:73], v[146:149], v[202:205], v[70:73]
	v_mfma_f32_16x16x32_bf16 v[70:73], v[150:153], v[206:209], v[70:73]
	v_mfma_f32_16x16x32_bf16 v[66:69], v[154:157], v[202:205], v[66:69]
	v_mfma_f32_16x16x32_bf16 v[66:69], v[158:161], v[206:209], v[66:69]
	v_mfma_f32_16x16x32_bf16 v[82:85], v[154:157], v[194:197], v[82:85]
	v_mfma_f32_16x16x32_bf16 v[82:85], v[158:161], v[198:201], v[82:85]
	v_mfma_f32_16x16x32_bf16 v[114:117], v[154:157], v[184:187], v[114:117]
	v_mfma_f32_16x16x32_bf16 v[114:117], v[158:161], v[190:193], v[114:117]
	v_mfma_f32_16x16x32_bf16 v[130:133], v[154:157], v[162:165], v[130:133]
	v_mfma_f32_16x16x32_bf16 v[130:133], v[158:161], v[166:169], v[130:133]
	s_barrier
; #define PG8_STAGE(bufoff, gbase, voff) do { _Pragma("unroll") for (int _i = 0; _i < 2; ++_i) \
;         __builtin_amdgcn_global_load_lds((const unsigned*)((const char*)(gbase) + (voff)[_i]), (PG8_LAS unsigned*)(lds + (bufoff) + ldsw + _i * 8192), 16, 0, 0); } while (0)
; #define PG8_LDA(dst, b, h) do { _Pragma("unroll") for (int m = 0; m < 4; ++m) _Pragma("unroll") for (int k = 0; k < 2; ++k) dst[m][k] = *(const PG8_LAS bf16x8*)(lds + PG8_SA(b, h) + aoff + m * 2048 + k * 1024); } while (0)
; #define PG8_WAIT_V(n) asm volatile("s_waitcnt vmcnt(" #n ")" ::: "memory")
; #define PG8_WAIT_L(n) asm volatile("s_waitcnt lgkmcnt(" #n ")" ::: "memory")
;     ...
;         for (int t = 0; t < nt * KREP; t += 2) {
;             const bool last = (t == nt * KREP - 2);
;             const int t1w = KREP > 1 ? ((t + 1) & (nt - 1)) : t + 1, t2w = KREP > 1 ? ((t + 2) & (nt - 1)) : t + 2;
;             const char* a1 = cA + (size_t)t1w * kstep;
;             const char* a2 = last ? nA : cA + (size_t)t2w * kstep; const char* b2 = last ? nB : cB + (size_t)t2w * kstep;
;             const char* a3 = a2 + kstep; const char* b3 = b2 + kstep;
;             if (last && has_next) S.a_ready(nxt);
;             const int relax = __builtin_amdgcn_readfirstlane((MK_RELAXW && t == 0 && ui > 0) ? 1 : 0);
;             if constexpr (SP2) {
;             PG8_LDB(B0, 0, 0); PG8_LDB(B1, 0, 1); PG8_SCHED; PG8_LDA(At, 0, 0); PG8_STAGE(PG8_SA(1, 1), a1 + hstep, voffA);
;             PG8_WAIT_V_SEL(relax);
;             PG8_WAIT_L(0); PG8_BAR; PG8_MMA(0, 0, At, B0); PG8_MMA(0, 1, At, B1); PG8_BAR; PG8_SCHED;
;             PG8_LDA(At, 0, 1); PG8_STAGE(PG8_SB(0, 0), b2, voffB); PG8_STAGE(PG8_SB(0, 1), b2 + hstep, voffB); PG8_STAGE(PG8_SA(0, 0), a2, voffA);
;             PG8_WAIT_V_SEL(relax);
;             PG8_WAIT_L(0); PG8_BAR; PG8_MMA(1, 0, At, B0); PG8_MMA(1, 1, At, B1); PG8_BAR; PG8_SCHED;
;             PG8_LDB(B0, 1, 0); PG8_LDB(B1, 1, 1); PG8_SCHED; PG8_LDA(At, 1, 0); PG8_STAGE(PG8_SA(0, 1), a2 + hstep, voffA);
;             PG8_WAIT_V(8); PG8_WAIT_L(0); PG8_BAR; PG8_MMA(0, 0, At, B0); PG8_MMA(0, 1, At, B1); PG8_BAR; PG8_SCHED;
;             PG8_LDA(At, 1, 1); PG8_STAGE(PG8_SB(1, 0), b3, voffB); PG8_STAGE(PG8_SB(1, 1), b3 + hstep, voffB); PG8_STAGE(PG8_SA(1, 0), a3, voffA);
;             PG8_WAIT_V(8); PG8_WAIT_L(0); PG8_BAR; PG8_MMA(1, 0, At, B0); PG8_MMA(1, 1, At, B1); PG8_BAR; PG8_SCHED;
	s_setprio 0
	s_add_i32 s0, s79, s30
	s_mov_b32 m0, s0
	ds_read_b128 v[162:165], v230 offset:49152
	ds_read_b128 v[166:169], v230 offset:50176
	ds_read_b128 v[184:187], v230 offset:51200
	ds_read_b128 v[190:193], v230 offset:52224
	ds_read_b128 v[194:197], v230 offset:53248
	ds_read_b128 v[198:201], v230 offset:54272
	ds_read_b128 v[202:205], v230 offset:55296
	ds_read_b128 v[206:209], v230 offset:56320
	s_add_u32 s100, s84, 0x80
	s_addc_u32 s101, s85, 0
	global_load_lds_dwordx4 v182, s[100:101]
	s_add_i32 m0, s0, 0x2000
	s_add_u32 s0, s84, 0x80080
	s_addc_u32 s1, s85, 0
	s_add_i32 s79, s81, s30
	global_load_lds_dwordx4 v178, s[100:101]
	s_mov_b32 m0, s79
	s_nop 0
	global_load_lds_dwordx4 v182, s[0:1]
	s_add_i32 m0, s79, 0x2000
	s_nop 0
	global_load_lds_dwordx4 v178, s[0:1]
	s_mov_b32 m0, s49
	s_nop 0
	s_add_u32 s100, s86, 0x80
	s_addc_u32 s101, s87, 0
	global_load_lds_dwordx4 v174, s[100:101]
	s_mov_b32 m0, s50
	s_nop 0
	global_load_lds_dwordx4 v176, s[100:101]
	s_waitcnt vmcnt(8)
	s_waitcnt lgkmcnt(0)
	.p2align 3
	s_setprio 1
	s_barrier
	v_mfma_f32_16x16x32_bf16 v[62:65], v[90:93], v[162:165], v[62:65]
	v_mfma_f32_16x16x32_bf16 v[62:65], v[94:97], v[166:169], v[62:65]
	v_mfma_f32_16x16x32_bf16 v[46:49], v[90:93], v[184:187], v[46:49]
	v_mfma_f32_16x16x32_bf16 v[46:49], v[94:97], v[190:193], v[46:49]
	v_mfma_f32_16x16x32_bf16 v[30:33], v[90:93], v[194:197], v[30:33]
	v_mfma_f32_16x16x32_bf16 v[30:33], v[94:97], v[198:201], v[30:33]
	v_mfma_f32_16x16x32_bf16 v[14:17], v[90:93], v[202:205], v[14:17]
	v_mfma_f32_16x16x32_bf16 v[14:17], v[94:97], v[206:209], v[14:17]
	v_mfma_f32_16x16x32_bf16 v[10:13], v[98:101], v[202:205], v[10:13]
	v_mfma_f32_16x16x32_bf16 v[10:13], v[102:105], v[206:209], v[10:13]
	v_mfma_f32_16x16x32_bf16 v[26:29], v[98:101], v[194:197], v[26:29]
	v_mfma_f32_16x16x32_bf16 v[26:29], v[102:105], v[198:201], v[26:29]
	v_mfma_f32_16x16x32_bf16 v[42:45], v[98:101], v[184:187], v[42:45]
	v_mfma_f32_16x16x32_bf16 v[42:45], v[102:105], v[190:193], v[42:45]
	v_mfma_f32_16x16x32_bf16 v[58:61], v[98:101], v[162:165], v[58:61]
	v_mfma_f32_16x16x32_bf16 v[58:61], v[102:105], v[166:169], v[58:61]
	v_mfma_f32_16x16x32_bf16 v[54:57], v[146:149], v[162:165], v[54:57]
	v_mfma_f32_16x16x32_bf16 v[54:57], v[150:153], v[166:169], v[54:57]
	v_mfma_f32_16x16x32_bf16 v[38:41], v[146:149], v[184:187], v[38:41]
	v_mfma_f32_16x16x32_bf16 v[38:41], v[150:153], v[190:193], v[38:41]
	v_mfma_f32_16x16x32_bf16 v[22:25], v[146:149], v[194:197], v[22:25]
	v_mfma_f32_16x16x32_bf16 v[22:25], v[150:153], v[198:201], v[22:25]
	v_mfma_f32_16x16x32_bf16 v[6:9], v[146:149], v[202:205], v[6:9]
	v_mfma_f32_16x16x32_bf16 v[6:9], v[150:153], v[206:209], v[6:9]
	v_mfma_f32_16x16x32_bf16 v[2:5], v[154:157], v[202:205], v[2:5]
	v_mfma_f32_16x16x32_bf16 v[2:5], v[158:161], v[206:209], v[2:5]
	v_mfma_f32_16x16x32_bf16 v[18:21], v[154:157], v[194:197], v[18:21]
	v_mfma_f32_16x16x32_bf16 v[18:21], v[158:161], v[198:201], v[18:21]
	v_mfma_f32_16x16x32_bf16 v[34:37], v[154:157], v[184:187], v[34:37]
	v_mfma_f32_16x16x32_bf16 v[34:37], v[158:161], v[190:193], v[34:37]
	v_mfma_f32_16x16x32_bf16 v[50:53], v[154:157], v[162:165], v[50:53]
	v_mfma_f32_16x16x32_bf16 v[50:53], v[158:161], v[166:169], v[50:53]
	s_barrier
	s_setprio 0
	s_add_i32 s73, s73, 2
	s_add_u32 s82, s82, 0x100
	s_addc_u32 s83, s83, 0
	s_add_u32 s59, s59, 0x100
	s_addc_u32 s71, s71, 0
	s_cmp_gt_u32 s73, 29
	s_cbranch_scc0 .LBB0_541
	s_branch .Lpeel_541_x
.LBB0_541:
	s_add_u32 s0, s82, 0xfff80080
	s_addc_u32 s1, s83, -1
	s_add_i32 s79, 0, 0x10000
	s_cmp_eq_u32 s73, 28
	s_cselect_b32 s87, s40, s1
	s_cselect_b32 s86, s41, s0
	s_cselect_b32 s85, s57, s71
	s_cselect_b32 s84, s58, s59
	s_add_i32 s81, 0, 0x14000
	ds_read_b128 v[90:93], v210
	ds_read_b128 v[94:97], v210 offset:1024
	ds_read_b128 v[98:101], v210 offset:2048
	ds_read_b128 v[102:105], v210 offset:3072
	ds_read_b128 v[146:149], v210 offset:16384
	ds_read_b128 v[150:153], v210 offset:17408
	ds_read_b128 v[154:157], v210 offset:18432
	ds_read_b128 v[158:161], v210 offset:19456
	s_add_i32 m0, s44, 0xc000
	ds_read_b128 v[162:165], v230
	ds_read_b128 v[166:169], v230 offset:1024
	ds_read_b128 v[184:187], v230 offset:2048
	ds_read_b128 v[190:193], v230 offset:3072
	ds_read_b128 v[194:197], v230 offset:4096
	ds_read_b128 v[198:201], v230 offset:5120
	ds_read_b128 v[202:205], v230 offset:6144
	ds_read_b128 v[206:209], v230 offset:7168
	global_load_lds_dwordx4 v180, s[82:83]
	s_add_i32 m0, s44, 0xe000
	s_nop 0
	global_load_lds_dwordx4 v188, s[82:83]
	s_waitcnt vmcnt(8)
	s_waitcnt lgkmcnt(0)
	.p2align 3
	s_setprio 1
	s_barrier
; #define PG8_STAGE(bufoff, gbase, voff) do { _Pragma("unroll") for (int _i = 0; _i < 2; ++_i) \
;         __builtin_amdgcn_global_load_lds((const unsigned*)((const char*)(gbase) + (voff)[_i]), (PG8_LAS unsigned*)(lds + (bufoff) + ldsw + _i * 8192), 16, 0, 0); } while (0)
; #define PG8_LDA(dst, b, h) do { _Pragma("unroll") for (int m = 0; m < 4; ++m) _Pragma("unroll") for (int k = 0; k < 2; ++k) dst[m][k] = *(const PG8_LAS bf16x8*)(lds + PG8_SA(b, h) + aoff + m * 2048 + k * 1024); } while (0)
; #define PG8_LDB(dst, b, h) do { _Pragma("unroll") for (int n = 0; n < 2; ++n) _Pragma("unroll") for (int k = 0; k < 2; ++k) dst[n][k] = *(const PG8_LAS bf16x8*)(lds + PG8_SB(b, h) + boff + n * 2048 + k * 1024); } while (0)
; #define PG8_WAIT_V(n) asm volatile("s_waitcnt vmcnt(" #n ")" ::: "memory")
; #define PG8_WAIT_L(n) asm volatile("s_waitcnt lgkmcnt(" #n ")" ::: "memory")
; #define PG8_WAIT_V_SEL(sel) asm volatile("s_cmp_eq_u32 %0, 0\n\ts_cbranch_scc1 .Lw8_%=\n\ts_waitcnt vmcnt(22)\n\ts_branch .Lwd_%=\n.Lw8_%=:\n\ts_waitcnt vmcnt(8)\n.Lwd_%=:" :: "s"(sel) : "memory", "scc")
; #define PG8_BAR __builtin_amdgcn_s_barrier()
; #define PG8_SCHED __builtin_amdgcn_sched_barrier(0)
;     ...
;             PG8_WAIT_L(0); PG8_BAR; PG8_MMA(0, 0, At, B0); PG8_MMA(0, 1, At, B1); PG8_BAR; PG8_SCHED;
;             PG8_LDA(At, 0, 1); PG8_STAGE(PG8_SB(0, 0), b2, voffB); PG8_STAGE(PG8_SB(0, 1), b2 + hstep, voffB); PG8_STAGE(PG8_SA(0, 0), a2, voffA);
;             PG8_WAIT_V_SEL(relax);
;             PG8_WAIT_L(0); PG8_BAR; PG8_MMA(1, 0, At, B0); PG8_MMA(1, 1, At, B1); PG8_BAR; PG8_SCHED;
;             PG8_LDB(B0, 1, 0); PG8_LDB(B1, 1, 1); PG8_SCHED; PG8_LDA(At, 1, 0); PG8_STAGE(PG8_SA(0, 1), a2 + hstep, voffA);
;             PG8_WAIT_V(8); PG8_WAIT_L(0); PG8_BAR; PG8_MMA(0, 0, At, B0); PG8_MMA(0, 1, At, B1); PG8_BAR; PG8_SCHED;
	v_mfma_f32_16x16x32_bf16 v[142:145], v[90:93], v[162:165], v[142:145]
	v_mfma_f32_16x16x32_bf16 v[142:145], v[94:97], v[166:169], v[142:145]
	v_mfma_f32_16x16x32_bf16 v[126:129], v[90:93], v[184:187], v[126:129]
	v_mfma_f32_16x16x32_bf16 v[126:129], v[94:97], v[190:193], v[126:129]
	v_mfma_f32_16x16x32_bf16 v[110:113], v[90:93], v[194:197], v[110:113]
	v_mfma_f32_16x16x32_bf16 v[110:113], v[94:97], v[198:201], v[110:113]
	v_mfma_f32_16x16x32_bf16 v[78:81], v[90:93], v[202:205], v[78:81]
	v_mfma_f32_16x16x32_bf16 v[78:81], v[94:97], v[206:209], v[78:81]
	v_mfma_f32_16x16x32_bf16 v[74:77], v[98:101], v[202:205], v[74:77]
	v_mfma_f32_16x16x32_bf16 v[74:77], v[102:105], v[206:209], v[74:77]
	v_mfma_f32_16x16x32_bf16 v[106:109], v[98:101], v[194:197], v[106:109]
	v_mfma_f32_16x16x32_bf16 v[106:109], v[102:105], v[198:201], v[106:109]
	v_mfma_f32_16x16x32_bf16 v[122:125], v[98:101], v[184:187], v[122:125]
	v_mfma_f32_16x16x32_bf16 v[122:125], v[102:105], v[190:193], v[122:125]
	v_mfma_f32_16x16x32_bf16 v[138:141], v[98:101], v[162:165], v[138:141]
	v_mfma_f32_16x16x32_bf16 v[138:141], v[102:105], v[166:169], v[138:141]
	v_mfma_f32_16x16x32_bf16 v[134:137], v[146:149], v[162:165], v[134:137]
	v_mfma_f32_16x16x32_bf16 v[134:137], v[150:153], v[166:169], v[134:137]
	v_mfma_f32_16x16x32_bf16 v[118:121], v[146:149], v[184:187], v[118:121]
	v_mfma_f32_16x16x32_bf16 v[118:121], v[150:153], v[190:193], v[118:121]
	v_mfma_f32_16x16x32_bf16 v[86:89], v[146:149], v[194:197], v[86:89]
	v_mfma_f32_16x16x32_bf16 v[86:89], v[150:153], v[198:201], v[86:89]
	v_mfma_f32_16x16x32_bf16 v[70:73], v[146:149], v[202:205], v[70:73]
	v_mfma_f32_16x16x32_bf16 v[70:73], v[150:153], v[206:209], v[70:73]
	v_mfma_f32_16x16x32_bf16 v[66:69], v[154:157], v[202:205], v[66:69]
	v_mfma_f32_16x16x32_bf16 v[66:69], v[158:161], v[206:209], v[66:69]
	v_mfma_f32_16x16x32_bf16 v[82:85], v[154:157], v[194:197], v[82:85]
	v_mfma_f32_16x16x32_bf16 v[82:85], v[158:161], v[198:201], v[82:85]
	v_mfma_f32_16x16x32_bf16 v[114:117], v[154:157], v[184:187], v[114:117]
	v_mfma_f32_16x16x32_bf16 v[114:117], v[158:161], v[190:193], v[114:117]
	v_mfma_f32_16x16x32_bf16 v[130:133], v[154:157], v[162:165], v[130:133]
	v_mfma_f32_16x16x32_bf16 v[130:133], v[158:161], v[166:169], v[130:133]
	s_barrier
	s_setprio 0
	s_add_i32 s0, s79, s30
	s_mov_b32 m0, s0
	ds_read_b128 v[162:165], v230 offset:16384
	ds_read_b128 v[166:169], v230 offset:17408
	ds_read_b128 v[184:187], v230 offset:18432
	ds_read_b128 v[190:193], v230 offset:19456
	ds_read_b128 v[194:197], v230 offset:20480
	ds_read_b128 v[198:201], v230 offset:21504
	ds_read_b128 v[202:205], v230 offset:22528
	ds_read_b128 v[206:209], v230 offset:23552
	global_load_lds_dwordx4 v182, s[84:85]
	s_add_i32 m0, s0, 0x2000
	s_add_u32 s0, s84, 0x80000
	s_addc_u32 s1, s85, 0
	s_add_i32 s79, s81, s30
	global_load_lds_dwordx4 v178, s[84:85]
	s_mov_b32 m0, s79
	s_nop 0
	global_load_lds_dwordx4 v182, s[0:1]
	s_add_i32 m0, s79, 0x2000
	s_nop 0
	global_load_lds_dwordx4 v178, s[0:1]
	s_mov_b32 m0, s44
	s_nop 0
	global_load_lds_dwordx4 v174, s[86:87]
	s_mov_b32 m0, s45
	s_nop 0
	global_load_lds_dwordx4 v176, s[86:87]
	s_waitcnt vmcnt(8)
	s_waitcnt lgkmcnt(0)
	.p2align 3
	s_setprio 1
	s_barrier
	v_mfma_f32_16x16x32_bf16 v[62:65], v[90:93], v[162:165], v[62:65]
	v_mfma_f32_16x16x32_bf16 v[62:65], v[94:97], v[166:169], v[62:65]
	v_mfma_f32_16x16x32_bf16 v[46:49], v[90:93], v[184:187], v[46:49]
	v_mfma_f32_16x16x32_bf16 v[46:49], v[94:97], v[190:193], v[46:49]
	v_mfma_f32_16x16x32_bf16 v[30:33], v[90:93], v[194:197], v[30:33]
	v_mfma_f32_16x16x32_bf16 v[30:33], v[94:97], v[198:201], v[30:33]
	v_mfma_f32_16x16x32_bf16 v[14:17], v[90:93], v[202:205], v[14:17]
	v_mfma_f32_16x16x32_bf16 v[14:17], v[94:97], v[206:209], v[14:17]
	v_mfma_f32_16x16x32_bf16 v[10:13], v[98:101], v[202:205], v[10:13]
	v_mfma_f32_16x16x32_bf16 v[10:13], v[102:105], v[206:209], v[10:13]
	v_mfma_f32_16x16x32_bf16 v[26:29], v[98:101], v[194:197], v[26:29]
	v_mfma_f32_16x16x32_bf16 v[26:29], v[102:105], v[198:201], v[26:29]
	v_mfma_f32_16x16x32_bf16 v[42:45], v[98:101], v[184:187], v[42:45]
	v_mfma_f32_16x16x32_bf16 v[42:45], v[102:105], v[190:193], v[42:45]
	v_mfma_f32_16x16x32_bf16 v[58:61], v[98:101], v[162:165], v[58:61]
	v_mfma_f32_16x16x32_bf16 v[58:61], v[102:105], v[166:169], v[58:61]
	v_mfma_f32_16x16x32_bf16 v[54:57], v[146:149], v[162:165], v[54:57]
	v_mfma_f32_16x16x32_bf16 v[54:57], v[150:153], v[166:169], v[54:57]
	v_mfma_f32_16x16x32_bf16 v[38:41], v[146:149], v[184:187], v[38:41]
	v_mfma_f32_16x16x32_bf16 v[38:41], v[150:153], v[190:193], v[38:41]
	v_mfma_f32_16x16x32_bf16 v[22:25], v[146:149], v[194:197], v[22:25]
	v_mfma_f32_16x16x32_bf16 v[22:25], v[150:153], v[198:201], v[22:25]
	v_mfma_f32_16x16x32_bf16 v[6:9], v[146:149], v[202:205], v[6:9]
	v_mfma_f32_16x16x32_bf16 v[6:9], v[150:153], v[206:209], v[6:9]
	v_mfma_f32_16x16x32_bf16 v[2:5], v[154:157], v[202:205], v[2:5]
	v_mfma_f32_16x16x32_bf16 v[2:5], v[158:161], v[206:209], v[2:5]
	v_mfma_f32_16x16x32_bf16 v[18:21], v[154:157], v[194:197], v[18:21]
	v_mfma_f32_16x16x32_bf16 v[18:21], v[158:161], v[198:201], v[18:21]
	v_mfma_f32_16x16x32_bf16 v[34:37], v[154:157], v[184:187], v[34:37]
	v_mfma_f32_16x16x32_bf16 v[34:37], v[158:161], v[190:193], v[34:37]
	v_mfma_f32_16x16x32_bf16 v[50:53], v[154:157], v[162:165], v[50:53]
	v_mfma_f32_16x16x32_bf16 v[50:53], v[158:161], v[166:169], v[50:53]
	s_barrier
; #define PG8_STAGE(bufoff, gbase, voff) do { _Pragma("unroll") for (int _i = 0; _i < 2; ++_i) \
;         __builtin_amdgcn_global_load_lds((const unsigned*)((const char*)(gbase) + (voff)[_i]), (PG8_LAS unsigned*)(lds + (bufoff) + ldsw + _i * 8192), 16, 0, 0); } while (0)
; #define PG8_LDA(dst, b, h) do { _Pragma("unroll") for (int m = 0; m < 4; ++m) _Pragma("unroll") for (int k = 0; k < 2; ++k) dst[m][k] = *(const PG8_LAS bf16x8*)(lds + PG8_SA(b, h) + aoff + m * 2048 + k * 1024); } while (0)
; #define PG8_LDB(dst, b, h) do { _Pragma("unroll") for (int n = 0; n < 2; ++n) _Pragma("unroll") for (int k = 0; k < 2; ++k) dst[n][k] = *(const PG8_LAS bf16x8*)(lds + PG8_SB(b, h) + boff + n * 2048 + k * 1024); } while (0)
; #define PG8_WAIT_V(n) asm volatile("s_waitcnt vmcnt(" #n ")" ::: "memory")
; #define PG8_WAIT_L(n) asm volatile("s_waitcnt lgkmcnt(" #n ")" ::: "memory")
; #define PG8_BAR __builtin_amdgcn_s_barrier()
; #define PG8_SCHED __builtin_amdgcn_sched_barrier(0)
;     ...
;             PG8_WAIT_L(0); PG8_BAR; PG8_MMA(1, 0, At, B0); PG8_MMA(1, 1, At, B1); PG8_BAR; PG8_SCHED;
;             PG8_LDB(B0, 1, 0); PG8_LDB(B1, 1, 1); PG8_SCHED; PG8_LDA(At, 1, 0); PG8_STAGE(PG8_SA(0, 1), a2 + hstep, voffA);
;             PG8_WAIT_V(8); PG8_WAIT_L(0); PG8_BAR; PG8_MMA(0, 0, At, B0); PG8_MMA(0, 1, At, B1); PG8_BAR; PG8_SCHED;
;             PG8_LDA(At, 1, 1); PG8_STAGE(PG8_SB(1, 0), b3, voffB); PG8_STAGE(PG8_SB(1, 1), b3 + hstep, voffB); PG8_STAGE(PG8_SA(1, 0), a3, voffA);
;             PG8_WAIT_V(8); PG8_WAIT_L(0); PG8_BAR; PG8_MMA(1, 0, At, B0); PG8_MMA(1, 1, At, B1); PG8_BAR; PG8_SCHED;
	s_setprio 0
	s_add_i32 s79, 0, 0x18000
	s_add_i32 s81, 0, 0x1c000
	ds_read_b128 v[90:93], v210 offset:32768
	ds_read_b128 v[94:97], v210 offset:33792
	ds_read_b128 v[98:101], v210 offset:34816
	ds_read_b128 v[102:105], v210 offset:35840
	ds_read_b128 v[146:149], v210 offset:49152
	ds_read_b128 v[150:153], v210 offset:50176
	ds_read_b128 v[154:157], v210 offset:51200
	ds_read_b128 v[158:161], v210 offset:52224
	s_add_u32 s0, s86, 0x80000
	s_addc_u32 s1, s87, 0
	s_mov_b32 m0, s46
	ds_read_b128 v[162:165], v230 offset:32768
	ds_read_b128 v[166:169], v230 offset:33792
	ds_read_b128 v[184:187], v230 offset:34816
	ds_read_b128 v[190:193], v230 offset:35840
	ds_read_b128 v[194:197], v230 offset:36864
	ds_read_b128 v[198:201], v230 offset:37888
	ds_read_b128 v[202:205], v230 offset:38912
	ds_read_b128 v[206:209], v230 offset:39936
	global_load_lds_dwordx4 v174, s[0:1]
	s_mov_b32 m0, s47
	s_nop 0
	global_load_lds_dwordx4 v176, s[0:1]
	s_waitcnt vmcnt(8)
	s_waitcnt lgkmcnt(0)
	.p2align 3
	s_setprio 1
	s_barrier
	v_mfma_f32_16x16x32_bf16 v[142:145], v[90:93], v[162:165], v[142:145]
	v_mfma_f32_16x16x32_bf16 v[142:145], v[94:97], v[166:169], v[142:145]
	v_mfma_f32_16x16x32_bf16 v[126:129], v[90:93], v[184:187], v[126:129]
	v_mfma_f32_16x16x32_bf16 v[126:129], v[94:97], v[190:193], v[126:129]
	v_mfma_f32_16x16x32_bf16 v[110:113], v[90:93], v[194:197], v[110:113]
	v_mfma_f32_16x16x32_bf16 v[110:113], v[94:97], v[198:201], v[110:113]
	v_mfma_f32_16x16x32_bf16 v[78:81], v[90:93], v[202:205], v[78:81]
	v_mfma_f32_16x16x32_bf16 v[78:81], v[94:97], v[206:209], v[78:81]
	v_mfma_f32_16x16x32_bf16 v[74:77], v[98:101], v[202:205], v[74:77]
	v_mfma_f32_16x16x32_bf16 v[74:77], v[102:105], v[206:209], v[74:77]
	v_mfma_f32_16x16x32_bf16 v[106:109], v[98:101], v[194:197], v[106:109]
	v_mfma_f32_16x16x32_bf16 v[106:109], v[102:105], v[198:201], v[106:109]
	v_mfma_f32_16x16x32_bf16 v[122:125], v[98:101], v[184:187], v[122:125]
	v_mfma_f32_16x16x32_bf16 v[122:125], v[102:105], v[190:193], v[122:125]
	v_mfma_f32_16x16x32_bf16 v[138:141], v[98:101], v[162:165], v[138:141]
	v_mfma_f32_16x16x32_bf16 v[138:141], v[102:105], v[166:169], v[138:141]
	v_mfma_f32_16x16x32_bf16 v[134:137], v[146:149], v[162:165], v[134:137]
	v_mfma_f32_16x16x32_bf16 v[134:137], v[150:153], v[166:169], v[134:137]
	v_mfma_f32_16x16x32_bf16 v[118:121], v[146:149], v[184:187], v[118:121]
	v_mfma_f32_16x16x32_bf16 v[118:121], v[150:153], v[190:193], v[118:121]
	v_mfma_f32_16x16x32_bf16 v[86:89], v[146:149], v[194:197], v[86:89]
	v_mfma_f32_16x16x32_bf16 v[86:89], v[150:153], v[198:201], v[86:89]
	v_mfma_f32_16x16x32_bf16 v[70:73], v[146:149], v[202:205], v[70:73]
	v_mfma_f32_16x16x32_bf16 v[70:73], v[150:153], v[206:209], v[70:73]
	v_mfma_f32_16x16x32_bf16 v[66:69], v[154:157], v[202:205], v[66:69]
	v_mfma_f32_16x16x32_bf16 v[66:69], v[158:161], v[206:209], v[66:69]
	v_mfma_f32_16x16x32_bf16 v[82:85], v[154:157], v[194:197], v[82:85]
	v_mfma_f32_16x16x32_bf16 v[82:85], v[158:161], v[198:201], v[82:85]
	v_mfma_f32_16x16x32_bf16 v[114:117], v[154:157], v[184:187], v[114:117]
	v_mfma_f32_16x16x32_bf16 v[114:117], v[158:161], v[190:193], v[114:117]
	v_mfma_f32_16x16x32_bf16 v[130:133], v[154:157], v[162:165], v[130:133]
	v_mfma_f32_16x16x32_bf16 v[130:133], v[158:161], v[166:169], v[130:133]
	s_barrier
	s_setprio 0
	s_add_i32 s0, s79, s30
	s_mov_b32 m0, s0
	ds_read_b128 v[162:165], v230 offset:49152
	ds_read_b128 v[166:169], v230 offset:50176
	ds_read_b128 v[184:187], v230 offset:51200
	ds_read_b128 v[190:193], v230 offset:52224
	ds_read_b128 v[194:197], v230 offset:53248
	ds_read_b128 v[198:201], v230 offset:54272
	ds_read_b128 v[202:205], v230 offset:55296
	ds_read_b128 v[206:209], v230 offset:56320
	s_add_u32 s100, s84, 0x80
	s_addc_u32 s101, s85, 0
	global_load_lds_dwordx4 v182, s[100:101]
	s_add_i32 m0, s0, 0x2000
	s_add_u32 s0, s84, 0x80080
	s_addc_u32 s1, s85, 0
	s_add_i32 s79, s81, s30
	global_load_lds_dwordx4 v178, s[100:101]
	s_mov_b32 m0, s79
	s_nop 0
	global_load_lds_dwordx4 v182, s[0:1]
	s_add_i32 m0, s79, 0x2000
	s_nop 0
	global_load_lds_dwordx4 v178, s[0:1]
	s_mov_b32 m0, s49
	s_nop 0
	s_add_u32 s100, s86, 0x80
	s_addc_u32 s101, s87, 0
	global_load_lds_dwordx4 v174, s[100:101]
	s_mov_b32 m0, s50
	s_nop 0
	global_load_lds_dwordx4 v176, s[100:101]
	s_waitcnt vmcnt(8)
	s_waitcnt lgkmcnt(0)
	.p2align 3
	s_setprio 1
	s_barrier
	v_mfma_f32_16x16x32_bf16 v[62:65], v[90:93], v[162:165], v[62:65]
	v_mfma_f32_16x16x32_bf16 v[62:65], v[94:97], v[166:169], v[62:65]
	v_mfma_f32_16x16x32_bf16 v[46:49], v[90:93], v[184:187], v[46:49]
	v_mfma_f32_16x16x32_bf16 v[46:49], v[94:97], v[190:193], v[46:49]
	v_mfma_f32_16x16x32_bf16 v[30:33], v[90:93], v[194:197], v[30:33]
	v_mfma_f32_16x16x32_bf16 v[30:33], v[94:97], v[198:201], v[30:33]
	v_mfma_f32_16x16x32_bf16 v[14:17], v[90:93], v[202:205], v[14:17]
	v_mfma_f32_16x16x32_bf16 v[14:17], v[94:97], v[206:209], v[14:17]
	v_mfma_f32_16x16x32_bf16 v[10:13], v[98:101], v[202:205], v[10:13]
	v_mfma_f32_16x16x32_bf16 v[10:13], v[102:105], v[206:209], v[10:13]
	v_mfma_f32_16x16x32_bf16 v[26:29], v[98:101], v[194:197], v[26:29]
	v_mfma_f32_16x16x32_bf16 v[26:29], v[102:105], v[198:201], v[26:29]
	v_mfma_f32_16x16x32_bf16 v[42:45], v[98:101], v[184:187], v[42:45]
	v_mfma_f32_16x16x32_bf16 v[42:45], v[102:105], v[190:193], v[42:45]
	v_mfma_f32_16x16x32_bf16 v[58:61], v[98:101], v[162:165], v[58:61]
	v_mfma_f32_16x16x32_bf16 v[58:61], v[102:105], v[166:169], v[58:61]
	v_mfma_f32_16x16x32_bf16 v[54:57], v[146:149], v[162:165], v[54:57]
	v_mfma_f32_16x16x32_bf16 v[54:57], v[150:153], v[166:169], v[54:57]
	v_mfma_f32_16x16x32_bf16 v[38:41], v[146:149], v[184:187], v[38:41]
	v_mfma_f32_16x16x32_bf16 v[38:41], v[150:153], v[190:193], v[38:41]
	v_mfma_f32_16x16x32_bf16 v[22:25], v[146:149], v[194:197], v[22:25]
	v_mfma_f32_16x16x32_bf16 v[22:25], v[150:153], v[198:201], v[22:25]
	v_mfma_f32_16x16x32_bf16 v[6:9], v[146:149], v[202:205], v[6:9]
	v_mfma_f32_16x16x32_bf16 v[6:9], v[150:153], v[206:209], v[6:9]
	v_mfma_f32_16x16x32_bf16 v[2:5], v[154:157], v[202:205], v[2:5]
	v_mfma_f32_16x16x32_bf16 v[2:5], v[158:161], v[206:209], v[2:5]
	v_mfma_f32_16x16x32_bf16 v[18:21], v[154:157], v[194:197], v[18:21]
	v_mfma_f32_16x16x32_bf16 v[18:21], v[158:161], v[198:201], v[18:21]
	v_mfma_f32_16x16x32_bf16 v[34:37], v[154:157], v[184:187], v[34:37]
	v_mfma_f32_16x16x32_bf16 v[34:37], v[158:161], v[190:193], v[34:37]
	v_mfma_f32_16x16x32_bf16 v[50:53], v[154:157], v[162:165], v[50:53]
	v_mfma_f32_16x16x32_bf16 v[50:53], v[158:161], v[166:169], v[50:53]
	s_barrier
	s_setprio 0
	s_add_i32 s73, s73, 2
	s_add_u32 s82, s82, 0x100
	s_addc_u32 s83, s83, 0
	s_add_u32 s59, s59, 0x100
	s_addc_u32 s71, s71, 0
	s_cmp_gt_u32 s73, 29
	s_cbranch_scc0 .LBB0_541
.Lpeel_541_x:
	s_branch .Lrlx_go_x
.Lrlx_go_0:
	s_waitcnt vmcnt(22)
	s_branch .Lrlx_go_0_b

; #define PG8_STAGE(bufoff, gbase, voff) do { _Pragma("unroll") for (int _i = 0; _i < 2; ++_i) \
;         __builtin_amdgcn_global_load_lds((const unsigned*)((const char*)(gbase) + (voff)[_i]), (PG8_LAS unsigned*)(lds + (bufoff) + ldsw + _i * 8192), 16, 0, 0); } while (0)
; #define PG8_LDA(dst, b, h) do { _Pragma("unroll") for (int m = 0; m < 4; ++m) _Pragma("unroll") for (int k = 0; k < 2; ++k) dst[m][k] = *(const PG8_LAS bf16x8*)(lds + PG8_SA(b, h) + aoff + m * 2048 + k * 1024); } while (0)
; #define PG8_LDB(dst, b, h) do { _Pragma("unroll") for (int n = 0; n < 2; ++n) _Pragma("unroll") for (int k = 0; k < 2; ++k) dst[n][k] = *(const PG8_LAS bf16x8*)(lds + PG8_SB(b, h) + boff + n * 2048 + k * 1024); } while (0)
; #define PG8_WAIT_L(n) asm volatile("s_waitcnt lgkmcnt(" #n ")" ::: "memory")
; #define PG8_WAIT_V_SEL(sel) asm volatile("s_cmp_eq_u32 %0, 0\n\ts_cbranch_scc1 .Lw8_%=\n\ts_waitcnt vmcnt(22)\n\ts_branch .Lwd_%=\n.Lw8_%=:\n\ts_waitcnt vmcnt(8)\n.Lwd_%=:" :: "s"(sel) : "memory", "scc")
;     ...
;         const char* nA = has_next ? (const char*)g.A + (size_t)nxt.pm * tstep : cA; const char* nB = has_next ? (const char*)g.Bt + (size_t)nxt.pn * tstep : cB;
;         for (int t = 0; t < nt * KREP; t += 2) {
;             const bool last = (t == nt * KREP - 2);
;             const int t1w = KREP > 1 ? ((t + 1) & (nt - 1)) : t + 1, t2w = KREP > 1 ? ((t + 2) & (nt - 1)) : t + 2;
;             const char* a1 = cA + (size_t)t1w * kstep;
;             const char* a2 = last ? nA : cA + (size_t)t2w * kstep; const char* b2 = last ? nB : cB + (size_t)t2w * kstep;
;             const char* a3 = a2 + kstep; const char* b3 = b2 + kstep;
;             if (last && has_next) S.a_ready(nxt);
;             const int relax = __builtin_amdgcn_readfirstlane((MK_RELAXW && t == 0 && ui > 0) ? 1 : 0);
;             if constexpr (SP2) {
;             PG8_LDB(B0, 0, 0); PG8_LDB(B1, 0, 1); PG8_SCHED; PG8_LDA(At, 0, 0); PG8_STAGE(PG8_SA(1, 1), a1 + hstep, voffA);
;             PG8_WAIT_V_SEL(relax);
;             PG8_WAIT_L(0); PG8_BAR; PG8_MMA(0, 0, At, B0); PG8_MMA(0, 1, At, B1); PG8_BAR; PG8_SCHED;
;             PG8_LDA(At, 0, 1); PG8_STAGE(PG8_SB(0, 0), b2, voffB); PG8_STAGE(PG8_SB(0, 1), b2 + hstep, voffB); PG8_STAGE(PG8_SA(0, 0), a2, voffA);
;             PG8_WAIT_V_SEL(relax);
;             PG8_WAIT_L(0); PG8_BAR; PG8_MMA(1, 0, At, B0); PG8_MMA(1, 1, At, B1); PG8_BAR; PG8_SCHED;
.LBB0_595:
	s_ashr_i32 s67, s66, 31
	s_lshl_b64 s[0:1], s[66:67], 20
	s_add_u32 s68, s31, s0
	s_addc_u32 s69, s33, s1
	s_and_b64 s[0:1], s[2:3], exec
	s_cselect_b32 s40, s69, s75
	s_cselect_b32 s41, s68, s74
	s_ashr_i32 s65, s64, 31
	s_lshl_b64 s[0:1], s[64:65], 20
	s_add_u32 s70, s24, s0
	s_addc_u32 s71, s30, s1
	s_and_b64 s[0:1], s[2:3], exec
	s_cselect_b32 s65, s71, s77
	s_cselect_b32 s73, s70, s76
	s_add_u32 s74, s74, 0x80080
	s_addc_u32 s75, s75, 0
	s_add_u32 s80, s76, 0x100
	s_addc_u32 s81, s77, 0
	s_mov_b32 s82, -2
	v_add_u32_e32 v180, 0x10000, v146
	s_add_u32 s0, s74, 0xfff80080
	s_addc_u32 s1, s75, -1
	s_add_i32 s83, 0, 0x10000
	s_cmp_eq_u32 s82, 28
	s_cselect_b32 s79, s40, s1
	s_cselect_b32 s78, s41, s0
	s_cselect_b32 s77, s65, s81
	s_cselect_b32 s76, s73, s80
	s_add_i32 s84, 0, 0x14000
	ds_read_b128 v[150:153], v180
	ds_read_b128 v[154:157], v180 offset:1024
	ds_read_b128 v[158:161], v180 offset:2048
	ds_read_b128 v[162:165], v180 offset:3072
	ds_read_b128 v[166:169], v180 offset:16384
	ds_read_b128 v[172:175], v180 offset:17408
	ds_read_b128 v[176:179], v180 offset:18432
	ds_read_b128 v[188:191], v180 offset:19456
	s_add_i32 m0, s35, 0xc000
	ds_read_b128 v[192:195], v148
	ds_read_b128 v[196:199], v148 offset:1024
	ds_read_b128 v[200:203], v148 offset:2048
	ds_read_b128 v[204:207], v148 offset:3072
	ds_read_b128 v[208:211], v148 offset:4096
	ds_read_b128 v[212:215], v148 offset:5120
	ds_read_b128 v[216:219], v148 offset:6144
	ds_read_b128 v[220:223], v148 offset:7168
	global_load_lds_dwordx4 v140, s[74:75]
	s_add_i32 m0, s35, 0xe000
	s_nop 0
	global_load_lds_dwordx4 v142, s[74:75]
	s_cmp_lg_u32 s26, 0
	s_cbranch_scc1 .Lrlx_qkv_0
	s_waitcnt vmcnt(8)
.Lrlx_qkv_0_b:
	s_waitcnt lgkmcnt(0)
	.p2align 3
	s_setprio 1
	s_barrier
	v_mfma_f32_16x16x32_bf16 v[126:129], v[150:153], v[192:195], 0
	v_mfma_f32_16x16x32_bf16 v[126:129], v[154:157], v[196:199], v[126:129]
	v_mfma_f32_16x16x32_bf16 v[122:125], v[150:153], v[200:203], 0
	v_mfma_f32_16x16x32_bf16 v[122:125], v[154:157], v[204:207], v[122:125]
	v_mfma_f32_16x16x32_bf16 v[118:121], v[150:153], v[208:211], 0
	v_mfma_f32_16x16x32_bf16 v[118:121], v[154:157], v[212:215], v[118:121]
	v_mfma_f32_16x16x32_bf16 v[114:117], v[150:153], v[216:219], 0
	v_mfma_f32_16x16x32_bf16 v[114:117], v[154:157], v[220:223], v[114:117]
	v_mfma_f32_16x16x32_bf16 v[98:101], v[158:161], v[216:219], 0
	v_mfma_f32_16x16x32_bf16 v[98:101], v[162:165], v[220:223], v[98:101]
	v_mfma_f32_16x16x32_bf16 v[102:105], v[158:161], v[208:211], 0
	v_mfma_f32_16x16x32_bf16 v[102:105], v[162:165], v[212:215], v[102:105]
	v_mfma_f32_16x16x32_bf16 v[106:109], v[158:161], v[200:203], 0
	v_mfma_f32_16x16x32_bf16 v[106:109], v[162:165], v[204:207], v[106:109]
	v_mfma_f32_16x16x32_bf16 v[110:113], v[158:161], v[192:195], 0
	v_mfma_f32_16x16x32_bf16 v[110:113], v[162:165], v[196:199], v[110:113]
	v_mfma_f32_16x16x32_bf16 v[70:73], v[166:169], v[192:195], 0
	v_mfma_f32_16x16x32_bf16 v[70:73], v[172:175], v[196:199], v[70:73]
	v_mfma_f32_16x16x32_bf16 v[66:69], v[166:169], v[200:203], 0
	v_mfma_f32_16x16x32_bf16 v[66:69], v[172:175], v[204:207], v[66:69]
	v_mfma_f32_16x16x32_bf16 v[58:61], v[166:169], v[208:211], 0
	v_mfma_f32_16x16x32_bf16 v[58:61], v[172:175], v[212:215], v[58:61]
	v_mfma_f32_16x16x32_bf16 v[46:49], v[166:169], v[216:219], 0
	v_mfma_f32_16x16x32_bf16 v[46:49], v[172:175], v[220:223], v[46:49]
	v_mfma_f32_16x16x32_bf16 v[34:37], v[176:179], v[216:219], 0
	v_mfma_f32_16x16x32_bf16 v[34:37], v[188:191], v[220:223], v[34:37]
	v_mfma_f32_16x16x32_bf16 v[38:41], v[176:179], v[208:211], 0
	v_mfma_f32_16x16x32_bf16 v[38:41], v[188:191], v[212:215], v[38:41]
	v_mfma_f32_16x16x32_bf16 v[42:45], v[176:179], v[200:203], 0
	v_mfma_f32_16x16x32_bf16 v[42:45], v[188:191], v[204:207], v[42:45]
	v_mfma_f32_16x16x32_bf16 v[50:53], v[176:179], v[192:195], 0
	v_mfma_f32_16x16x32_bf16 v[50:53], v[188:191], v[196:199], v[50:53]
	s_barrier
	s_setprio 0
	s_add_i32 s0, s83, s20
	s_mov_b32 m0, s0
	ds_read_b128 v[192:195], v148 offset:16384
	ds_read_b128 v[196:199], v148 offset:17408
	ds_read_b128 v[200:203], v148 offset:18432
	ds_read_b128 v[204:207], v148 offset:19456
	ds_read_b128 v[208:211], v148 offset:20480
	ds_read_b128 v[212:215], v148 offset:21504
	ds_read_b128 v[216:219], v148 offset:22528
	ds_read_b128 v[220:223], v148 offset:23552
	global_load_lds_dwordx4 v132, s[76:77]
	s_add_i32 m0, s0, 0x2000
	s_add_u32 s0, s76, 0x80000
	s_addc_u32 s1, s77, 0
	s_add_i32 s83, s84, s20
	global_load_lds_dwordx4 v136, s[76:77]
	s_mov_b32 m0, s83
	s_nop 0
	global_load_lds_dwordx4 v132, s[0:1]
	s_add_i32 m0, s83, 0x2000
	s_nop 0
	global_load_lds_dwordx4 v136, s[0:1]
	s_mov_b32 m0, s35
	s_nop 0
	global_load_lds_dwordx4 v130, s[78:79]
	s_mov_b32 m0, s37
	s_nop 0
	global_load_lds_dwordx4 v134, s[78:79]
	s_cmp_lg_u32 s26, 0
	s_cbranch_scc1 .Lrlx_qkv_1
	s_waitcnt vmcnt(8)
; #define PG8_STAGE(bufoff, gbase, voff) do { _Pragma("unroll") for (int _i = 0; _i < 2; ++_i) \
;         __builtin_amdgcn_global_load_lds((const unsigned*)((const char*)(gbase) + (voff)[_i]), (PG8_LAS unsigned*)(lds + (bufoff) + ldsw + _i * 8192), 16, 0, 0); } while (0)
; #define PG8_LDA(dst, b, h) do { _Pragma("unroll") for (int m = 0; m < 4; ++m) _Pragma("unroll") for (int k = 0; k < 2; ++k) dst[m][k] = *(const PG8_LAS bf16x8*)(lds + PG8_SA(b, h) + aoff + m * 2048 + k * 1024); } while (0)
; #define PG8_LDB(dst, b, h) do { _Pragma("unroll") for (int n = 0; n < 2; ++n) _Pragma("unroll") for (int k = 0; k < 2; ++k) dst[n][k] = *(const PG8_LAS bf16x8*)(lds + PG8_SB(b, h) + boff + n * 2048 + k * 1024); } while (0)
; #define PG8_WAIT_V(n) asm volatile("s_waitcnt vmcnt(" #n ")" ::: "memory")
; #define PG8_WAIT_L(n) asm volatile("s_waitcnt lgkmcnt(" #n ")" ::: "memory")
; #define PG8_WAIT_V_SEL(sel) asm volatile("s_cmp_eq_u32 %0, 0\n\ts_cbranch_scc1 .Lw8_%=\n\ts_waitcnt vmcnt(22)\n\ts_branch .Lwd_%=\n.Lw8_%=:\n\ts_waitcnt vmcnt(8)\n.Lwd_%=:" :: "s"(sel) : "memory", "scc")
; #define PG8_BAR __builtin_amdgcn_s_barrier()
; #define PG8_SCHED __builtin_amdgcn_sched_barrier(0)
;     ...
;             PG8_WAIT_L(0); PG8_BAR; PG8_MMA(0, 0, At, B0); PG8_MMA(0, 1, At, B1); PG8_BAR; PG8_SCHED;
;             PG8_LDA(At, 0, 1); PG8_STAGE(PG8_SB(0, 0), b2, voffB); PG8_STAGE(PG8_SB(0, 1), b2 + hstep, voffB); PG8_STAGE(PG8_SA(0, 0), a2, voffA);
;             PG8_WAIT_V_SEL(relax);
;             PG8_WAIT_L(0); PG8_BAR; PG8_MMA(1, 0, At, B0); PG8_MMA(1, 1, At, B1); PG8_BAR; PG8_SCHED;
;             PG8_LDB(B0, 1, 0); PG8_LDB(B1, 1, 1); PG8_SCHED; PG8_LDA(At, 1, 0); PG8_STAGE(PG8_SA(0, 1), a2 + hstep, voffA);
;             PG8_WAIT_V(8); PG8_WAIT_L(0); PG8_BAR; PG8_MMA(0, 0, At, B0); PG8_MMA(0, 1, At, B1); PG8_BAR; PG8_SCHED;
.Lrlx_qkv_1_b:
	s_waitcnt lgkmcnt(0)
	.p2align 3
	s_setprio 1
	s_barrier
	v_mfma_f32_16x16x32_bf16 v[94:97], v[150:153], v[192:195], 0
	v_mfma_f32_16x16x32_bf16 v[94:97], v[154:157], v[196:199], v[94:97]
	v_mfma_f32_16x16x32_bf16 v[90:93], v[150:153], v[200:203], 0
	v_mfma_f32_16x16x32_bf16 v[90:93], v[154:157], v[204:207], v[90:93]
	v_mfma_f32_16x16x32_bf16 v[86:89], v[150:153], v[208:211], 0
	v_mfma_f32_16x16x32_bf16 v[86:89], v[154:157], v[212:215], v[86:89]
	v_mfma_f32_16x16x32_bf16 v[82:85], v[150:153], v[216:219], 0
	v_mfma_f32_16x16x32_bf16 v[82:85], v[154:157], v[220:223], v[82:85]
	v_mfma_f32_16x16x32_bf16 v[54:57], v[158:161], v[216:219], 0
	v_mfma_f32_16x16x32_bf16 v[54:57], v[162:165], v[220:223], v[54:57]
	v_mfma_f32_16x16x32_bf16 v[62:65], v[158:161], v[208:211], 0
	v_mfma_f32_16x16x32_bf16 v[62:65], v[162:165], v[212:215], v[62:65]
	v_mfma_f32_16x16x32_bf16 v[74:77], v[158:161], v[200:203], 0
	v_mfma_f32_16x16x32_bf16 v[74:77], v[162:165], v[204:207], v[74:77]
	v_mfma_f32_16x16x32_bf16 v[78:81], v[158:161], v[192:195], 0
	v_mfma_f32_16x16x32_bf16 v[78:81], v[162:165], v[196:199], v[78:81]
	v_mfma_f32_16x16x32_bf16 v[30:33], v[166:169], v[192:195], 0
	v_mfma_f32_16x16x32_bf16 v[30:33], v[172:175], v[196:199], v[30:33]
	v_mfma_f32_16x16x32_bf16 v[26:29], v[166:169], v[200:203], 0
	v_mfma_f32_16x16x32_bf16 v[26:29], v[172:175], v[204:207], v[26:29]
	v_mfma_f32_16x16x32_bf16 v[22:25], v[166:169], v[208:211], 0
	v_mfma_f32_16x16x32_bf16 v[22:25], v[172:175], v[212:215], v[22:25]
	v_mfma_f32_16x16x32_bf16 v[18:21], v[166:169], v[216:219], 0
	v_mfma_f32_16x16x32_bf16 v[18:21], v[172:175], v[220:223], v[18:21]
	v_mfma_f32_16x16x32_bf16 v[2:5], v[176:179], v[216:219], 0
	v_mfma_f32_16x16x32_bf16 v[2:5], v[188:191], v[220:223], v[2:5]
	v_mfma_f32_16x16x32_bf16 v[6:9], v[176:179], v[208:211], 0
	v_mfma_f32_16x16x32_bf16 v[6:9], v[188:191], v[212:215], v[6:9]
	v_mfma_f32_16x16x32_bf16 v[10:13], v[176:179], v[200:203], 0
	v_mfma_f32_16x16x32_bf16 v[10:13], v[188:191], v[204:207], v[10:13]
	v_mfma_f32_16x16x32_bf16 v[14:17], v[176:179], v[192:195], 0
	v_mfma_f32_16x16x32_bf16 v[14:17], v[188:191], v[196:199], v[14:17]
	s_barrier
	s_setprio 0
	s_add_i32 s83, 0, 0x18000
	s_add_i32 s84, 0, 0x1c000
	ds_read_b128 v[150:153], v180 offset:32768
	ds_read_b128 v[154:157], v180 offset:33792
	ds_read_b128 v[158:161], v180 offset:34816
	ds_read_b128 v[162:165], v180 offset:35840
	ds_read_b128 v[166:169], v180 offset:49152
	ds_read_b128 v[172:175], v180 offset:50176
	ds_read_b128 v[176:179], v180 offset:51200
	ds_read_b128 v[188:191], v180 offset:52224
	s_add_u32 s0, s78, 0x80000
	s_addc_u32 s1, s79, 0
	s_mov_b32 m0, s43
	ds_read_b128 v[192:195], v148 offset:32768
	ds_read_b128 v[196:199], v148 offset:33792
	ds_read_b128 v[200:203], v148 offset:34816
	ds_read_b128 v[204:207], v148 offset:35840
	ds_read_b128 v[208:211], v148 offset:36864
	ds_read_b128 v[212:215], v148 offset:37888
	ds_read_b128 v[216:219], v148 offset:38912
	ds_read_b128 v[220:223], v148 offset:39936
	global_load_lds_dwordx4 v130, s[0:1]
	s_mov_b32 m0, s44
	s_nop 0
	global_load_lds_dwordx4 v134, s[0:1]
	s_waitcnt vmcnt(8)
	s_waitcnt lgkmcnt(0)
	.p2align 3
	s_setprio 1
	s_barrier
	v_mfma_f32_16x16x32_bf16 v[126:129], v[150:153], v[192:195], v[126:129]
	v_mfma_f32_16x16x32_bf16 v[126:129], v[154:157], v[196:199], v[126:129]
	v_mfma_f32_16x16x32_bf16 v[122:125], v[150:153], v[200:203], v[122:125]
	v_mfma_f32_16x16x32_bf16 v[122:125], v[154:157], v[204:207], v[122:125]
	v_mfma_f32_16x16x32_bf16 v[118:121], v[150:153], v[208:211], v[118:121]
	v_mfma_f32_16x16x32_bf16 v[118:121], v[154:157], v[212:215], v[118:121]
	v_mfma_f32_16x16x32_bf16 v[114:117], v[150:153], v[216:219], v[114:117]
	v_mfma_f32_16x16x32_bf16 v[114:117], v[154:157], v[220:223], v[114:117]
	v_mfma_f32_16x16x32_bf16 v[98:101], v[158:161], v[216:219], v[98:101]
	v_mfma_f32_16x16x32_bf16 v[98:101], v[162:165], v[220:223], v[98:101]
	v_mfma_f32_16x16x32_bf16 v[102:105], v[158:161], v[208:211], v[102:105]
	v_mfma_f32_16x16x32_bf16 v[102:105], v[162:165], v[212:215], v[102:105]
	v_mfma_f32_16x16x32_bf16 v[106:109], v[158:161], v[200:203], v[106:109]
	v_mfma_f32_16x16x32_bf16 v[106:109], v[162:165], v[204:207], v[106:109]
	v_mfma_f32_16x16x32_bf16 v[110:113], v[158:161], v[192:195], v[110:113]
	v_mfma_f32_16x16x32_bf16 v[110:113], v[162:165], v[196:199], v[110:113]
	v_mfma_f32_16x16x32_bf16 v[70:73], v[166:169], v[192:195], v[70:73]
	v_mfma_f32_16x16x32_bf16 v[70:73], v[172:175], v[196:199], v[70:73]
	v_mfma_f32_16x16x32_bf16 v[66:69], v[166:169], v[200:203], v[66:69]
	v_mfma_f32_16x16x32_bf16 v[66:69], v[172:175], v[204:207], v[66:69]
	v_mfma_f32_16x16x32_bf16 v[58:61], v[166:169], v[208:211], v[58:61]
	v_mfma_f32_16x16x32_bf16 v[58:61], v[172:175], v[212:215], v[58:61]
	v_mfma_f32_16x16x32_bf16 v[46:49], v[166:169], v[216:219], v[46:49]
	v_mfma_f32_16x16x32_bf16 v[46:49], v[172:175], v[220:223], v[46:49]
	v_mfma_f32_16x16x32_bf16 v[34:37], v[176:179], v[216:219], v[34:37]
	v_mfma_f32_16x16x32_bf16 v[34:37], v[188:191], v[220:223], v[34:37]
	v_mfma_f32_16x16x32_bf16 v[38:41], v[176:179], v[208:211], v[38:41]
	v_mfma_f32_16x16x32_bf16 v[38:41], v[188:191], v[212:215], v[38:41]
	v_mfma_f32_16x16x32_bf16 v[42:45], v[176:179], v[200:203], v[42:45]
	v_mfma_f32_16x16x32_bf16 v[42:45], v[188:191], v[204:207], v[42:45]
	v_mfma_f32_16x16x32_bf16 v[50:53], v[176:179], v[192:195], v[50:53]
	v_mfma_f32_16x16x32_bf16 v[50:53], v[188:191], v[196:199], v[50:53]
	s_barrier
; #define PG8_STAGE(bufoff, gbase, voff) do { _Pragma("unroll") for (int _i = 0; _i < 2; ++_i) \
;         __builtin_amdgcn_global_load_lds((const unsigned*)((const char*)(gbase) + (voff)[_i]), (PG8_LAS unsigned*)(lds + (bufoff) + ldsw + _i * 8192), 16, 0, 0); } while (0)
; #define PG8_LDA(dst, b, h) do { _Pragma("unroll") for (int m = 0; m < 4; ++m) _Pragma("unroll") for (int k = 0; k < 2; ++k) dst[m][k] = *(const PG8_LAS bf16x8*)(lds + PG8_SA(b, h) + aoff + m * 2048 + k * 1024); } while (0)
; #define PG8_WAIT_V(n) asm volatile("s_waitcnt vmcnt(" #n ")" ::: "memory")
; #define PG8_WAIT_L(n) asm volatile("s_waitcnt lgkmcnt(" #n ")" ::: "memory")
;     ...
;         for (int t = 0; t < nt * KREP; t += 2) {
;             const bool last = (t == nt * KREP - 2);
;             const int t1w = KREP > 1 ? ((t + 1) & (nt - 1)) : t + 1, t2w = KREP > 1 ? ((t + 2) & (nt - 1)) : t + 2;
;             const char* a1 = cA + (size_t)t1w * kstep;
;             const char* a2 = last ? nA : cA + (size_t)t2w * kstep; const char* b2 = last ? nB : cB + (size_t)t2w * kstep;
;             const char* a3 = a2 + kstep; const char* b3 = b2 + kstep;
;             if (last && has_next) S.a_ready(nxt);
;             const int relax = __builtin_amdgcn_readfirstlane((MK_RELAXW && t == 0 && ui > 0) ? 1 : 0);
;             if constexpr (SP2) {
;             PG8_LDB(B0, 0, 0); PG8_LDB(B1, 0, 1); PG8_SCHED; PG8_LDA(At, 0, 0); PG8_STAGE(PG8_SA(1, 1), a1 + hstep, voffA);
;             PG8_WAIT_V_SEL(relax);
;             PG8_WAIT_L(0); PG8_BAR; PG8_MMA(0, 0, At, B0); PG8_MMA(0, 1, At, B1); PG8_BAR; PG8_SCHED;
;             PG8_LDA(At, 0, 1); PG8_STAGE(PG8_SB(0, 0), b2, voffB); PG8_STAGE(PG8_SB(0, 1), b2 + hstep, voffB); PG8_STAGE(PG8_SA(0, 0), a2, voffA);
;             PG8_WAIT_V_SEL(relax);
;             PG8_WAIT_L(0); PG8_BAR; PG8_MMA(1, 0, At, B0); PG8_MMA(1, 1, At, B1); PG8_BAR; PG8_SCHED;
;             PG8_LDB(B0, 1, 0); PG8_LDB(B1, 1, 1); PG8_SCHED; PG8_LDA(At, 1, 0); PG8_STAGE(PG8_SA(0, 1), a2 + hstep, voffA);
;             PG8_WAIT_V(8); PG8_WAIT_L(0); PG8_BAR; PG8_MMA(0, 0, At, B0); PG8_MMA(0, 1, At, B1); PG8_BAR; PG8_SCHED;
;             PG8_LDA(At, 1, 1); PG8_STAGE(PG8_SB(1, 0), b3, voffB); PG8_STAGE(PG8_SB(1, 1), b3 + hstep, voffB); PG8_STAGE(PG8_SA(1, 0), a3, voffA);
;             PG8_WAIT_V(8); PG8_WAIT_L(0); PG8_BAR; PG8_MMA(1, 0, At, B0); PG8_MMA(1, 1, At, B1); PG8_BAR; PG8_SCHED;
	s_setprio 0
	s_add_i32 s0, s83, s20
	s_mov_b32 m0, s0
	ds_read_b128 v[192:195], v148 offset:49152
	ds_read_b128 v[196:199], v148 offset:50176
	ds_read_b128 v[200:203], v148 offset:51200
	ds_read_b128 v[204:207], v148 offset:52224
	ds_read_b128 v[208:211], v148 offset:53248
	ds_read_b128 v[212:215], v148 offset:54272
	ds_read_b128 v[216:219], v148 offset:55296
	ds_read_b128 v[220:223], v148 offset:56320
	s_add_u32 s100, s76, 0x80
	s_addc_u32 s101, s77, 0
	global_load_lds_dwordx4 v132, s[100:101]
	s_add_i32 m0, s0, 0x2000
	s_add_u32 s0, s76, 0x80080
	s_addc_u32 s1, s77, 0
	s_add_i32 s76, s84, s20
	global_load_lds_dwordx4 v136, s[100:101]
	s_mov_b32 m0, s76
	s_nop 0
	global_load_lds_dwordx4 v132, s[0:1]
	s_add_i32 m0, s76, 0x2000
	s_nop 0
	global_load_lds_dwordx4 v136, s[0:1]
	s_mov_b32 m0, s48
	s_nop 0
	s_add_u32 s100, s78, 0x80
	s_addc_u32 s101, s79, 0
	global_load_lds_dwordx4 v130, s[100:101]
	s_mov_b32 m0, s49
	s_nop 0
	global_load_lds_dwordx4 v134, s[100:101]
	s_waitcnt vmcnt(8)
	s_waitcnt lgkmcnt(0)
	.p2align 3
	s_setprio 1
	s_barrier
	v_mfma_f32_16x16x32_bf16 v[94:97], v[150:153], v[192:195], v[94:97]
	v_mfma_f32_16x16x32_bf16 v[94:97], v[154:157], v[196:199], v[94:97]
	v_mfma_f32_16x16x32_bf16 v[90:93], v[150:153], v[200:203], v[90:93]
	v_mfma_f32_16x16x32_bf16 v[90:93], v[154:157], v[204:207], v[90:93]
	v_mfma_f32_16x16x32_bf16 v[86:89], v[150:153], v[208:211], v[86:89]
	v_mfma_f32_16x16x32_bf16 v[86:89], v[154:157], v[212:215], v[86:89]
	v_mfma_f32_16x16x32_bf16 v[82:85], v[150:153], v[216:219], v[82:85]
	v_mfma_f32_16x16x32_bf16 v[82:85], v[154:157], v[220:223], v[82:85]
	v_mfma_f32_16x16x32_bf16 v[54:57], v[158:161], v[216:219], v[54:57]
	v_mfma_f32_16x16x32_bf16 v[54:57], v[162:165], v[220:223], v[54:57]
	v_mfma_f32_16x16x32_bf16 v[62:65], v[158:161], v[208:211], v[62:65]
	v_mfma_f32_16x16x32_bf16 v[62:65], v[162:165], v[212:215], v[62:65]
	v_mfma_f32_16x16x32_bf16 v[74:77], v[158:161], v[200:203], v[74:77]
	v_mfma_f32_16x16x32_bf16 v[74:77], v[162:165], v[204:207], v[74:77]
	v_mfma_f32_16x16x32_bf16 v[78:81], v[158:161], v[192:195], v[78:81]
	v_mfma_f32_16x16x32_bf16 v[78:81], v[162:165], v[196:199], v[78:81]
	v_mfma_f32_16x16x32_bf16 v[30:33], v[166:169], v[192:195], v[30:33]
	v_mfma_f32_16x16x32_bf16 v[30:33], v[172:175], v[196:199], v[30:33]
	v_mfma_f32_16x16x32_bf16 v[26:29], v[166:169], v[200:203], v[26:29]
	v_mfma_f32_16x16x32_bf16 v[26:29], v[172:175], v[204:207], v[26:29]
	v_mfma_f32_16x16x32_bf16 v[22:25], v[166:169], v[208:211], v[22:25]
	v_mfma_f32_16x16x32_bf16 v[22:25], v[172:175], v[212:215], v[22:25]
	v_mfma_f32_16x16x32_bf16 v[18:21], v[166:169], v[216:219], v[18:21]
	v_mfma_f32_16x16x32_bf16 v[18:21], v[172:175], v[220:223], v[18:21]
	v_mfma_f32_16x16x32_bf16 v[2:5], v[176:179], v[216:219], v[2:5]
	v_mfma_f32_16x16x32_bf16 v[2:5], v[188:191], v[220:223], v[2:5]
	v_mfma_f32_16x16x32_bf16 v[6:9], v[176:179], v[208:211], v[6:9]
	v_mfma_f32_16x16x32_bf16 v[6:9], v[188:191], v[212:215], v[6:9]
	v_mfma_f32_16x16x32_bf16 v[10:13], v[176:179], v[200:203], v[10:13]
	v_mfma_f32_16x16x32_bf16 v[10:13], v[188:191], v[204:207], v[10:13]
	v_mfma_f32_16x16x32_bf16 v[14:17], v[176:179], v[192:195], v[14:17]
	v_mfma_f32_16x16x32_bf16 v[14:17], v[188:191], v[196:199], v[14:17]
	s_barrier
	s_setprio 0
	s_add_i32 s82, s82, 2
	s_add_u32 s74, s74, 0x100
	s_addc_u32 s75, s75, 0
	s_add_u32 s80, s80, 0x100
	s_addc_u32 s81, s81, 0
	s_cmp_gt_u32 s82, 29
	s_cbranch_scc0 .LBB0_596
	s_branch .Lpeel_596_x
.LBB0_596:
	s_add_u32 s0, s74, 0xfff80080
	s_addc_u32 s1, s75, -1
	s_add_i32 s83, 0, 0x10000
	s_cmp_eq_u32 s82, 28
	s_cselect_b32 s79, s40, s1
	s_cselect_b32 s78, s41, s0
	s_cselect_b32 s77, s65, s81
	s_cselect_b32 s76, s73, s80
	s_add_i32 s84, 0, 0x14000
	ds_read_b128 v[150:153], v180
	ds_read_b128 v[154:157], v180 offset:1024
	ds_read_b128 v[158:161], v180 offset:2048
	ds_read_b128 v[162:165], v180 offset:3072
	ds_read_b128 v[166:169], v180 offset:16384
	ds_read_b128 v[172:175], v180 offset:17408
	ds_read_b128 v[176:179], v180 offset:18432
	ds_read_b128 v[188:191], v180 offset:19456
	s_add_i32 m0, s35, 0xc000
	ds_read_b128 v[192:195], v148
	ds_read_b128 v[196:199], v148 offset:1024
	ds_read_b128 v[200:203], v148 offset:2048
	ds_read_b128 v[204:207], v148 offset:3072
	ds_read_b128 v[208:211], v148 offset:4096
	ds_read_b128 v[212:215], v148 offset:5120
	ds_read_b128 v[216:219], v148 offset:6144
	ds_read_b128 v[220:223], v148 offset:7168
	global_load_lds_dwordx4 v140, s[74:75]
	s_add_i32 m0, s35, 0xe000
	s_nop 0
	global_load_lds_dwordx4 v142, s[74:75]
	s_waitcnt vmcnt(8)
	s_waitcnt lgkmcnt(0)
	.p2align 3
	s_setprio 1
	s_barrier
; #define PG8_STAGE(bufoff, gbase, voff) do { _Pragma("unroll") for (int _i = 0; _i < 2; ++_i) \
;         __builtin_amdgcn_global_load_lds((const unsigned*)((const char*)(gbase) + (voff)[_i]), (PG8_LAS unsigned*)(lds + (bufoff) + ldsw + _i * 8192), 16, 0, 0); } while (0)
; #define PG8_LDA(dst, b, h) do { _Pragma("unroll") for (int m = 0; m < 4; ++m) _Pragma("unroll") for (int k = 0; k < 2; ++k) dst[m][k] = *(const PG8_LAS bf16x8*)(lds + PG8_SA(b, h) + aoff + m * 2048 + k * 1024); } while (0)
; #define PG8_LDB(dst, b, h) do { _Pragma("unroll") for (int n = 0; n < 2; ++n) _Pragma("unroll") for (int k = 0; k < 2; ++k) dst[n][k] = *(const PG8_LAS bf16x8*)(lds + PG8_SB(b, h) + boff + n * 2048 + k * 1024); } while (0)
; #define PG8_WAIT_V(n) asm volatile("s_waitcnt vmcnt(" #n ")" ::: "memory")
; #define PG8_WAIT_L(n) asm volatile("s_waitcnt lgkmcnt(" #n ")" ::: "memory")
; #define PG8_WAIT_V_SEL(sel) asm volatile("s_cmp_eq_u32 %0, 0\n\ts_cbranch_scc1 .Lw8_%=\n\ts_waitcnt vmcnt(22)\n\ts_branch .Lwd_%=\n.Lw8_%=:\n\ts_waitcnt vmcnt(8)\n.Lwd_%=:" :: "s"(sel) : "memory", "scc")
; #define PG8_BAR __builtin_amdgcn_s_barrier()
; #define PG8_SCHED __builtin_amdgcn_sched_barrier(0)
;     ...
;             PG8_WAIT_L(0); PG8_BAR; PG8_MMA(0, 0, At, B0); PG8_MMA(0, 1, At, B1); PG8_BAR; PG8_SCHED;
;             PG8_LDA(At, 0, 1); PG8_STAGE(PG8_SB(0, 0), b2, voffB); PG8_STAGE(PG8_SB(0, 1), b2 + hstep, voffB); PG8_STAGE(PG8_SA(0, 0), a2, voffA);
;             PG8_WAIT_V_SEL(relax);
;             PG8_WAIT_L(0); PG8_BAR; PG8_MMA(1, 0, At, B0); PG8_MMA(1, 1, At, B1); PG8_BAR; PG8_SCHED;
;             PG8_LDB(B0, 1, 0); PG8_LDB(B1, 1, 1); PG8_SCHED; PG8_LDA(At, 1, 0); PG8_STAGE(PG8_SA(0, 1), a2 + hstep, voffA);
;             PG8_WAIT_V(8); PG8_WAIT_L(0); PG8_BAR; PG8_MMA(0, 0, At, B0); PG8_MMA(0, 1, At, B1); PG8_BAR; PG8_SCHED;
	v_mfma_f32_16x16x32_bf16 v[126:129], v[150:153], v[192:195], v[126:129]
	v_mfma_f32_16x16x32_bf16 v[126:129], v[154:157], v[196:199], v[126:129]
	v_mfma_f32_16x16x32_bf16 v[122:125], v[150:153], v[200:203], v[122:125]
	v_mfma_f32_16x16x32_bf16 v[122:125], v[154:157], v[204:207], v[122:125]
	v_mfma_f32_16x16x32_bf16 v[118:121], v[150:153], v[208:211], v[118:121]
	v_mfma_f32_16x16x32_bf16 v[118:121], v[154:157], v[212:215], v[118:121]
	v_mfma_f32_16x16x32_bf16 v[114:117], v[150:153], v[216:219], v[114:117]
	v_mfma_f32_16x16x32_bf16 v[114:117], v[154:157], v[220:223], v[114:117]
	v_mfma_f32_16x16x32_bf16 v[98:101], v[158:161], v[216:219], v[98:101]
	v_mfma_f32_16x16x32_bf16 v[98:101], v[162:165], v[220:223], v[98:101]
	v_mfma_f32_16x16x32_bf16 v[102:105], v[158:161], v[208:211], v[102:105]
	v_mfma_f32_16x16x32_bf16 v[102:105], v[162:165], v[212:215], v[102:105]
	v_mfma_f32_16x16x32_bf16 v[106:109], v[158:161], v[200:203], v[106:109]
	v_mfma_f32_16x16x32_bf16 v[106:109], v[162:165], v[204:207], v[106:109]
	v_mfma_f32_16x16x32_bf16 v[110:113], v[158:161], v[192:195], v[110:113]
	v_mfma_f32_16x16x32_bf16 v[110:113], v[162:165], v[196:199], v[110:113]
	v_mfma_f32_16x16x32_bf16 v[70:73], v[166:169], v[192:195], v[70:73]
	v_mfma_f32_16x16x32_bf16 v[70:73], v[172:175], v[196:199], v[70:73]
	v_mfma_f32_16x16x32_bf16 v[66:69], v[166:169], v[200:203], v[66:69]
	v_mfma_f32_16x16x32_bf16 v[66:69], v[172:175], v[204:207], v[66:69]
	v_mfma_f32_16x16x32_bf16 v[58:61], v[166:169], v[208:211], v[58:61]
	v_mfma_f32_16x16x32_bf16 v[58:61], v[172:175], v[212:215], v[58:61]
	v_mfma_f32_16x16x32_bf16 v[46:49], v[166:169], v[216:219], v[46:49]
	v_mfma_f32_16x16x32_bf16 v[46:49], v[172:175], v[220:223], v[46:49]
	v_mfma_f32_16x16x32_bf16 v[34:37], v[176:179], v[216:219], v[34:37]
	v_mfma_f32_16x16x32_bf16 v[34:37], v[188:191], v[220:223], v[34:37]
	v_mfma_f32_16x16x32_bf16 v[38:41], v[176:179], v[208:211], v[38:41]
	v_mfma_f32_16x16x32_bf16 v[38:41], v[188:191], v[212:215], v[38:41]
	v_mfma_f32_16x16x32_bf16 v[42:45], v[176:179], v[200:203], v[42:45]
	v_mfma_f32_16x16x32_bf16 v[42:45], v[188:191], v[204:207], v[42:45]
	v_mfma_f32_16x16x32_bf16 v[50:53], v[176:179], v[192:195], v[50:53]
	v_mfma_f32_16x16x32_bf16 v[50:53], v[188:191], v[196:199], v[50:53]
	s_barrier
	s_setprio 0
	s_add_i32 s0, s83, s20
	s_mov_b32 m0, s0
	ds_read_b128 v[192:195], v148 offset:16384
	ds_read_b128 v[196:199], v148 offset:17408
	ds_read_b128 v[200:203], v148 offset:18432
	ds_read_b128 v[204:207], v148 offset:19456
	ds_read_b128 v[208:211], v148 offset:20480
	ds_read_b128 v[212:215], v148 offset:21504
	ds_read_b128 v[216:219], v148 offset:22528
	ds_read_b128 v[220:223], v148 offset:23552
	global_load_lds_dwordx4 v132, s[76:77]
	s_add_i32 m0, s0, 0x2000
	s_add_u32 s0, s76, 0x80000
	s_addc_u32 s1, s77, 0
	s_add_i32 s83, s84, s20
	global_load_lds_dwordx4 v136, s[76:77]
	s_mov_b32 m0, s83
	s_nop 0
	global_load_lds_dwordx4 v132, s[0:1]
	s_add_i32 m0, s83, 0x2000
	s_nop 0
	global_load_lds_dwordx4 v136, s[0:1]
	s_mov_b32 m0, s35
	s_nop 0
	global_load_lds_dwordx4 v130, s[78:79]
	s_mov_b32 m0, s37
	s_nop 0
	global_load_lds_dwordx4 v134, s[78:79]
	s_waitcnt vmcnt(8)
	s_waitcnt lgkmcnt(0)
	.p2align 3
	s_setprio 1
	s_barrier
	v_mfma_f32_16x16x32_bf16 v[94:97], v[150:153], v[192:195], v[94:97]
	v_mfma_f32_16x16x32_bf16 v[94:97], v[154:157], v[196:199], v[94:97]
	v_mfma_f32_16x16x32_bf16 v[90:93], v[150:153], v[200:203], v[90:93]
	v_mfma_f32_16x16x32_bf16 v[90:93], v[154:157], v[204:207], v[90:93]
	v_mfma_f32_16x16x32_bf16 v[86:89], v[150:153], v[208:211], v[86:89]
	v_mfma_f32_16x16x32_bf16 v[86:89], v[154:157], v[212:215], v[86:89]
	v_mfma_f32_16x16x32_bf16 v[82:85], v[150:153], v[216:219], v[82:85]
	v_mfma_f32_16x16x32_bf16 v[82:85], v[154:157], v[220:223], v[82:85]
	v_mfma_f32_16x16x32_bf16 v[54:57], v[158:161], v[216:219], v[54:57]
	v_mfma_f32_16x16x32_bf16 v[54:57], v[162:165], v[220:223], v[54:57]
	v_mfma_f32_16x16x32_bf16 v[62:65], v[158:161], v[208:211], v[62:65]
	v_mfma_f32_16x16x32_bf16 v[62:65], v[162:165], v[212:215], v[62:65]
	v_mfma_f32_16x16x32_bf16 v[74:77], v[158:161], v[200:203], v[74:77]
	v_mfma_f32_16x16x32_bf16 v[74:77], v[162:165], v[204:207], v[74:77]
	v_mfma_f32_16x16x32_bf16 v[78:81], v[158:161], v[192:195], v[78:81]
	v_mfma_f32_16x16x32_bf16 v[78:81], v[162:165], v[196:199], v[78:81]
	v_mfma_f32_16x16x32_bf16 v[30:33], v[166:169], v[192:195], v[30:33]
	v_mfma_f32_16x16x32_bf16 v[30:33], v[172:175], v[196:199], v[30:33]
	v_mfma_f32_16x16x32_bf16 v[26:29], v[166:169], v[200:203], v[26:29]
	v_mfma_f32_16x16x32_bf16 v[26:29], v[172:175], v[204:207], v[26:29]
	v_mfma_f32_16x16x32_bf16 v[22:25], v[166:169], v[208:211], v[22:25]
	v_mfma_f32_16x16x32_bf16 v[22:25], v[172:175], v[212:215], v[22:25]
	v_mfma_f32_16x16x32_bf16 v[18:21], v[166:169], v[216:219], v[18:21]
	v_mfma_f32_16x16x32_bf16 v[18:21], v[172:175], v[220:223], v[18:21]
	v_mfma_f32_16x16x32_bf16 v[2:5], v[176:179], v[216:219], v[2:5]
	v_mfma_f32_16x16x32_bf16 v[2:5], v[188:191], v[220:223], v[2:5]
	v_mfma_f32_16x16x32_bf16 v[6:9], v[176:179], v[208:211], v[6:9]
	v_mfma_f32_16x16x32_bf16 v[6:9], v[188:191], v[212:215], v[6:9]
	v_mfma_f32_16x16x32_bf16 v[10:13], v[176:179], v[200:203], v[10:13]
	v_mfma_f32_16x16x32_bf16 v[10:13], v[188:191], v[204:207], v[10:13]
	v_mfma_f32_16x16x32_bf16 v[14:17], v[176:179], v[192:195], v[14:17]
	v_mfma_f32_16x16x32_bf16 v[14:17], v[188:191], v[196:199], v[14:17]
	s_barrier
; #define PG8_STAGE(bufoff, gbase, voff) do { _Pragma("unroll") for (int _i = 0; _i < 2; ++_i) \
;         __builtin_amdgcn_global_load_lds((const unsigned*)((const char*)(gbase) + (voff)[_i]), (PG8_LAS unsigned*)(lds + (bufoff) + ldsw + _i * 8192), 16, 0, 0); } while (0)
; #define PG8_LDA(dst, b, h) do { _Pragma("unroll") for (int m = 0; m < 4; ++m) _Pragma("unroll") for (int k = 0; k < 2; ++k) dst[m][k] = *(const PG8_LAS bf16x8*)(lds + PG8_SA(b, h) + aoff + m * 2048 + k * 1024); } while (0)
; #define PG8_LDB(dst, b, h) do { _Pragma("unroll") for (int n = 0; n < 2; ++n) _Pragma("unroll") for (int k = 0; k < 2; ++k) dst[n][k] = *(const PG8_LAS bf16x8*)(lds + PG8_SB(b, h) + boff + n * 2048 + k * 1024); } while (0)
; #define PG8_WAIT_V(n) asm volatile("s_waitcnt vmcnt(" #n ")" ::: "memory")
; #define PG8_WAIT_L(n) asm volatile("s_waitcnt lgkmcnt(" #n ")" ::: "memory")
; #define PG8_BAR __builtin_amdgcn_s_barrier()
; #define PG8_SCHED __builtin_amdgcn_sched_barrier(0)
;     ...
;             PG8_WAIT_L(0); PG8_BAR; PG8_MMA(1, 0, At, B0); PG8_MMA(1, 1, At, B1); PG8_BAR; PG8_SCHED;
;             PG8_LDB(B0, 1, 0); PG8_LDB(B1, 1, 1); PG8_SCHED; PG8_LDA(At, 1, 0); PG8_STAGE(PG8_SA(0, 1), a2 + hstep, voffA);
;             PG8_WAIT_V(8); PG8_WAIT_L(0); PG8_BAR; PG8_MMA(0, 0, At, B0); PG8_MMA(0, 1, At, B1); PG8_BAR; PG8_SCHED;
;             PG8_LDA(At, 1, 1); PG8_STAGE(PG8_SB(1, 0), b3, voffB); PG8_STAGE(PG8_SB(1, 1), b3 + hstep, voffB); PG8_STAGE(PG8_SA(1, 0), a3, voffA);
;             PG8_WAIT_V(8); PG8_WAIT_L(0); PG8_BAR; PG8_MMA(1, 0, At, B0); PG8_MMA(1, 1, At, B1); PG8_BAR; PG8_SCHED;
	s_setprio 0
	s_add_i32 s83, 0, 0x18000
	s_add_i32 s84, 0, 0x1c000
	ds_read_b128 v[150:153], v180 offset:32768
	ds_read_b128 v[154:157], v180 offset:33792
	ds_read_b128 v[158:161], v180 offset:34816
	ds_read_b128 v[162:165], v180 offset:35840
	ds_read_b128 v[166:169], v180 offset:49152
	ds_read_b128 v[172:175], v180 offset:50176
	ds_read_b128 v[176:179], v180 offset:51200
	ds_read_b128 v[188:191], v180 offset:52224
	s_add_u32 s0, s78, 0x80000
	s_addc_u32 s1, s79, 0
	s_mov_b32 m0, s43
	ds_read_b128 v[192:195], v148 offset:32768
	ds_read_b128 v[196:199], v148 offset:33792
	ds_read_b128 v[200:203], v148 offset:34816
	ds_read_b128 v[204:207], v148 offset:35840
	ds_read_b128 v[208:211], v148 offset:36864
	ds_read_b128 v[212:215], v148 offset:37888
	ds_read_b128 v[216:219], v148 offset:38912
	ds_read_b128 v[220:223], v148 offset:39936
	global_load_lds_dwordx4 v130, s[0:1]
	s_mov_b32 m0, s44
	s_nop 0
	global_load_lds_dwordx4 v134, s[0:1]
	s_waitcnt vmcnt(8)
	s_waitcnt lgkmcnt(0)
	.p2align 3
	s_setprio 1
	s_barrier
	v_mfma_f32_16x16x32_bf16 v[126:129], v[150:153], v[192:195], v[126:129]
	v_mfma_f32_16x16x32_bf16 v[126:129], v[154:157], v[196:199], v[126:129]
	v_mfma_f32_16x16x32_bf16 v[122:125], v[150:153], v[200:203], v[122:125]
	v_mfma_f32_16x16x32_bf16 v[122:125], v[154:157], v[204:207], v[122:125]
	v_mfma_f32_16x16x32_bf16 v[118:121], v[150:153], v[208:211], v[118:121]
	v_mfma_f32_16x16x32_bf16 v[118:121], v[154:157], v[212:215], v[118:121]
	v_mfma_f32_16x16x32_bf16 v[114:117], v[150:153], v[216:219], v[114:117]
	v_mfma_f32_16x16x32_bf16 v[114:117], v[154:157], v[220:223], v[114:117]
	v_mfma_f32_16x16x32_bf16 v[98:101], v[158:161], v[216:219], v[98:101]
	v_mfma_f32_16x16x32_bf16 v[98:101], v[162:165], v[220:223], v[98:101]
	v_mfma_f32_16x16x32_bf16 v[102:105], v[158:161], v[208:211], v[102:105]
	v_mfma_f32_16x16x32_bf16 v[102:105], v[162:165], v[212:215], v[102:105]
	v_mfma_f32_16x16x32_bf16 v[106:109], v[158:161], v[200:203], v[106:109]
	v_mfma_f32_16x16x32_bf16 v[106:109], v[162:165], v[204:207], v[106:109]
	v_mfma_f32_16x16x32_bf16 v[110:113], v[158:161], v[192:195], v[110:113]
	v_mfma_f32_16x16x32_bf16 v[110:113], v[162:165], v[196:199], v[110:113]
	v_mfma_f32_16x16x32_bf16 v[70:73], v[166:169], v[192:195], v[70:73]
	v_mfma_f32_16x16x32_bf16 v[70:73], v[172:175], v[196:199], v[70:73]
	v_mfma_f32_16x16x32_bf16 v[66:69], v[166:169], v[200:203], v[66:69]
	v_mfma_f32_16x16x32_bf16 v[66:69], v[172:175], v[204:207], v[66:69]
	v_mfma_f32_16x16x32_bf16 v[58:61], v[166:169], v[208:211], v[58:61]
	v_mfma_f32_16x16x32_bf16 v[58:61], v[172:175], v[212:215], v[58:61]
	v_mfma_f32_16x16x32_bf16 v[46:49], v[166:169], v[216:219], v[46:49]
	v_mfma_f32_16x16x32_bf16 v[46:49], v[172:175], v[220:223], v[46:49]
	v_mfma_f32_16x16x32_bf16 v[34:37], v[176:179], v[216:219], v[34:37]
	v_mfma_f32_16x16x32_bf16 v[34:37], v[188:191], v[220:223], v[34:37]
	v_mfma_f32_16x16x32_bf16 v[38:41], v[176:179], v[208:211], v[38:41]
	v_mfma_f32_16x16x32_bf16 v[38:41], v[188:191], v[212:215], v[38:41]
	v_mfma_f32_16x16x32_bf16 v[42:45], v[176:179], v[200:203], v[42:45]
	v_mfma_f32_16x16x32_bf16 v[42:45], v[188:191], v[204:207], v[42:45]
	v_mfma_f32_16x16x32_bf16 v[50:53], v[176:179], v[192:195], v[50:53]
	v_mfma_f32_16x16x32_bf16 v[50:53], v[188:191], v[196:199], v[50:53]
	s_barrier
	s_setprio 0
	s_add_i32 s0, s83, s20
	s_mov_b32 m0, s0
	ds_read_b128 v[192:195], v148 offset:49152
	ds_read_b128 v[196:199], v148 offset:50176
	ds_read_b128 v[200:203], v148 offset:51200
	ds_read_b128 v[204:207], v148 offset:52224
	ds_read_b128 v[208:211], v148 offset:53248
	ds_read_b128 v[212:215], v148 offset:54272
	ds_read_b128 v[216:219], v148 offset:55296
	ds_read_b128 v[220:223], v148 offset:56320
	s_add_u32 s100, s76, 0x80
	s_addc_u32 s101, s77, 0
	global_load_lds_dwordx4 v132, s[100:101]
	s_add_i32 m0, s0, 0x2000
	s_add_u32 s0, s76, 0x80080
	s_addc_u32 s1, s77, 0
	s_add_i32 s76, s84, s20
	global_load_lds_dwordx4 v136, s[100:101]
	s_mov_b32 m0, s76
	s_nop 0
	global_load_lds_dwordx4 v132, s[0:1]
	s_add_i32 m0, s76, 0x2000
	s_nop 0
	global_load_lds_dwordx4 v136, s[0:1]
	s_mov_b32 m0, s48
	s_nop 0
	s_add_u32 s100, s78, 0x80
	s_addc_u32 s101, s79, 0
	global_load_lds_dwordx4 v130, s[100:101]
	s_mov_b32 m0, s49
	s_nop 0
	global_load_lds_dwordx4 v134, s[100:101]
	s_waitcnt vmcnt(8)
	s_waitcnt lgkmcnt(0)
	.p2align 3
	s_setprio 1
	s_barrier
	v_mfma_f32_16x16x32_bf16 v[94:97], v[150:153], v[192:195], v[94:97]
	v_mfma_f32_16x16x32_bf16 v[94:97], v[154:157], v[196:199], v[94:97]
	v_mfma_f32_16x16x32_bf16 v[90:93], v[150:153], v[200:203], v[90:93]
	v_mfma_f32_16x16x32_bf16 v[90:93], v[154:157], v[204:207], v[90:93]
	v_mfma_f32_16x16x32_bf16 v[86:89], v[150:153], v[208:211], v[86:89]
	v_mfma_f32_16x16x32_bf16 v[86:89], v[154:157], v[212:215], v[86:89]
	v_mfma_f32_16x16x32_bf16 v[82:85], v[150:153], v[216:219], v[82:85]
	v_mfma_f32_16x16x32_bf16 v[82:85], v[154:157], v[220:223], v[82:85]
	v_mfma_f32_16x16x32_bf16 v[54:57], v[158:161], v[216:219], v[54:57]
	v_mfma_f32_16x16x32_bf16 v[54:57], v[162:165], v[220:223], v[54:57]
	v_mfma_f32_16x16x32_bf16 v[62:65], v[158:161], v[208:211], v[62:65]
	v_mfma_f32_16x16x32_bf16 v[62:65], v[162:165], v[212:215], v[62:65]
	v_mfma_f32_16x16x32_bf16 v[74:77], v[158:161], v[200:203], v[74:77]
	v_mfma_f32_16x16x32_bf16 v[74:77], v[162:165], v[204:207], v[74:77]
	v_mfma_f32_16x16x32_bf16 v[78:81], v[158:161], v[192:195], v[78:81]
	v_mfma_f32_16x16x32_bf16 v[78:81], v[162:165], v[196:199], v[78:81]
	v_mfma_f32_16x16x32_bf16 v[30:33], v[166:169], v[192:195], v[30:33]
	v_mfma_f32_16x16x32_bf16 v[30:33], v[172:175], v[196:199], v[30:33]
	v_mfma_f32_16x16x32_bf16 v[26:29], v[166:169], v[200:203], v[26:29]
	v_mfma_f32_16x16x32_bf16 v[26:29], v[172:175], v[204:207], v[26:29]
	v_mfma_f32_16x16x32_bf16 v[22:25], v[166:169], v[208:211], v[22:25]
	v_mfma_f32_16x16x32_bf16 v[22:25], v[172:175], v[212:215], v[22:25]
	v_mfma_f32_16x16x32_bf16 v[18:21], v[166:169], v[216:219], v[18:21]
	v_mfma_f32_16x16x32_bf16 v[18:21], v[172:175], v[220:223], v[18:21]
	v_mfma_f32_16x16x32_bf16 v[2:5], v[176:179], v[216:219], v[2:5]
	v_mfma_f32_16x16x32_bf16 v[2:5], v[188:191], v[220:223], v[2:5]
	v_mfma_f32_16x16x32_bf16 v[6:9], v[176:179], v[208:211], v[6:9]
	v_mfma_f32_16x16x32_bf16 v[6:9], v[188:191], v[212:215], v[6:9]
	v_mfma_f32_16x16x32_bf16 v[10:13], v[176:179], v[200:203], v[10:13]
	v_mfma_f32_16x16x32_bf16 v[10:13], v[188:191], v[204:207], v[10:13]
	v_mfma_f32_16x16x32_bf16 v[14:17], v[176:179], v[192:195], v[14:17]
	v_mfma_f32_16x16x32_bf16 v[14:17], v[188:191], v[196:199], v[14:17]
	s_barrier
	s_setprio 0
	s_add_i32 s82, s82, 2
	s_add_u32 s74, s74, 0x100
	s_addc_u32 s75, s75, 0
	s_add_u32 s80, s80, 0x100
	s_addc_u32 s81, s81, 0
	s_cmp_gt_u32 s82, 29
	s_cbranch_scc0 .LBB0_596
.Lpeel_596_x:
	s_branch .Lrlx_qkv_x
.Lrlx_qkv_0:
	s_waitcnt vmcnt(22)
	s_branch .Lrlx_qkv_0_b

; #define PG8_STAGE(bufoff, gbase, voff) do { _Pragma("unroll") for (int _i = 0; _i < 2; ++_i) \
;         __builtin_amdgcn_global_load_lds((const unsigned*)((const char*)(gbase) + (voff)[_i]), (PG8_LAS unsigned*)(lds + (bufoff) + ldsw + _i * 8192), 16, 0, 0); } while (0)
; #define PG8_LDA(dst, b, h) do { _Pragma("unroll") for (int m = 0; m < 4; ++m) _Pragma("unroll") for (int k = 0; k < 2; ++k) dst[m][k] = *(const PG8_LAS bf16x8*)(lds + PG8_SA(b, h) + aoff + m * 2048 + k * 1024); } while (0)
; #define PG8_LDB(dst, b, h) do { _Pragma("unroll") for (int n = 0; n < 2; ++n) _Pragma("unroll") for (int k = 0; k < 2; ++k) dst[n][k] = *(const PG8_LAS bf16x8*)(lds + PG8_SB(b, h) + boff + n * 2048 + k * 1024); } while (0)
; #define PG8_WAIT_L(n) asm volatile("s_waitcnt lgkmcnt(" #n ")" ::: "memory")
; #define PG8_WAIT_V_SEL(sel) asm volatile("s_cmp_eq_u32 %0, 0\n\ts_cbranch_scc1 .Lw8_%=\n\ts_waitcnt vmcnt(22)\n\ts_branch .Lwd_%=\n.Lw8_%=:\n\ts_waitcnt vmcnt(8)\n.Lwd_%=:" :: "s"(sel) : "memory", "scc")
;     ...
;         const char* nA = has_next ? (const char*)g.A + (size_t)nxt.pm * tstep : cA; const char* nB = has_next ? (const char*)g.Bt + (size_t)nxt.pn * tstep : cB;
;         for (int t = 0; t < nt * KREP; t += 2) {
;             const bool last = (t == nt * KREP - 2);
;             const int t1w = KREP > 1 ? ((t + 1) & (nt - 1)) : t + 1, t2w = KREP > 1 ? ((t + 2) & (nt - 1)) : t + 2;
;             const char* a1 = cA + (size_t)t1w * kstep;
;             const char* a2 = last ? nA : cA + (size_t)t2w * kstep; const char* b2 = last ? nB : cB + (size_t)t2w * kstep;
;             const char* a3 = a2 + kstep; const char* b3 = b2 + kstep;
;             if (last && has_next) S.a_ready(nxt);
;             const int relax = __builtin_amdgcn_readfirstlane((MK_RELAXW && t == 0 && ui > 0) ? 1 : 0);
;             if constexpr (SP2) {
;             PG8_LDB(B0, 0, 0); PG8_LDB(B1, 0, 1); PG8_SCHED; PG8_LDA(At, 0, 0); PG8_STAGE(PG8_SA(1, 1), a1 + hstep, voffA);
;             PG8_WAIT_V_SEL(relax);
;             PG8_WAIT_L(0); PG8_BAR; PG8_MMA(0, 0, At, B0); PG8_MMA(0, 1, At, B1); PG8_BAR; PG8_SCHED;
;             PG8_LDA(At, 0, 1); PG8_STAGE(PG8_SB(0, 0), b2, voffB); PG8_STAGE(PG8_SB(0, 1), b2 + hstep, voffB); PG8_STAGE(PG8_SA(0, 0), a2, voffA);
;             PG8_WAIT_V_SEL(relax);
;             PG8_WAIT_L(0); PG8_BAR; PG8_MMA(1, 0, At, B0); PG8_MMA(1, 1, At, B1); PG8_BAR; PG8_SCHED;
.LBB0_1169:
	s_ashr_i32 s69, s68, 31
	s_lshl_b64 s[0:1], s[68:69], 20
	s_add_u32 s70, s35, s0
	s_addc_u32 s71, s37, s1
	s_and_b64 s[0:1], s[4:5], exec
	s_cselect_b32 s40, s71, s79
	s_cselect_b32 s41, s70, s78
	s_ashr_i32 s67, s66, 31
	s_lshl_b64 s[0:1], s[66:67], 20
	s_add_u32 s72, s43, s0
	s_addc_u32 s73, s44, s1
	s_and_b64 s[0:1], s[4:5], exec
	s_cselect_b32 s67, s73, s81
	s_cselect_b32 s69, s72, s80
	s_add_u32 s78, s78, 0x80080
	s_addc_u32 s79, s79, 0
	s_add_u32 s75, s80, 0x100
	s_addc_u32 s77, s81, 0
	s_mov_b32 s84, -2
	s_waitcnt lgkmcnt(0)
	v_add_u32_e32 v184, 0x10000, v224
	s_add_u32 s0, s78, 0xfff80080
	s_addc_u32 s1, s79, -1
	s_add_i32 s85, 0, 0x10000
	s_cmp_eq_u32 s84, 28
	s_cselect_b32 s83, s40, s1
	s_cselect_b32 s82, s41, s0
	s_cselect_b32 s81, s67, s77
	s_cselect_b32 s80, s69, s75
	s_add_i32 s86, 0, 0x14000
	ds_read_b128 v[90:93], v184
	ds_read_b128 v[94:97], v184 offset:1024
	ds_read_b128 v[98:101], v184 offset:2048
	ds_read_b128 v[102:105], v184 offset:3072
	ds_read_b128 v[146:149], v184 offset:16384
	ds_read_b128 v[150:153], v184 offset:17408
	ds_read_b128 v[154:157], v184 offset:18432
	ds_read_b128 v[158:161], v184 offset:19456
	s_add_i32 m0, s45, 0xc000
	ds_read_b128 v[162:165], v227
	ds_read_b128 v[166:169], v227 offset:1024
	ds_read_b128 v[188:191], v227 offset:2048
	ds_read_b128 v[192:195], v227 offset:3072
	ds_read_b128 v[196:199], v227 offset:4096
	ds_read_b128 v[200:203], v227 offset:5120
	ds_read_b128 v[204:207], v227 offset:6144
	ds_read_b128 v[208:211], v227 offset:7168
	global_load_lds_dwordx4 v178, s[78:79]
	s_add_i32 m0, s45, 0xe000
	s_nop 0
	global_load_lds_dwordx4 v180, s[78:79]
	s_cmp_lg_u32 s57, 0
	s_cbranch_scc1 .Lrlx_wo_0
	s_waitcnt vmcnt(8)
.Lrlx_wo_0_b:
	s_waitcnt lgkmcnt(0)
	.p2align 3
	s_setprio 1
	s_barrier
	v_mfma_f32_16x16x32_bf16 v[142:145], v[90:93], v[162:165], 0
	v_mfma_f32_16x16x32_bf16 v[142:145], v[94:97], v[166:169], v[142:145]
	v_mfma_f32_16x16x32_bf16 v[126:129], v[90:93], v[188:191], 0
	v_mfma_f32_16x16x32_bf16 v[126:129], v[94:97], v[192:195], v[126:129]
	v_mfma_f32_16x16x32_bf16 v[110:113], v[90:93], v[196:199], 0
	v_mfma_f32_16x16x32_bf16 v[110:113], v[94:97], v[200:203], v[110:113]
	v_mfma_f32_16x16x32_bf16 v[78:81], v[90:93], v[204:207], 0
	v_mfma_f32_16x16x32_bf16 v[78:81], v[94:97], v[208:211], v[78:81]
	v_mfma_f32_16x16x32_bf16 v[74:77], v[98:101], v[204:207], 0
	v_mfma_f32_16x16x32_bf16 v[74:77], v[102:105], v[208:211], v[74:77]
	v_mfma_f32_16x16x32_bf16 v[106:109], v[98:101], v[196:199], 0
	v_mfma_f32_16x16x32_bf16 v[106:109], v[102:105], v[200:203], v[106:109]
	v_mfma_f32_16x16x32_bf16 v[122:125], v[98:101], v[188:191], 0
	v_mfma_f32_16x16x32_bf16 v[122:125], v[102:105], v[192:195], v[122:125]
	v_mfma_f32_16x16x32_bf16 v[138:141], v[98:101], v[162:165], 0
	v_mfma_f32_16x16x32_bf16 v[138:141], v[102:105], v[166:169], v[138:141]
	v_mfma_f32_16x16x32_bf16 v[134:137], v[146:149], v[162:165], 0
	v_mfma_f32_16x16x32_bf16 v[134:137], v[150:153], v[166:169], v[134:137]
	v_mfma_f32_16x16x32_bf16 v[118:121], v[146:149], v[188:191], 0
	v_mfma_f32_16x16x32_bf16 v[118:121], v[150:153], v[192:195], v[118:121]
	v_mfma_f32_16x16x32_bf16 v[86:89], v[146:149], v[196:199], 0
	v_mfma_f32_16x16x32_bf16 v[86:89], v[150:153], v[200:203], v[86:89]
	v_mfma_f32_16x16x32_bf16 v[70:73], v[146:149], v[204:207], 0
	v_mfma_f32_16x16x32_bf16 v[70:73], v[150:153], v[208:211], v[70:73]
	v_mfma_f32_16x16x32_bf16 v[66:69], v[154:157], v[204:207], 0
	v_mfma_f32_16x16x32_bf16 v[66:69], v[158:161], v[208:211], v[66:69]
	v_mfma_f32_16x16x32_bf16 v[82:85], v[154:157], v[196:199], 0
	v_mfma_f32_16x16x32_bf16 v[82:85], v[158:161], v[200:203], v[82:85]
	v_mfma_f32_16x16x32_bf16 v[114:117], v[154:157], v[188:191], 0
	v_mfma_f32_16x16x32_bf16 v[114:117], v[158:161], v[192:195], v[114:117]
	v_mfma_f32_16x16x32_bf16 v[130:133], v[154:157], v[162:165], 0
	v_mfma_f32_16x16x32_bf16 v[130:133], v[158:161], v[166:169], v[130:133]
	s_barrier
	s_setprio 0
	s_add_i32 s0, s85, s33
	s_mov_b32 m0, s0
	ds_read_b128 v[162:165], v227 offset:16384
	ds_read_b128 v[166:169], v227 offset:17408
	ds_read_b128 v[188:191], v227 offset:18432
	ds_read_b128 v[192:195], v227 offset:19456
	ds_read_b128 v[196:199], v227 offset:20480
	ds_read_b128 v[200:203], v227 offset:21504
	ds_read_b128 v[204:207], v227 offset:22528
	ds_read_b128 v[208:211], v227 offset:23552
	global_load_lds_dwordx4 v182, s[80:81]
	s_add_i32 m0, s0, 0x2000
	s_add_u32 s0, s80, 0x80000
	s_addc_u32 s1, s81, 0
	s_add_i32 s85, s86, s33
	global_load_lds_dwordx4 v176, s[80:81]
	s_mov_b32 m0, s85
	s_nop 0
	global_load_lds_dwordx4 v182, s[0:1]
	s_add_i32 m0, s85, 0x2000
	s_nop 0
	global_load_lds_dwordx4 v176, s[0:1]
	s_mov_b32 m0, s45
	s_nop 0
	global_load_lds_dwordx4 v172, s[82:83]
	s_mov_b32 m0, s46
	s_nop 0
	global_load_lds_dwordx4 v174, s[82:83]
	s_cmp_lg_u32 s57, 0
	s_cbranch_scc1 .Lrlx_wo_1
	s_waitcnt vmcnt(8)
; #define PG8_STAGE(bufoff, gbase, voff) do { _Pragma("unroll") for (int _i = 0; _i < 2; ++_i) \
;         __builtin_amdgcn_global_load_lds((const unsigned*)((const char*)(gbase) + (voff)[_i]), (PG8_LAS unsigned*)(lds + (bufoff) + ldsw + _i * 8192), 16, 0, 0); } while (0)
; #define PG8_LDA(dst, b, h) do { _Pragma("unroll") for (int m = 0; m < 4; ++m) _Pragma("unroll") for (int k = 0; k < 2; ++k) dst[m][k] = *(const PG8_LAS bf16x8*)(lds + PG8_SA(b, h) + aoff + m * 2048 + k * 1024); } while (0)
; #define PG8_LDB(dst, b, h) do { _Pragma("unroll") for (int n = 0; n < 2; ++n) _Pragma("unroll") for (int k = 0; k < 2; ++k) dst[n][k] = *(const PG8_LAS bf16x8*)(lds + PG8_SB(b, h) + boff + n * 2048 + k * 1024); } while (0)
; #define PG8_WAIT_V(n) asm volatile("s_waitcnt vmcnt(" #n ")" ::: "memory")
; #define PG8_WAIT_L(n) asm volatile("s_waitcnt lgkmcnt(" #n ")" ::: "memory")
; #define PG8_WAIT_V_SEL(sel) asm volatile("s_cmp_eq_u32 %0, 0\n\ts_cbranch_scc1 .Lw8_%=\n\ts_waitcnt vmcnt(22)\n\ts_branch .Lwd_%=\n.Lw8_%=:\n\ts_waitcnt vmcnt(8)\n.Lwd_%=:" :: "s"(sel) : "memory", "scc")
; #define PG8_BAR __builtin_amdgcn_s_barrier()
; #define PG8_SCHED __builtin_amdgcn_sched_barrier(0)
;     ...
;             PG8_WAIT_L(0); PG8_BAR; PG8_MMA(0, 0, At, B0); PG8_MMA(0, 1, At, B1); PG8_BAR; PG8_SCHED;
;             PG8_LDA(At, 0, 1); PG8_STAGE(PG8_SB(0, 0), b2, voffB); PG8_STAGE(PG8_SB(0, 1), b2 + hstep, voffB); PG8_STAGE(PG8_SA(0, 0), a2, voffA);
;             PG8_WAIT_V_SEL(relax);
;             PG8_WAIT_L(0); PG8_BAR; PG8_MMA(1, 0, At, B0); PG8_MMA(1, 1, At, B1); PG8_BAR; PG8_SCHED;
;             PG8_LDB(B0, 1, 0); PG8_LDB(B1, 1, 1); PG8_SCHED; PG8_LDA(At, 1, 0); PG8_STAGE(PG8_SA(0, 1), a2 + hstep, voffA);
;             PG8_WAIT_V(8); PG8_WAIT_L(0); PG8_BAR; PG8_MMA(0, 0, At, B0); PG8_MMA(0, 1, At, B1); PG8_BAR; PG8_SCHED;
.Lrlx_wo_1_b:
	s_waitcnt lgkmcnt(0)
	.p2align 3
	s_setprio 1
	s_barrier
	v_mfma_f32_16x16x32_bf16 v[62:65], v[90:93], v[162:165], 0
	v_mfma_f32_16x16x32_bf16 v[62:65], v[94:97], v[166:169], v[62:65]
	v_mfma_f32_16x16x32_bf16 v[46:49], v[90:93], v[188:191], 0
	v_mfma_f32_16x16x32_bf16 v[46:49], v[94:97], v[192:195], v[46:49]
	v_mfma_f32_16x16x32_bf16 v[30:33], v[90:93], v[196:199], 0
	v_mfma_f32_16x16x32_bf16 v[30:33], v[94:97], v[200:203], v[30:33]
	v_mfma_f32_16x16x32_bf16 v[14:17], v[90:93], v[204:207], 0
	v_mfma_f32_16x16x32_bf16 v[14:17], v[94:97], v[208:211], v[14:17]
	v_mfma_f32_16x16x32_bf16 v[10:13], v[98:101], v[204:207], 0
	v_mfma_f32_16x16x32_bf16 v[10:13], v[102:105], v[208:211], v[10:13]
	v_mfma_f32_16x16x32_bf16 v[26:29], v[98:101], v[196:199], 0
	v_mfma_f32_16x16x32_bf16 v[26:29], v[102:105], v[200:203], v[26:29]
	v_mfma_f32_16x16x32_bf16 v[42:45], v[98:101], v[188:191], 0
	v_mfma_f32_16x16x32_bf16 v[42:45], v[102:105], v[192:195], v[42:45]
	v_mfma_f32_16x16x32_bf16 v[58:61], v[98:101], v[162:165], 0
	v_mfma_f32_16x16x32_bf16 v[58:61], v[102:105], v[166:169], v[58:61]
	v_mfma_f32_16x16x32_bf16 v[54:57], v[146:149], v[162:165], 0
	v_mfma_f32_16x16x32_bf16 v[54:57], v[150:153], v[166:169], v[54:57]
	v_mfma_f32_16x16x32_bf16 v[38:41], v[146:149], v[188:191], 0
	v_mfma_f32_16x16x32_bf16 v[38:41], v[150:153], v[192:195], v[38:41]
	v_mfma_f32_16x16x32_bf16 v[22:25], v[146:149], v[196:199], 0
	v_mfma_f32_16x16x32_bf16 v[22:25], v[150:153], v[200:203], v[22:25]
	v_mfma_f32_16x16x32_bf16 v[6:9], v[146:149], v[204:207], 0
	v_mfma_f32_16x16x32_bf16 v[6:9], v[150:153], v[208:211], v[6:9]
	v_mfma_f32_16x16x32_bf16 v[2:5], v[154:157], v[204:207], 0
	v_mfma_f32_16x16x32_bf16 v[2:5], v[158:161], v[208:211], v[2:5]
	v_mfma_f32_16x16x32_bf16 v[18:21], v[154:157], v[196:199], 0
	v_mfma_f32_16x16x32_bf16 v[18:21], v[158:161], v[200:203], v[18:21]
	v_mfma_f32_16x16x32_bf16 v[34:37], v[154:157], v[188:191], 0
	v_mfma_f32_16x16x32_bf16 v[34:37], v[158:161], v[192:195], v[34:37]
	v_mfma_f32_16x16x32_bf16 v[50:53], v[154:157], v[162:165], 0
	v_mfma_f32_16x16x32_bf16 v[50:53], v[158:161], v[166:169], v[50:53]
	s_barrier
	s_setprio 0
	s_add_i32 s85, 0, 0x18000
	s_add_i32 s86, 0, 0x1c000
	ds_read_b128 v[90:93], v184 offset:32768
	ds_read_b128 v[94:97], v184 offset:33792
	ds_read_b128 v[98:101], v184 offset:34816
	ds_read_b128 v[102:105], v184 offset:35840
	ds_read_b128 v[146:149], v184 offset:49152
	ds_read_b128 v[150:153], v184 offset:50176
	ds_read_b128 v[154:157], v184 offset:51200
	ds_read_b128 v[158:161], v184 offset:52224
	s_add_u32 s0, s82, 0x80000
	s_addc_u32 s1, s83, 0
	s_mov_b32 m0, s47
	ds_read_b128 v[162:165], v227 offset:32768
	ds_read_b128 v[166:169], v227 offset:33792
	ds_read_b128 v[188:191], v227 offset:34816
	ds_read_b128 v[192:195], v227 offset:35840
	ds_read_b128 v[196:199], v227 offset:36864
	ds_read_b128 v[200:203], v227 offset:37888
	ds_read_b128 v[204:207], v227 offset:38912
	ds_read_b128 v[208:211], v227 offset:39936
	global_load_lds_dwordx4 v172, s[0:1]
	s_mov_b32 m0, s48
	s_nop 0
	global_load_lds_dwordx4 v174, s[0:1]
	s_waitcnt vmcnt(8)
	s_waitcnt lgkmcnt(0)
	.p2align 3
	s_setprio 1
	s_barrier
	v_mfma_f32_16x16x32_bf16 v[142:145], v[90:93], v[162:165], v[142:145]
	v_mfma_f32_16x16x32_bf16 v[142:145], v[94:97], v[166:169], v[142:145]
	v_mfma_f32_16x16x32_bf16 v[126:129], v[90:93], v[188:191], v[126:129]
	v_mfma_f32_16x16x32_bf16 v[126:129], v[94:97], v[192:195], v[126:129]
	v_mfma_f32_16x16x32_bf16 v[110:113], v[90:93], v[196:199], v[110:113]
	v_mfma_f32_16x16x32_bf16 v[110:113], v[94:97], v[200:203], v[110:113]
	v_mfma_f32_16x16x32_bf16 v[78:81], v[90:93], v[204:207], v[78:81]
	v_mfma_f32_16x16x32_bf16 v[78:81], v[94:97], v[208:211], v[78:81]
	v_mfma_f32_16x16x32_bf16 v[74:77], v[98:101], v[204:207], v[74:77]
	v_mfma_f32_16x16x32_bf16 v[74:77], v[102:105], v[208:211], v[74:77]
	v_mfma_f32_16x16x32_bf16 v[106:109], v[98:101], v[196:199], v[106:109]
	v_mfma_f32_16x16x32_bf16 v[106:109], v[102:105], v[200:203], v[106:109]
	v_mfma_f32_16x16x32_bf16 v[122:125], v[98:101], v[188:191], v[122:125]
	v_mfma_f32_16x16x32_bf16 v[122:125], v[102:105], v[192:195], v[122:125]
	v_mfma_f32_16x16x32_bf16 v[138:141], v[98:101], v[162:165], v[138:141]
	v_mfma_f32_16x16x32_bf16 v[138:141], v[102:105], v[166:169], v[138:141]
	v_mfma_f32_16x16x32_bf16 v[134:137], v[146:149], v[162:165], v[134:137]
	v_mfma_f32_16x16x32_bf16 v[134:137], v[150:153], v[166:169], v[134:137]
	v_mfma_f32_16x16x32_bf16 v[118:121], v[146:149], v[188:191], v[118:121]
	v_mfma_f32_16x16x32_bf16 v[118:121], v[150:153], v[192:195], v[118:121]
	v_mfma_f32_16x16x32_bf16 v[86:89], v[146:149], v[196:199], v[86:89]
	v_mfma_f32_16x16x32_bf16 v[86:89], v[150:153], v[200:203], v[86:89]
	v_mfma_f32_16x16x32_bf16 v[70:73], v[146:149], v[204:207], v[70:73]
	v_mfma_f32_16x16x32_bf16 v[70:73], v[150:153], v[208:211], v[70:73]
	v_mfma_f32_16x16x32_bf16 v[66:69], v[154:157], v[204:207], v[66:69]
	v_mfma_f32_16x16x32_bf16 v[66:69], v[158:161], v[208:211], v[66:69]
	v_mfma_f32_16x16x32_bf16 v[82:85], v[154:157], v[196:199], v[82:85]
	v_mfma_f32_16x16x32_bf16 v[82:85], v[158:161], v[200:203], v[82:85]
	v_mfma_f32_16x16x32_bf16 v[114:117], v[154:157], v[188:191], v[114:117]
	v_mfma_f32_16x16x32_bf16 v[114:117], v[158:161], v[192:195], v[114:117]
	v_mfma_f32_16x16x32_bf16 v[130:133], v[154:157], v[162:165], v[130:133]
	v_mfma_f32_16x16x32_bf16 v[130:133], v[158:161], v[166:169], v[130:133]
	s_barrier
; #define PG8_STAGE(bufoff, gbase, voff) do { _Pragma("unroll") for (int _i = 0; _i < 2; ++_i) \
;         __builtin_amdgcn_global_load_lds((const unsigned*)((const char*)(gbase) + (voff)[_i]), (PG8_LAS unsigned*)(lds + (bufoff) + ldsw + _i * 8192), 16, 0, 0); } while (0)
; #define PG8_LDA(dst, b, h) do { _Pragma("unroll") for (int m = 0; m < 4; ++m) _Pragma("unroll") for (int k = 0; k < 2; ++k) dst[m][k] = *(const PG8_LAS bf16x8*)(lds + PG8_SA(b, h) + aoff + m * 2048 + k * 1024); } while (0)
; #define PG8_WAIT_V(n) asm volatile("s_waitcnt vmcnt(" #n ")" ::: "memory")
; #define PG8_WAIT_L(n) asm volatile("s_waitcnt lgkmcnt(" #n ")" ::: "memory")
;     ...
;         for (int t = 0; t < nt * KREP; t += 2) {
;             const bool last = (t == nt * KREP - 2);
;             const int t1w = KREP > 1 ? ((t + 1) & (nt - 1)) : t + 1, t2w = KREP > 1 ? ((t + 2) & (nt - 1)) : t + 2;
;             const char* a1 = cA + (size_t)t1w * kstep;
;             const char* a2 = last ? nA : cA + (size_t)t2w * kstep; const char* b2 = last ? nB : cB + (size_t)t2w * kstep;
;             const char* a3 = a2 + kstep; const char* b3 = b2 + kstep;
;             if (last && has_next) S.a_ready(nxt);
;             const int relax = __builtin_amdgcn_readfirstlane((MK_RELAXW && t == 0 && ui > 0) ? 1 : 0);
;             if constexpr (SP2) {
;             PG8_LDB(B0, 0, 0); PG8_LDB(B1, 0, 1); PG8_SCHED; PG8_LDA(At, 0, 0); PG8_STAGE(PG8_SA(1, 1), a1 + hstep, voffA);
;             PG8_WAIT_V_SEL(relax);
;             PG8_WAIT_L(0); PG8_BAR; PG8_MMA(0, 0, At, B0); PG8_MMA(0, 1, At, B1); PG8_BAR; PG8_SCHED;
;             PG8_LDA(At, 0, 1); PG8_STAGE(PG8_SB(0, 0), b2, voffB); PG8_STAGE(PG8_SB(0, 1), b2 + hstep, voffB); PG8_STAGE(PG8_SA(0, 0), a2, voffA);
;             PG8_WAIT_V_SEL(relax);
;             PG8_WAIT_L(0); PG8_BAR; PG8_MMA(1, 0, At, B0); PG8_MMA(1, 1, At, B1); PG8_BAR; PG8_SCHED;
;             PG8_LDB(B0, 1, 0); PG8_LDB(B1, 1, 1); PG8_SCHED; PG8_LDA(At, 1, 0); PG8_STAGE(PG8_SA(0, 1), a2 + hstep, voffA);
;             PG8_WAIT_V(8); PG8_WAIT_L(0); PG8_BAR; PG8_MMA(0, 0, At, B0); PG8_MMA(0, 1, At, B1); PG8_BAR; PG8_SCHED;
;             PG8_LDA(At, 1, 1); PG8_STAGE(PG8_SB(1, 0), b3, voffB); PG8_STAGE(PG8_SB(1, 1), b3 + hstep, voffB); PG8_STAGE(PG8_SA(1, 0), a3, voffA);
;             PG8_WAIT_V(8); PG8_WAIT_L(0); PG8_BAR; PG8_MMA(1, 0, At, B0); PG8_MMA(1, 1, At, B1); PG8_BAR; PG8_SCHED;
	s_setprio 0
	s_add_i32 s0, s85, s33
	s_mov_b32 m0, s0
	ds_read_b128 v[162:165], v227 offset:49152
	ds_read_b128 v[166:169], v227 offset:50176
	ds_read_b128 v[188:191], v227 offset:51200
	ds_read_b128 v[192:195], v227 offset:52224
	ds_read_b128 v[196:199], v227 offset:53248
	ds_read_b128 v[200:203], v227 offset:54272
	ds_read_b128 v[204:207], v227 offset:55296
	ds_read_b128 v[208:211], v227 offset:56320
	s_add_u32 s100, s80, 0x80
	s_addc_u32 s101, s81, 0
	global_load_lds_dwordx4 v182, s[100:101]
	s_add_i32 m0, s0, 0x2000
	s_add_u32 s0, s80, 0x80080
	s_addc_u32 s1, s81, 0
	s_add_i32 s80, s86, s33
	global_load_lds_dwordx4 v176, s[100:101]
	s_mov_b32 m0, s80
	s_nop 0
	global_load_lds_dwordx4 v182, s[0:1]
	s_add_i32 m0, s80, 0x2000
	s_nop 0
	global_load_lds_dwordx4 v176, s[0:1]
	s_mov_b32 m0, s50
	s_nop 0
	s_add_u32 s100, s82, 0x80
	s_addc_u32 s101, s83, 0
	global_load_lds_dwordx4 v172, s[100:101]
	s_mov_b32 m0, s51
	s_nop 0
	global_load_lds_dwordx4 v174, s[100:101]
	s_waitcnt vmcnt(8)
	s_waitcnt lgkmcnt(0)
	.p2align 3
	s_setprio 1
	s_barrier
	v_mfma_f32_16x16x32_bf16 v[62:65], v[90:93], v[162:165], v[62:65]
	v_mfma_f32_16x16x32_bf16 v[62:65], v[94:97], v[166:169], v[62:65]
	v_mfma_f32_16x16x32_bf16 v[46:49], v[90:93], v[188:191], v[46:49]
	v_mfma_f32_16x16x32_bf16 v[46:49], v[94:97], v[192:195], v[46:49]
	v_mfma_f32_16x16x32_bf16 v[30:33], v[90:93], v[196:199], v[30:33]
	v_mfma_f32_16x16x32_bf16 v[30:33], v[94:97], v[200:203], v[30:33]
	v_mfma_f32_16x16x32_bf16 v[14:17], v[90:93], v[204:207], v[14:17]
	v_mfma_f32_16x16x32_bf16 v[14:17], v[94:97], v[208:211], v[14:17]
	v_mfma_f32_16x16x32_bf16 v[10:13], v[98:101], v[204:207], v[10:13]
	v_mfma_f32_16x16x32_bf16 v[10:13], v[102:105], v[208:211], v[10:13]
	v_mfma_f32_16x16x32_bf16 v[26:29], v[98:101], v[196:199], v[26:29]
	v_mfma_f32_16x16x32_bf16 v[26:29], v[102:105], v[200:203], v[26:29]
	v_mfma_f32_16x16x32_bf16 v[42:45], v[98:101], v[188:191], v[42:45]
	v_mfma_f32_16x16x32_bf16 v[42:45], v[102:105], v[192:195], v[42:45]
	v_mfma_f32_16x16x32_bf16 v[58:61], v[98:101], v[162:165], v[58:61]
	v_mfma_f32_16x16x32_bf16 v[58:61], v[102:105], v[166:169], v[58:61]
	v_mfma_f32_16x16x32_bf16 v[54:57], v[146:149], v[162:165], v[54:57]
	v_mfma_f32_16x16x32_bf16 v[54:57], v[150:153], v[166:169], v[54:57]
	v_mfma_f32_16x16x32_bf16 v[38:41], v[146:149], v[188:191], v[38:41]
	v_mfma_f32_16x16x32_bf16 v[38:41], v[150:153], v[192:195], v[38:41]
	v_mfma_f32_16x16x32_bf16 v[22:25], v[146:149], v[196:199], v[22:25]
	v_mfma_f32_16x16x32_bf16 v[22:25], v[150:153], v[200:203], v[22:25]
	v_mfma_f32_16x16x32_bf16 v[6:9], v[146:149], v[204:207], v[6:9]
	v_mfma_f32_16x16x32_bf16 v[6:9], v[150:153], v[208:211], v[6:9]
	v_mfma_f32_16x16x32_bf16 v[2:5], v[154:157], v[204:207], v[2:5]
	v_mfma_f32_16x16x32_bf16 v[2:5], v[158:161], v[208:211], v[2:5]
	v_mfma_f32_16x16x32_bf16 v[18:21], v[154:157], v[196:199], v[18:21]
	v_mfma_f32_16x16x32_bf16 v[18:21], v[158:161], v[200:203], v[18:21]
	v_mfma_f32_16x16x32_bf16 v[34:37], v[154:157], v[188:191], v[34:37]
	v_mfma_f32_16x16x32_bf16 v[34:37], v[158:161], v[192:195], v[34:37]
	v_mfma_f32_16x16x32_bf16 v[50:53], v[154:157], v[162:165], v[50:53]
	v_mfma_f32_16x16x32_bf16 v[50:53], v[158:161], v[166:169], v[50:53]
	s_barrier
	s_setprio 0
	s_add_i32 s84, s84, 2
	s_add_u32 s78, s78, 0x100
	s_addc_u32 s79, s79, 0
	s_add_u32 s75, s75, 0x100
	s_addc_u32 s77, s77, 0
	s_cmp_gt_u32 s84, 29
	s_cbranch_scc0 .LBB0_1170
	s_branch .Lpeel_1170_x
.LBB0_1170:
	s_add_u32 s0, s78, 0xfff80080
	s_addc_u32 s1, s79, -1
	s_add_i32 s85, 0, 0x10000
	s_cmp_eq_u32 s84, 28
	s_cselect_b32 s83, s40, s1
	s_cselect_b32 s82, s41, s0
	s_cselect_b32 s81, s67, s77
	s_cselect_b32 s80, s69, s75
	s_add_i32 s86, 0, 0x14000
	ds_read_b128 v[90:93], v184
	ds_read_b128 v[94:97], v184 offset:1024
	ds_read_b128 v[98:101], v184 offset:2048
	ds_read_b128 v[102:105], v184 offset:3072
	ds_read_b128 v[146:149], v184 offset:16384
	ds_read_b128 v[150:153], v184 offset:17408
	ds_read_b128 v[154:157], v184 offset:18432
	ds_read_b128 v[158:161], v184 offset:19456
	s_add_i32 m0, s45, 0xc000
	ds_read_b128 v[162:165], v227
	ds_read_b128 v[166:169], v227 offset:1024
	ds_read_b128 v[188:191], v227 offset:2048
	ds_read_b128 v[192:195], v227 offset:3072
	ds_read_b128 v[196:199], v227 offset:4096
	ds_read_b128 v[200:203], v227 offset:5120
	ds_read_b128 v[204:207], v227 offset:6144
	ds_read_b128 v[208:211], v227 offset:7168
	global_load_lds_dwordx4 v178, s[78:79]
	s_add_i32 m0, s45, 0xe000
	s_nop 0
	global_load_lds_dwordx4 v180, s[78:79]
	s_waitcnt vmcnt(8)
	s_waitcnt lgkmcnt(0)
	.p2align 3
	s_setprio 1
	s_barrier
; #define PG8_STAGE(bufoff, gbase, voff) do { _Pragma("unroll") for (int _i = 0; _i < 2; ++_i) \
;         __builtin_amdgcn_global_load_lds((const unsigned*)((const char*)(gbase) + (voff)[_i]), (PG8_LAS unsigned*)(lds + (bufoff) + ldsw + _i * 8192), 16, 0, 0); } while (0)
; #define PG8_LDA(dst, b, h) do { _Pragma("unroll") for (int m = 0; m < 4; ++m) _Pragma("unroll") for (int k = 0; k < 2; ++k) dst[m][k] = *(const PG8_LAS bf16x8*)(lds + PG8_SA(b, h) + aoff + m * 2048 + k * 1024); } while (0)
; #define PG8_LDB(dst, b, h) do { _Pragma("unroll") for (int n = 0; n < 2; ++n) _Pragma("unroll") for (int k = 0; k < 2; ++k) dst[n][k] = *(const PG8_LAS bf16x8*)(lds + PG8_SB(b, h) + boff + n * 2048 + k * 1024); } while (0)
; #define PG8_WAIT_V(n) asm volatile("s_waitcnt vmcnt(" #n ")" ::: "memory")
; #define PG8_WAIT_L(n) asm volatile("s_waitcnt lgkmcnt(" #n ")" ::: "memory")
; #define PG8_WAIT_V_SEL(sel) asm volatile("s_cmp_eq_u32 %0, 0\n\ts_cbranch_scc1 .Lw8_%=\n\ts_waitcnt vmcnt(22)\n\ts_branch .Lwd_%=\n.Lw8_%=:\n\ts_waitcnt vmcnt(8)\n.Lwd_%=:" :: "s"(sel) : "memory", "scc")
; #define PG8_BAR __builtin_amdgcn_s_barrier()
; #define PG8_SCHED __builtin_amdgcn_sched_barrier(0)
;     ...
;             PG8_WAIT_L(0); PG8_BAR; PG8_MMA(0, 0, At, B0); PG8_MMA(0, 1, At, B1); PG8_BAR; PG8_SCHED;
;             PG8_LDA(At, 0, 1); PG8_STAGE(PG8_SB(0, 0), b2, voffB); PG8_STAGE(PG8_SB(0, 1), b2 + hstep, voffB); PG8_STAGE(PG8_SA(0, 0), a2, voffA);
;             PG8_WAIT_V_SEL(relax);
;             PG8_WAIT_L(0); PG8_BAR; PG8_MMA(1, 0, At, B0); PG8_MMA(1, 1, At, B1); PG8_BAR; PG8_SCHED;
;             PG8_LDB(B0, 1, 0); PG8_LDB(B1, 1, 1); PG8_SCHED; PG8_LDA(At, 1, 0); PG8_STAGE(PG8_SA(0, 1), a2 + hstep, voffA);
;             PG8_WAIT_V(8); PG8_WAIT_L(0); PG8_BAR; PG8_MMA(0, 0, At, B0); PG8_MMA(0, 1, At, B1); PG8_BAR; PG8_SCHED;
	v_mfma_f32_16x16x32_bf16 v[142:145], v[90:93], v[162:165], v[142:145]
	v_mfma_f32_16x16x32_bf16 v[142:145], v[94:97], v[166:169], v[142:145]
	v_mfma_f32_16x16x32_bf16 v[126:129], v[90:93], v[188:191], v[126:129]
	v_mfma_f32_16x16x32_bf16 v[126:129], v[94:97], v[192:195], v[126:129]
	v_mfma_f32_16x16x32_bf16 v[110:113], v[90:93], v[196:199], v[110:113]
	v_mfma_f32_16x16x32_bf16 v[110:113], v[94:97], v[200:203], v[110:113]
	v_mfma_f32_16x16x32_bf16 v[78:81], v[90:93], v[204:207], v[78:81]
	v_mfma_f32_16x16x32_bf16 v[78:81], v[94:97], v[208:211], v[78:81]
	v_mfma_f32_16x16x32_bf16 v[74:77], v[98:101], v[204:207], v[74:77]
	v_mfma_f32_16x16x32_bf16 v[74:77], v[102:105], v[208:211], v[74:77]
	v_mfma_f32_16x16x32_bf16 v[106:109], v[98:101], v[196:199], v[106:109]
	v_mfma_f32_16x16x32_bf16 v[106:109], v[102:105], v[200:203], v[106:109]
	v_mfma_f32_16x16x32_bf16 v[122:125], v[98:101], v[188:191], v[122:125]
	v_mfma_f32_16x16x32_bf16 v[122:125], v[102:105], v[192:195], v[122:125]
	v_mfma_f32_16x16x32_bf16 v[138:141], v[98:101], v[162:165], v[138:141]
	v_mfma_f32_16x16x32_bf16 v[138:141], v[102:105], v[166:169], v[138:141]
	v_mfma_f32_16x16x32_bf16 v[134:137], v[146:149], v[162:165], v[134:137]
	v_mfma_f32_16x16x32_bf16 v[134:137], v[150:153], v[166:169], v[134:137]
	v_mfma_f32_16x16x32_bf16 v[118:121], v[146:149], v[188:191], v[118:121]
	v_mfma_f32_16x16x32_bf16 v[118:121], v[150:153], v[192:195], v[118:121]
	v_mfma_f32_16x16x32_bf16 v[86:89], v[146:149], v[196:199], v[86:89]
	v_mfma_f32_16x16x32_bf16 v[86:89], v[150:153], v[200:203], v[86:89]
	v_mfma_f32_16x16x32_bf16 v[70:73], v[146:149], v[204:207], v[70:73]
	v_mfma_f32_16x16x32_bf16 v[70:73], v[150:153], v[208:211], v[70:73]
	v_mfma_f32_16x16x32_bf16 v[66:69], v[154:157], v[204:207], v[66:69]
	v_mfma_f32_16x16x32_bf16 v[66:69], v[158:161], v[208:211], v[66:69]
	v_mfma_f32_16x16x32_bf16 v[82:85], v[154:157], v[196:199], v[82:85]
	v_mfma_f32_16x16x32_bf16 v[82:85], v[158:161], v[200:203], v[82:85]
	v_mfma_f32_16x16x32_bf16 v[114:117], v[154:157], v[188:191], v[114:117]
	v_mfma_f32_16x16x32_bf16 v[114:117], v[158:161], v[192:195], v[114:117]
	v_mfma_f32_16x16x32_bf16 v[130:133], v[154:157], v[162:165], v[130:133]
	v_mfma_f32_16x16x32_bf16 v[130:133], v[158:161], v[166:169], v[130:133]
	s_barrier
	s_setprio 0
	s_add_i32 s0, s85, s33
	s_mov_b32 m0, s0
	ds_read_b128 v[162:165], v227 offset:16384
	ds_read_b128 v[166:169], v227 offset:17408
	ds_read_b128 v[188:191], v227 offset:18432
	ds_read_b128 v[192:195], v227 offset:19456
	ds_read_b128 v[196:199], v227 offset:20480
	ds_read_b128 v[200:203], v227 offset:21504
	ds_read_b128 v[204:207], v227 offset:22528
	ds_read_b128 v[208:211], v227 offset:23552
	global_load_lds_dwordx4 v182, s[80:81]
	s_add_i32 m0, s0, 0x2000
	s_add_u32 s0, s80, 0x80000
	s_addc_u32 s1, s81, 0
	s_add_i32 s85, s86, s33
	global_load_lds_dwordx4 v176, s[80:81]
	s_mov_b32 m0, s85
	s_nop 0
	global_load_lds_dwordx4 v182, s[0:1]
	s_add_i32 m0, s85, 0x2000
	s_nop 0
	global_load_lds_dwordx4 v176, s[0:1]
	s_mov_b32 m0, s45
	s_nop 0
	global_load_lds_dwordx4 v172, s[82:83]
	s_mov_b32 m0, s46
	s_nop 0
	global_load_lds_dwordx4 v174, s[82:83]
	s_waitcnt vmcnt(8)
	s_waitcnt lgkmcnt(0)
	.p2align 3
	s_setprio 1
	s_barrier
	v_mfma_f32_16x16x32_bf16 v[62:65], v[90:93], v[162:165], v[62:65]
	v_mfma_f32_16x16x32_bf16 v[62:65], v[94:97], v[166:169], v[62:65]
	v_mfma_f32_16x16x32_bf16 v[46:49], v[90:93], v[188:191], v[46:49]
	v_mfma_f32_16x16x32_bf16 v[46:49], v[94:97], v[192:195], v[46:49]
	v_mfma_f32_16x16x32_bf16 v[30:33], v[90:93], v[196:199], v[30:33]
	v_mfma_f32_16x16x32_bf16 v[30:33], v[94:97], v[200:203], v[30:33]
	v_mfma_f32_16x16x32_bf16 v[14:17], v[90:93], v[204:207], v[14:17]
	v_mfma_f32_16x16x32_bf16 v[14:17], v[94:97], v[208:211], v[14:17]
	v_mfma_f32_16x16x32_bf16 v[10:13], v[98:101], v[204:207], v[10:13]
	v_mfma_f32_16x16x32_bf16 v[10:13], v[102:105], v[208:211], v[10:13]
	v_mfma_f32_16x16x32_bf16 v[26:29], v[98:101], v[196:199], v[26:29]
	v_mfma_f32_16x16x32_bf16 v[26:29], v[102:105], v[200:203], v[26:29]
	v_mfma_f32_16x16x32_bf16 v[42:45], v[98:101], v[188:191], v[42:45]
	v_mfma_f32_16x16x32_bf16 v[42:45], v[102:105], v[192:195], v[42:45]
	v_mfma_f32_16x16x32_bf16 v[58:61], v[98:101], v[162:165], v[58:61]
	v_mfma_f32_16x16x32_bf16 v[58:61], v[102:105], v[166:169], v[58:61]
	v_mfma_f32_16x16x32_bf16 v[54:57], v[146:149], v[162:165], v[54:57]
	v_mfma_f32_16x16x32_bf16 v[54:57], v[150:153], v[166:169], v[54:57]
	v_mfma_f32_16x16x32_bf16 v[38:41], v[146:149], v[188:191], v[38:41]
	v_mfma_f32_16x16x32_bf16 v[38:41], v[150:153], v[192:195], v[38:41]
	v_mfma_f32_16x16x32_bf16 v[22:25], v[146:149], v[196:199], v[22:25]
	v_mfma_f32_16x16x32_bf16 v[22:25], v[150:153], v[200:203], v[22:25]
	v_mfma_f32_16x16x32_bf16 v[6:9], v[146:149], v[204:207], v[6:9]
	v_mfma_f32_16x16x32_bf16 v[6:9], v[150:153], v[208:211], v[6:9]
	v_mfma_f32_16x16x32_bf16 v[2:5], v[154:157], v[204:207], v[2:5]
	v_mfma_f32_16x16x32_bf16 v[2:5], v[158:161], v[208:211], v[2:5]
	v_mfma_f32_16x16x32_bf16 v[18:21], v[154:157], v[196:199], v[18:21]
	v_mfma_f32_16x16x32_bf16 v[18:21], v[158:161], v[200:203], v[18:21]
	v_mfma_f32_16x16x32_bf16 v[34:37], v[154:157], v[188:191], v[34:37]
	v_mfma_f32_16x16x32_bf16 v[34:37], v[158:161], v[192:195], v[34:37]
	v_mfma_f32_16x16x32_bf16 v[50:53], v[154:157], v[162:165], v[50:53]
	v_mfma_f32_16x16x32_bf16 v[50:53], v[158:161], v[166:169], v[50:53]
	s_barrier
; #define PG8_STAGE(bufoff, gbase, voff) do { _Pragma("unroll") for (int _i = 0; _i < 2; ++_i) \
;         __builtin_amdgcn_global_load_lds((const unsigned*)((const char*)(gbase) + (voff)[_i]), (PG8_LAS unsigned*)(lds + (bufoff) + ldsw + _i * 8192), 16, 0, 0); } while (0)
; #define PG8_LDA(dst, b, h) do { _Pragma("unroll") for (int m = 0; m < 4; ++m) _Pragma("unroll") for (int k = 0; k < 2; ++k) dst[m][k] = *(const PG8_LAS bf16x8*)(lds + PG8_SA(b, h) + aoff + m * 2048 + k * 1024); } while (0)
; #define PG8_LDB(dst, b, h) do { _Pragma("unroll") for (int n = 0; n < 2; ++n) _Pragma("unroll") for (int k = 0; k < 2; ++k) dst[n][k] = *(const PG8_LAS bf16x8*)(lds + PG8_SB(b, h) + boff + n * 2048 + k * 1024); } while (0)
; #define PG8_WAIT_V(n) asm volatile("s_waitcnt vmcnt(" #n ")" ::: "memory")
; #define PG8_WAIT_L(n) asm volatile("s_waitcnt lgkmcnt(" #n ")" ::: "memory")
; #define PG8_BAR __builtin_amdgcn_s_barrier()
; #define PG8_SCHED __builtin_amdgcn_sched_barrier(0)
;     ...
;             PG8_WAIT_L(0); PG8_BAR; PG8_MMA(1, 0, At, B0); PG8_MMA(1, 1, At, B1); PG8_BAR; PG8_SCHED;
;             PG8_LDB(B0, 1, 0); PG8_LDB(B1, 1, 1); PG8_SCHED; PG8_LDA(At, 1, 0); PG8_STAGE(PG8_SA(0, 1), a2 + hstep, voffA);
;             PG8_WAIT_V(8); PG8_WAIT_L(0); PG8_BAR; PG8_MMA(0, 0, At, B0); PG8_MMA(0, 1, At, B1); PG8_BAR; PG8_SCHED;
;             PG8_LDA(At, 1, 1); PG8_STAGE(PG8_SB(1, 0), b3, voffB); PG8_STAGE(PG8_SB(1, 1), b3 + hstep, voffB); PG8_STAGE(PG8_SA(1, 0), a3, voffA);
;             PG8_WAIT_V(8); PG8_WAIT_L(0); PG8_BAR; PG8_MMA(1, 0, At, B0); PG8_MMA(1, 1, At, B1); PG8_BAR; PG8_SCHED;
	s_setprio 0
	s_add_i32 s85, 0, 0x18000
	s_add_i32 s86, 0, 0x1c000
	ds_read_b128 v[90:93], v184 offset:32768
	ds_read_b128 v[94:97], v184 offset:33792
	ds_read_b128 v[98:101], v184 offset:34816
	ds_read_b128 v[102:105], v184 offset:35840
	ds_read_b128 v[146:149], v184 offset:49152
	ds_read_b128 v[150:153], v184 offset:50176
	ds_read_b128 v[154:157], v184 offset:51200
	ds_read_b128 v[158:161], v184 offset:52224
	s_add_u32 s0, s82, 0x80000
	s_addc_u32 s1, s83, 0
	s_mov_b32 m0, s47
	ds_read_b128 v[162:165], v227 offset:32768
	ds_read_b128 v[166:169], v227 offset:33792
	ds_read_b128 v[188:191], v227 offset:34816
	ds_read_b128 v[192:195], v227 offset:35840
	ds_read_b128 v[196:199], v227 offset:36864
	ds_read_b128 v[200:203], v227 offset:37888
	ds_read_b128 v[204:207], v227 offset:38912
	ds_read_b128 v[208:211], v227 offset:39936
	global_load_lds_dwordx4 v172, s[0:1]
	s_mov_b32 m0, s48
	s_nop 0
	global_load_lds_dwordx4 v174, s[0:1]
	s_waitcnt vmcnt(8)
	s_waitcnt lgkmcnt(0)
	.p2align 3
	s_setprio 1
	s_barrier
	v_mfma_f32_16x16x32_bf16 v[142:145], v[90:93], v[162:165], v[142:145]
	v_mfma_f32_16x16x32_bf16 v[142:145], v[94:97], v[166:169], v[142:145]
	v_mfma_f32_16x16x32_bf16 v[126:129], v[90:93], v[188:191], v[126:129]
	v_mfma_f32_16x16x32_bf16 v[126:129], v[94:97], v[192:195], v[126:129]
	v_mfma_f32_16x16x32_bf16 v[110:113], v[90:93], v[196:199], v[110:113]
	v_mfma_f32_16x16x32_bf16 v[110:113], v[94:97], v[200:203], v[110:113]
	v_mfma_f32_16x16x32_bf16 v[78:81], v[90:93], v[204:207], v[78:81]
	v_mfma_f32_16x16x32_bf16 v[78:81], v[94:97], v[208:211], v[78:81]
	v_mfma_f32_16x16x32_bf16 v[74:77], v[98:101], v[204:207], v[74:77]
	v_mfma_f32_16x16x32_bf16 v[74:77], v[102:105], v[208:211], v[74:77]
	v_mfma_f32_16x16x32_bf16 v[106:109], v[98:101], v[196:199], v[106:109]
	v_mfma_f32_16x16x32_bf16 v[106:109], v[102:105], v[200:203], v[106:109]
	v_mfma_f32_16x16x32_bf16 v[122:125], v[98:101], v[188:191], v[122:125]
	v_mfma_f32_16x16x32_bf16 v[122:125], v[102:105], v[192:195], v[122:125]
	v_mfma_f32_16x16x32_bf16 v[138:141], v[98:101], v[162:165], v[138:141]
	v_mfma_f32_16x16x32_bf16 v[138:141], v[102:105], v[166:169], v[138:141]
	v_mfma_f32_16x16x32_bf16 v[134:137], v[146:149], v[162:165], v[134:137]
	v_mfma_f32_16x16x32_bf16 v[134:137], v[150:153], v[166:169], v[134:137]
	v_mfma_f32_16x16x32_bf16 v[118:121], v[146:149], v[188:191], v[118:121]
	v_mfma_f32_16x16x32_bf16 v[118:121], v[150:153], v[192:195], v[118:121]
	v_mfma_f32_16x16x32_bf16 v[86:89], v[146:149], v[196:199], v[86:89]
	v_mfma_f32_16x16x32_bf16 v[86:89], v[150:153], v[200:203], v[86:89]
	v_mfma_f32_16x16x32_bf16 v[70:73], v[146:149], v[204:207], v[70:73]
	v_mfma_f32_16x16x32_bf16 v[70:73], v[150:153], v[208:211], v[70:73]
	v_mfma_f32_16x16x32_bf16 v[66:69], v[154:157], v[204:207], v[66:69]
	v_mfma_f32_16x16x32_bf16 v[66:69], v[158:161], v[208:211], v[66:69]
	v_mfma_f32_16x16x32_bf16 v[82:85], v[154:157], v[196:199], v[82:85]
	v_mfma_f32_16x16x32_bf16 v[82:85], v[158:161], v[200:203], v[82:85]
	v_mfma_f32_16x16x32_bf16 v[114:117], v[154:157], v[188:191], v[114:117]
	v_mfma_f32_16x16x32_bf16 v[114:117], v[158:161], v[192:195], v[114:117]
	v_mfma_f32_16x16x32_bf16 v[130:133], v[154:157], v[162:165], v[130:133]
	v_mfma_f32_16x16x32_bf16 v[130:133], v[158:161], v[166:169], v[130:133]
	s_barrier
	s_setprio 0
	s_add_i32 s0, s85, s33
	s_mov_b32 m0, s0
	ds_read_b128 v[162:165], v227 offset:49152
	ds_read_b128 v[166:169], v227 offset:50176
	ds_read_b128 v[188:191], v227 offset:51200
	ds_read_b128 v[192:195], v227 offset:52224
	ds_read_b128 v[196:199], v227 offset:53248
	ds_read_b128 v[200:203], v227 offset:54272
	ds_read_b128 v[204:207], v227 offset:55296
	ds_read_b128 v[208:211], v227 offset:56320
	s_add_u32 s100, s80, 0x80
	s_addc_u32 s101, s81, 0
	global_load_lds_dwordx4 v182, s[100:101]
	s_add_i32 m0, s0, 0x2000
	s_add_u32 s0, s80, 0x80080
	s_addc_u32 s1, s81, 0
	s_add_i32 s80, s86, s33
	global_load_lds_dwordx4 v176, s[100:101]
	s_mov_b32 m0, s80
	s_nop 0
	global_load_lds_dwordx4 v182, s[0:1]
	s_add_i32 m0, s80, 0x2000
	s_nop 0
	global_load_lds_dwordx4 v176, s[0:1]
	s_mov_b32 m0, s50
	s_nop 0
	s_add_u32 s100, s82, 0x80
	s_addc_u32 s101, s83, 0
	global_load_lds_dwordx4 v172, s[100:101]
	s_mov_b32 m0, s51
	s_nop 0
	global_load_lds_dwordx4 v174, s[100:101]
	s_waitcnt vmcnt(8)
	s_waitcnt lgkmcnt(0)
	.p2align 3
	s_setprio 1
	s_barrier
	v_mfma_f32_16x16x32_bf16 v[62:65], v[90:93], v[162:165], v[62:65]
	v_mfma_f32_16x16x32_bf16 v[62:65], v[94:97], v[166:169], v[62:65]
	v_mfma_f32_16x16x32_bf16 v[46:49], v[90:93], v[188:191], v[46:49]
	v_mfma_f32_16x16x32_bf16 v[46:49], v[94:97], v[192:195], v[46:49]
	v_mfma_f32_16x16x32_bf16 v[30:33], v[90:93], v[196:199], v[30:33]
	v_mfma_f32_16x16x32_bf16 v[30:33], v[94:97], v[200:203], v[30:33]
	v_mfma_f32_16x16x32_bf16 v[14:17], v[90:93], v[204:207], v[14:17]
	v_mfma_f32_16x16x32_bf16 v[14:17], v[94:97], v[208:211], v[14:17]
	v_mfma_f32_16x16x32_bf16 v[10:13], v[98:101], v[204:207], v[10:13]
	v_mfma_f32_16x16x32_bf16 v[10:13], v[102:105], v[208:211], v[10:13]
	v_mfma_f32_16x16x32_bf16 v[26:29], v[98:101], v[196:199], v[26:29]
	v_mfma_f32_16x16x32_bf16 v[26:29], v[102:105], v[200:203], v[26:29]
	v_mfma_f32_16x16x32_bf16 v[42:45], v[98:101], v[188:191], v[42:45]
	v_mfma_f32_16x16x32_bf16 v[42:45], v[102:105], v[192:195], v[42:45]
	v_mfma_f32_16x16x32_bf16 v[58:61], v[98:101], v[162:165], v[58:61]
	v_mfma_f32_16x16x32_bf16 v[58:61], v[102:105], v[166:169], v[58:61]
	v_mfma_f32_16x16x32_bf16 v[54:57], v[146:149], v[162:165], v[54:57]
	v_mfma_f32_16x16x32_bf16 v[54:57], v[150:153], v[166:169], v[54:57]
	v_mfma_f32_16x16x32_bf16 v[38:41], v[146:149], v[188:191], v[38:41]
	v_mfma_f32_16x16x32_bf16 v[38:41], v[150:153], v[192:195], v[38:41]
	v_mfma_f32_16x16x32_bf16 v[22:25], v[146:149], v[196:199], v[22:25]
	v_mfma_f32_16x16x32_bf16 v[22:25], v[150:153], v[200:203], v[22:25]
	v_mfma_f32_16x16x32_bf16 v[6:9], v[146:149], v[204:207], v[6:9]
	v_mfma_f32_16x16x32_bf16 v[6:9], v[150:153], v[208:211], v[6:9]
	v_mfma_f32_16x16x32_bf16 v[2:5], v[154:157], v[204:207], v[2:5]
	v_mfma_f32_16x16x32_bf16 v[2:5], v[158:161], v[208:211], v[2:5]
	v_mfma_f32_16x16x32_bf16 v[18:21], v[154:157], v[196:199], v[18:21]
	v_mfma_f32_16x16x32_bf16 v[18:21], v[158:161], v[200:203], v[18:21]
	v_mfma_f32_16x16x32_bf16 v[34:37], v[154:157], v[188:191], v[34:37]
	v_mfma_f32_16x16x32_bf16 v[34:37], v[158:161], v[192:195], v[34:37]
	v_mfma_f32_16x16x32_bf16 v[50:53], v[154:157], v[162:165], v[50:53]
	v_mfma_f32_16x16x32_bf16 v[50:53], v[158:161], v[166:169], v[50:53]
	s_barrier
	s_setprio 0
	s_add_i32 s84, s84, 2
	s_add_u32 s78, s78, 0x100
	s_addc_u32 s79, s79, 0
	s_add_u32 s75, s75, 0x100
	s_addc_u32 s77, s77, 0
	s_cmp_gt_u32 s84, 29
	s_cbranch_scc0 .LBB0_1170
.Lpeel_1170_x:
	s_branch .Lrlx_wo_x
.Lrlx_wo_0:
	s_waitcnt vmcnt(22)
	s_branch .Lrlx_wo_0_b

;     __host__ __device__ bool next(int i, Unit& u) const { const long L = (long)i * G + c; if (L >= lim) return false; unit_of((int)L, u); return true; }
;     __device__ __forceinline__ bool next(int i, Unit& v) const { if (i != 0) return false; v = u; return true; }
; #define PG8_LDA(dst, b, h) do { _Pragma("unroll") for (int m = 0; m < 4; ++m) _Pragma("unroll") for (int k = 0; k < 2; ++k) dst[m][k] = *(const PG8_LAS bf16x8*)(lds + PG8_SA(b, h) + aoff + m * 2048 + k * 1024); } while (0)
;     ...
;         const bool has_next = S.next(ui + 1, nxt);
;         if constexpr (TP == 3) { if (ui > 0) tp_acc += __builtin_amdgcn_s_memrealtime() - tp3; }
;         const char* nA = has_next ? (const char*)g.A + (size_t)nxt.pm * tstep : cA; const char* nB = has_next ? (const char*)g.Bt + (size_t)nxt.pn * tstep : cB;
;         for (int t = 0; t < nt * KREP; t += 2) {
;             const bool last = (t == nt * KREP - 2);
;             const int t1w = KREP > 1 ? ((t + 1) & (nt - 1)) : t + 1, t2w = KREP > 1 ? ((t + 2) & (nt - 1)) : t + 2;
;             const char* a1 = cA + (size_t)t1w * kstep;
;             const char* a2 = last ? nA : cA + (size_t)t2w * kstep; const char* b2 = last ? nB : cB + (size_t)t2w * kstep;
;             const char* a3 = a2 + kstep; const char* b3 = b2 + kstep;
;             if (last && has_next) S.a_ready(nxt);
;             const int relax = __builtin_amdgcn_readfirstlane((MK_RELAXW && t == 0 && ui > 0) ? 1 : 0);
;             if constexpr (SP2) {
;             PG8_LDB(B0, 0, 0); PG8_LDB(B1, 0, 1); PG8_SCHED; PG8_LDA(At, 0, 0); PG8_STAGE(PG8_SA(1, 1), a1 + hstep, voffA);
;             PG8_WAIT_V_SEL(relax);
;             PG8_WAIT_L(0); PG8_BAR; PG8_MMA(0, 0, At, B0); PG8_MMA(0, 1, At, B1); PG8_BAR; PG8_SCHED;
;             PG8_LDA(At, 0, 1); PG8_STAGE(PG8_SB(0, 0), b2, voffB); PG8_STAGE(PG8_SB(0, 1), b2 + hstep, voffB); PG8_STAGE(PG8_SA(0, 0), a2, voffA);
;             PG8_WAIT_V_SEL(relax);
;             PG8_WAIT_L(0); PG8_BAR; PG8_MMA(1, 0, At, B0); PG8_MMA(1, 1, At, B1); PG8_BAR; PG8_SCHED;
;     ...
; #pragma unroll
;         for (int a = 0; a < 2; ++a)
; #pragma unroll
;             for (int b = 0; b < 2; ++b)
; #pragma unroll
;                 for (int m = 0; m < 4; ++m)
; #pragma unroll
;                     for (int n = 0; n < 2; ++n) acc[a][b][m][n] = (f32x4){0.f, 0.f, 0.f, 0.f};
;         cur = nxt; cA = nA; cB = nB; ++ui;
.LBB0_1326:
	s_ashr_i32 s89, s88, 31
	s_lshl_b64 s[40:41], s[88:89], 20
	s_add_u32 s90, s23, s40
	s_addc_u32 s91, s31, s41
	s_and_b64 s[40:41], s[8:9], exec
	s_cselect_b32 s59, s91, s13
	s_cselect_b32 s64, s90, s12
	s_ashr_i32 s87, s86, 31
	s_lshl_b64 s[40:41], s[86:87], 20
	s_add_u32 s92, s56, s40
	s_addc_u32 s93, s57, s41
	s_and_b64 s[40:41], s[8:9], exec
	s_cselect_b32 s65, s93, s97
	s_cselect_b32 s87, s92, s96
	s_add_u32 s66, s96, 0x100
	s_addc_u32 s67, s97, 0
	s_mov_b32 s0, -2
	v_add_u32_e32 v200, 0x10000, v203
	s_add_u32 s96, s12, 0x100
	s_addc_u32 s97, s13, 0
	s_add_i32 s51, 0, 0x10000
	s_cmp_eq_u32 s0, 28
	s_cselect_b32 s41, s59, s97
	s_cselect_b32 s40, s64, s96
	s_cselect_b32 vcc_hi, s65, s67
	s_cselect_b32 vcc_lo, s87, s66
	s_add_i32 s19, 0, 0x14000
	ds_read_b128 v[66:69], v200
	ds_read_b128 v[70:73], v200 offset:1024
	ds_read_b128 v[82:85], v200 offset:2048
	ds_read_b128 v[142:145], v200 offset:3072
	ds_read_b128 v[146:149], v200 offset:16384
	ds_read_b128 v[150:153], v200 offset:17408
	ds_read_b128 v[154:157], v200 offset:18432
	ds_read_b128 v[158:161], v200 offset:19456
	s_add_i32 m0, s95, 0xc000
	ds_read_b128 v[162:165], v219
	ds_read_b128 v[166:169], v219 offset:1024
	ds_read_b128 v[170:173], v219 offset:2048
	ds_read_b128 v[174:177], v219 offset:3072
	ds_read_b128 v[178:181], v219 offset:4096
	ds_read_b128 v[184:187], v219 offset:5120
	ds_read_b128 v[220:223], v219 offset:6144
	ds_read_b128 v[224:227], v219 offset:7168
	global_load_lds_dwordx4 v196, s[12:13]
	s_add_i32 m0, s95, 0xe000
	s_nop 0
	global_load_lds_dwordx4 v198, s[12:13]
	s_cmp_lg_u32 s11, 0
	s_cbranch_scc1 .Lrlx_f1_0
	s_waitcnt vmcnt(8)
.Lrlx_f1_0_b:
	s_waitcnt lgkmcnt(0)
	.p2align 3
	s_setprio 1
	s_barrier
	v_mfma_f32_16x16x32_bf16 v[114:117], v[66:69], v[162:165], 0
	v_mfma_f32_16x16x32_bf16 v[114:117], v[70:73], v[166:169], v[114:117]
	v_mfma_f32_16x16x32_bf16 v[110:113], v[66:69], v[170:173], 0
	v_mfma_f32_16x16x32_bf16 v[110:113], v[70:73], v[174:177], v[110:113]
	v_mfma_f32_16x16x32_bf16 v[78:81], v[66:69], v[178:181], 0
	v_mfma_f32_16x16x32_bf16 v[78:81], v[70:73], v[184:187], v[78:81]
	v_mfma_f32_16x16x32_bf16 v[74:77], v[66:69], v[220:223], 0
	v_mfma_f32_16x16x32_bf16 v[74:77], v[70:73], v[224:227], v[74:77]
	v_mfma_f32_16x16x32_bf16 v[134:137], v[82:85], v[220:223], 0
	v_mfma_f32_16x16x32_bf16 v[134:137], v[142:145], v[224:227], v[134:137]
	v_mfma_f32_16x16x32_bf16 v[138:141], v[82:85], v[178:181], 0
	v_mfma_f32_16x16x32_bf16 v[138:141], v[142:145], v[184:187], v[138:141]
	v_mfma_f32_16x16x32_bf16 v[102:105], v[82:85], v[170:173], 0
	v_mfma_f32_16x16x32_bf16 v[102:105], v[142:145], v[174:177], v[102:105]
	v_mfma_f32_16x16x32_bf16 v[106:109], v[82:85], v[162:165], 0
	v_mfma_f32_16x16x32_bf16 v[106:109], v[142:145], v[166:169], v[106:109]
	v_mfma_f32_16x16x32_bf16 v[98:101], v[146:149], v[162:165], 0
	v_mfma_f32_16x16x32_bf16 v[98:101], v[150:153], v[166:169], v[98:101]
	v_mfma_f32_16x16x32_bf16 v[94:97], v[146:149], v[170:173], 0
	v_mfma_f32_16x16x32_bf16 v[94:97], v[150:153], v[174:177], v[94:97]
	v_mfma_f32_16x16x32_bf16 v[130:133], v[146:149], v[178:181], 0
	v_mfma_f32_16x16x32_bf16 v[130:133], v[150:153], v[184:187], v[130:133]
	v_mfma_f32_16x16x32_bf16 v[126:129], v[146:149], v[220:223], 0
	v_mfma_f32_16x16x32_bf16 v[126:129], v[150:153], v[224:227], v[126:129]
	v_mfma_f32_16x16x32_bf16 v[118:121], v[154:157], v[220:223], 0
	v_mfma_f32_16x16x32_bf16 v[118:121], v[158:161], v[224:227], v[118:121]
	v_mfma_f32_16x16x32_bf16 v[122:125], v[154:157], v[178:181], 0
	v_mfma_f32_16x16x32_bf16 v[122:125], v[158:161], v[184:187], v[122:125]
	v_mfma_f32_16x16x32_bf16 v[86:89], v[154:157], v[170:173], 0
	v_mfma_f32_16x16x32_bf16 v[86:89], v[158:161], v[174:177], v[86:89]
	v_mfma_f32_16x16x32_bf16 v[90:93], v[154:157], v[162:165], 0
	v_mfma_f32_16x16x32_bf16 v[90:93], v[158:161], v[166:169], v[90:93]
	s_barrier
	s_setprio 0
	s_add_i32 s12, s51, s37
	s_mov_b32 m0, s12
	ds_read_b128 v[162:165], v219 offset:16384
	ds_read_b128 v[166:169], v219 offset:17408
	ds_read_b128 v[170:173], v219 offset:18432
	ds_read_b128 v[174:177], v219 offset:19456
	ds_read_b128 v[178:181], v219 offset:20480
	ds_read_b128 v[184:187], v219 offset:21504
	ds_read_b128 v[220:223], v219 offset:22528
	ds_read_b128 v[224:227], v219 offset:23552
	global_load_lds_dwordx4 v182, vcc
	s_add_i32 m0, s12, 0x2000
	s_add_u32 s12, vcc_lo, 0x80000
	s_addc_u32 s13, vcc_hi, 0
	s_add_i32 s19, s19, s37
	global_load_lds_dwordx4 v192, vcc
	s_mov_b32 m0, s19
	s_nop 0
	global_load_lds_dwordx4 v182, s[12:13]
	s_add_i32 m0, s19, 0x2000
	s_nop 0
	global_load_lds_dwordx4 v192, s[12:13]
	s_mov_b32 m0, s95
	s_nop 0
	global_load_lds_dwordx4 v188, s[40:41]
	s_mov_b32 m0, s20
	s_nop 0
	global_load_lds_dwordx4 v190, s[40:41]
	s_cmp_lg_u32 s11, 0
	s_cbranch_scc1 .Lrlx_f1_1
	s_waitcnt vmcnt(8)
; #define PG8_STAGE(bufoff, gbase, voff) do { _Pragma("unroll") for (int _i = 0; _i < 2; ++_i) \
;         __builtin_amdgcn_global_load_lds((const unsigned*)((const char*)(gbase) + (voff)[_i]), (PG8_LAS unsigned*)(lds + (bufoff) + ldsw + _i * 8192), 16, 0, 0); } while (0)
; #define PG8_LDA(dst, b, h) do { _Pragma("unroll") for (int m = 0; m < 4; ++m) _Pragma("unroll") for (int k = 0; k < 2; ++k) dst[m][k] = *(const PG8_LAS bf16x8*)(lds + PG8_SA(b, h) + aoff + m * 2048 + k * 1024); } while (0)
; #define PG8_LDB(dst, b, h) do { _Pragma("unroll") for (int n = 0; n < 2; ++n) _Pragma("unroll") for (int k = 0; k < 2; ++k) dst[n][k] = *(const PG8_LAS bf16x8*)(lds + PG8_SB(b, h) + boff + n * 2048 + k * 1024); } while (0)
; #define PG8_WAIT_V(n) asm volatile("s_waitcnt vmcnt(" #n ")" ::: "memory")
; #define PG8_WAIT_L(n) asm volatile("s_waitcnt lgkmcnt(" #n ")" ::: "memory")
; #define PG8_WAIT_V_SEL(sel) asm volatile("s_cmp_eq_u32 %0, 0\n\ts_cbranch_scc1 .Lw8_%=\n\ts_waitcnt vmcnt(22)\n\ts_branch .Lwd_%=\n.Lw8_%=:\n\ts_waitcnt vmcnt(8)\n.Lwd_%=:" :: "s"(sel) : "memory", "scc")
; #define PG8_BAR __builtin_amdgcn_s_barrier()
; #define PG8_SCHED __builtin_amdgcn_sched_barrier(0)
;     ...
;             PG8_WAIT_L(0); PG8_BAR; PG8_MMA(0, 0, At, B0); PG8_MMA(0, 1, At, B1); PG8_BAR; PG8_SCHED;
;             PG8_LDA(At, 0, 1); PG8_STAGE(PG8_SB(0, 0), b2, voffB); PG8_STAGE(PG8_SB(0, 1), b2 + hstep, voffB); PG8_STAGE(PG8_SA(0, 0), a2, voffA);
;             PG8_WAIT_V_SEL(relax);
;             PG8_WAIT_L(0); PG8_BAR; PG8_MMA(1, 0, At, B0); PG8_MMA(1, 1, At, B1); PG8_BAR; PG8_SCHED;
;             PG8_LDB(B0, 1, 0); PG8_LDB(B1, 1, 1); PG8_SCHED; PG8_LDA(At, 1, 0); PG8_STAGE(PG8_SA(0, 1), a2 + hstep, voffA);
;             PG8_WAIT_V(8); PG8_WAIT_L(0); PG8_BAR; PG8_MMA(0, 0, At, B0); PG8_MMA(0, 1, At, B1); PG8_BAR; PG8_SCHED;
;             PG8_LDA(At, 1, 1); PG8_STAGE(PG8_SB(1, 0), b3, voffB); PG8_STAGE(PG8_SB(1, 1), b3 + hstep, voffB); PG8_STAGE(PG8_SA(1, 0), a3, voffA);
;             PG8_WAIT_V(8); PG8_WAIT_L(0); PG8_BAR; PG8_MMA(1, 0, At, B0); PG8_MMA(1, 1, At, B1); PG8_BAR; PG8_SCHED;
.Lrlx_f1_1_b:
	s_waitcnt lgkmcnt(0)
	.p2align 3
	s_setprio 1
	s_barrier
	v_mfma_f32_16x16x32_bf16 v[30:33], v[66:69], v[162:165], 0
	v_mfma_f32_16x16x32_bf16 v[30:33], v[70:73], v[166:169], v[30:33]
	v_mfma_f32_16x16x32_bf16 v[26:29], v[66:69], v[170:173], 0
	v_mfma_f32_16x16x32_bf16 v[26:29], v[70:73], v[174:177], v[26:29]
	v_mfma_f32_16x16x32_bf16 v[62:65], v[66:69], v[178:181], 0
	v_mfma_f32_16x16x32_bf16 v[62:65], v[70:73], v[184:187], v[62:65]
	v_mfma_f32_16x16x32_bf16 v[58:61], v[66:69], v[220:223], 0
	v_mfma_f32_16x16x32_bf16 v[58:61], v[70:73], v[224:227], v[58:61]
	v_mfma_f32_16x16x32_bf16 v[50:53], v[82:85], v[220:223], 0
	v_mfma_f32_16x16x32_bf16 v[50:53], v[142:145], v[224:227], v[50:53]
	v_mfma_f32_16x16x32_bf16 v[54:57], v[82:85], v[178:181], 0
	v_mfma_f32_16x16x32_bf16 v[54:57], v[142:145], v[184:187], v[54:57]
	v_mfma_f32_16x16x32_bf16 v[18:21], v[82:85], v[170:173], 0
	v_mfma_f32_16x16x32_bf16 v[18:21], v[142:145], v[174:177], v[18:21]
	v_mfma_f32_16x16x32_bf16 v[22:25], v[82:85], v[162:165], 0
	v_mfma_f32_16x16x32_bf16 v[22:25], v[142:145], v[166:169], v[22:25]
	v_mfma_f32_16x16x32_bf16 v[14:17], v[146:149], v[162:165], 0
	v_mfma_f32_16x16x32_bf16 v[14:17], v[150:153], v[166:169], v[14:17]
	v_mfma_f32_16x16x32_bf16 v[10:13], v[146:149], v[170:173], 0
	v_mfma_f32_16x16x32_bf16 v[10:13], v[150:153], v[174:177], v[10:13]
	v_mfma_f32_16x16x32_bf16 v[46:49], v[146:149], v[178:181], 0
	v_mfma_f32_16x16x32_bf16 v[46:49], v[150:153], v[184:187], v[46:49]
	v_mfma_f32_16x16x32_bf16 v[38:41], v[146:149], v[220:223], 0
	v_mfma_f32_16x16x32_bf16 v[38:41], v[150:153], v[224:227], v[38:41]
	v_mfma_f32_16x16x32_bf16 v[42:45], v[154:157], v[220:223], 0
	v_mfma_f32_16x16x32_bf16 v[42:45], v[158:161], v[224:227], v[42:45]
	v_mfma_f32_16x16x32_bf16 v[34:37], v[154:157], v[178:181], 0
	v_mfma_f32_16x16x32_bf16 v[34:37], v[158:161], v[184:187], v[34:37]
	v_mfma_f32_16x16x32_bf16 v[2:5], v[154:157], v[170:173], 0
	v_mfma_f32_16x16x32_bf16 v[2:5], v[158:161], v[174:177], v[2:5]
	v_mfma_f32_16x16x32_bf16 v[6:9], v[154:157], v[162:165], 0
	v_mfma_f32_16x16x32_bf16 v[6:9], v[158:161], v[166:169], v[6:9]
	s_barrier
	s_setprio 0
	s_add_i32 s19, 0, 0x18000
	s_add_i32 s51, 0, 0x1c000
	ds_read_b128 v[66:69], v200 offset:32768
	ds_read_b128 v[70:73], v200 offset:33792
	ds_read_b128 v[82:85], v200 offset:34816
	ds_read_b128 v[142:145], v200 offset:35840
	ds_read_b128 v[146:149], v200 offset:49152
	ds_read_b128 v[150:153], v200 offset:50176
	ds_read_b128 v[154:157], v200 offset:51200
	ds_read_b128 v[158:161], v200 offset:52224
	s_add_u32 s12, s40, 0x80000
	s_addc_u32 s13, s41, 0
	s_mov_b32 m0, s44
	ds_read_b128 v[162:165], v219 offset:32768
	ds_read_b128 v[166:169], v219 offset:33792
	ds_read_b128 v[170:173], v219 offset:34816
	ds_read_b128 v[174:177], v219 offset:35840
	ds_read_b128 v[178:181], v219 offset:36864
	ds_read_b128 v[184:187], v219 offset:37888
	ds_read_b128 v[220:223], v219 offset:38912
	ds_read_b128 v[224:227], v219 offset:39936
	global_load_lds_dwordx4 v188, s[12:13]
	s_mov_b32 m0, s46
	s_nop 0
	global_load_lds_dwordx4 v190, s[12:13]
	s_waitcnt vmcnt(8)
	s_waitcnt lgkmcnt(0)
	.p2align 3
	s_setprio 1
	s_barrier
	v_mfma_f32_16x16x32_bf16 v[114:117], v[66:69], v[162:165], v[114:117]
	v_mfma_f32_16x16x32_bf16 v[114:117], v[70:73], v[166:169], v[114:117]
	v_mfma_f32_16x16x32_bf16 v[110:113], v[66:69], v[170:173], v[110:113]
	v_mfma_f32_16x16x32_bf16 v[110:113], v[70:73], v[174:177], v[110:113]
	v_mfma_f32_16x16x32_bf16 v[78:81], v[66:69], v[178:181], v[78:81]
	v_mfma_f32_16x16x32_bf16 v[78:81], v[70:73], v[184:187], v[78:81]
	v_mfma_f32_16x16x32_bf16 v[74:77], v[66:69], v[220:223], v[74:77]
	v_mfma_f32_16x16x32_bf16 v[74:77], v[70:73], v[224:227], v[74:77]
	v_mfma_f32_16x16x32_bf16 v[134:137], v[82:85], v[220:223], v[134:137]
	v_mfma_f32_16x16x32_bf16 v[134:137], v[142:145], v[224:227], v[134:137]
	v_mfma_f32_16x16x32_bf16 v[138:141], v[82:85], v[178:181], v[138:141]
	v_mfma_f32_16x16x32_bf16 v[138:141], v[142:145], v[184:187], v[138:141]
	v_mfma_f32_16x16x32_bf16 v[102:105], v[82:85], v[170:173], v[102:105]
	v_mfma_f32_16x16x32_bf16 v[102:105], v[142:145], v[174:177], v[102:105]
	v_mfma_f32_16x16x32_bf16 v[106:109], v[82:85], v[162:165], v[106:109]
	v_mfma_f32_16x16x32_bf16 v[106:109], v[142:145], v[166:169], v[106:109]
	v_mfma_f32_16x16x32_bf16 v[98:101], v[146:149], v[162:165], v[98:101]
	v_mfma_f32_16x16x32_bf16 v[98:101], v[150:153], v[166:169], v[98:101]
	v_mfma_f32_16x16x32_bf16 v[94:97], v[146:149], v[170:173], v[94:97]
	v_mfma_f32_16x16x32_bf16 v[94:97], v[150:153], v[174:177], v[94:97]
	v_mfma_f32_16x16x32_bf16 v[130:133], v[146:149], v[178:181], v[130:133]
	v_mfma_f32_16x16x32_bf16 v[130:133], v[150:153], v[184:187], v[130:133]
	v_mfma_f32_16x16x32_bf16 v[126:129], v[146:149], v[220:223], v[126:129]
	v_mfma_f32_16x16x32_bf16 v[126:129], v[150:153], v[224:227], v[126:129]
	v_mfma_f32_16x16x32_bf16 v[118:121], v[154:157], v[220:223], v[118:121]
	v_mfma_f32_16x16x32_bf16 v[118:121], v[158:161], v[224:227], v[118:121]
	v_mfma_f32_16x16x32_bf16 v[122:125], v[154:157], v[178:181], v[122:125]
	v_mfma_f32_16x16x32_bf16 v[122:125], v[158:161], v[184:187], v[122:125]
	v_mfma_f32_16x16x32_bf16 v[86:89], v[154:157], v[170:173], v[86:89]
	v_mfma_f32_16x16x32_bf16 v[86:89], v[158:161], v[174:177], v[86:89]
	v_mfma_f32_16x16x32_bf16 v[90:93], v[154:157], v[162:165], v[90:93]
	v_mfma_f32_16x16x32_bf16 v[90:93], v[158:161], v[166:169], v[90:93]
	s_barrier
; #define PG8_STAGE(bufoff, gbase, voff) do { _Pragma("unroll") for (int _i = 0; _i < 2; ++_i) \
;         __builtin_amdgcn_global_load_lds((const unsigned*)((const char*)(gbase) + (voff)[_i]), (PG8_LAS unsigned*)(lds + (bufoff) + ldsw + _i * 8192), 16, 0, 0); } while (0)
; #define PG8_LDA(dst, b, h) do { _Pragma("unroll") for (int m = 0; m < 4; ++m) _Pragma("unroll") for (int k = 0; k < 2; ++k) dst[m][k] = *(const PG8_LAS bf16x8*)(lds + PG8_SA(b, h) + aoff + m * 2048 + k * 1024); } while (0)
; #define PG8_WAIT_V(n) asm volatile("s_waitcnt vmcnt(" #n ")" ::: "memory")
; #define PG8_WAIT_L(n) asm volatile("s_waitcnt lgkmcnt(" #n ")" ::: "memory")
;     ...
;         for (int t = 0; t < nt * KREP; t += 2) {
;             const bool last = (t == nt * KREP - 2);
;             const int t1w = KREP > 1 ? ((t + 1) & (nt - 1)) : t + 1, t2w = KREP > 1 ? ((t + 2) & (nt - 1)) : t + 2;
;             const char* a1 = cA + (size_t)t1w * kstep;
;             const char* a2 = last ? nA : cA + (size_t)t2w * kstep; const char* b2 = last ? nB : cB + (size_t)t2w * kstep;
;             const char* a3 = a2 + kstep; const char* b3 = b2 + kstep;
;             if (last && has_next) S.a_ready(nxt);
;             const int relax = __builtin_amdgcn_readfirstlane((MK_RELAXW && t == 0 && ui > 0) ? 1 : 0);
;             if constexpr (SP2) {
;             PG8_LDB(B0, 0, 0); PG8_LDB(B1, 0, 1); PG8_SCHED; PG8_LDA(At, 0, 0); PG8_STAGE(PG8_SA(1, 1), a1 + hstep, voffA);
;             PG8_WAIT_V_SEL(relax);
;             PG8_WAIT_L(0); PG8_BAR; PG8_MMA(0, 0, At, B0); PG8_MMA(0, 1, At, B1); PG8_BAR; PG8_SCHED;
;             PG8_LDA(At, 0, 1); PG8_STAGE(PG8_SB(0, 0), b2, voffB); PG8_STAGE(PG8_SB(0, 1), b2 + hstep, voffB); PG8_STAGE(PG8_SA(0, 0), a2, voffA);
;             PG8_WAIT_V_SEL(relax);
;             PG8_WAIT_L(0); PG8_BAR; PG8_MMA(1, 0, At, B0); PG8_MMA(1, 1, At, B1); PG8_BAR; PG8_SCHED;
;             PG8_LDB(B0, 1, 0); PG8_LDB(B1, 1, 1); PG8_SCHED; PG8_LDA(At, 1, 0); PG8_STAGE(PG8_SA(0, 1), a2 + hstep, voffA);
;             PG8_WAIT_V(8); PG8_WAIT_L(0); PG8_BAR; PG8_MMA(0, 0, At, B0); PG8_MMA(0, 1, At, B1); PG8_BAR; PG8_SCHED;
;             PG8_LDA(At, 1, 1); PG8_STAGE(PG8_SB(1, 0), b3, voffB); PG8_STAGE(PG8_SB(1, 1), b3 + hstep, voffB); PG8_STAGE(PG8_SA(1, 0), a3, voffA);
;             PG8_WAIT_V(8); PG8_WAIT_L(0); PG8_BAR; PG8_MMA(1, 0, At, B0); PG8_MMA(1, 1, At, B1); PG8_BAR; PG8_SCHED;
	s_setprio 0
	s_add_i32 s12, s19, s37
	s_mov_b32 m0, s12
	ds_read_b128 v[162:165], v219 offset:49152
	ds_read_b128 v[166:169], v219 offset:50176
	ds_read_b128 v[170:173], v219 offset:51200
	ds_read_b128 v[174:177], v219 offset:52224
	ds_read_b128 v[178:181], v219 offset:53248
	ds_read_b128 v[184:187], v219 offset:54272
	ds_read_b128 v[220:223], v219 offset:55296
	ds_read_b128 v[224:227], v219 offset:56320
	s_add_u32 s100, vcc_lo, 0x80
	s_addc_u32 s101, vcc_hi, 0
	global_load_lds_dwordx4 v182, s[100:101]
	s_add_i32 m0, s12, 0x2000
	s_add_u32 s12, vcc_lo, 0x80080
	s_addc_u32 s13, vcc_hi, 0
	s_add_i32 s19, s51, s37
	global_load_lds_dwordx4 v192, s[100:101]
	s_mov_b32 m0, s19
	s_nop 0
	global_load_lds_dwordx4 v182, s[12:13]
	s_add_i32 m0, s19, 0x2000
	s_nop 0
	global_load_lds_dwordx4 v192, s[12:13]
	s_mov_b32 m0, s45
	s_nop 0
	s_add_u32 s100, s40, 0x80
	s_addc_u32 s101, s41, 0
	global_load_lds_dwordx4 v188, s[100:101]
	s_mov_b32 m0, s24
	s_nop 0
	global_load_lds_dwordx4 v190, s[100:101]
	s_waitcnt vmcnt(8)
	s_waitcnt lgkmcnt(0)
	.p2align 3
	s_setprio 1
	s_barrier
	v_mfma_f32_16x16x32_bf16 v[30:33], v[66:69], v[162:165], v[30:33]
	v_mfma_f32_16x16x32_bf16 v[30:33], v[70:73], v[166:169], v[30:33]
	v_mfma_f32_16x16x32_bf16 v[26:29], v[66:69], v[170:173], v[26:29]
	v_mfma_f32_16x16x32_bf16 v[26:29], v[70:73], v[174:177], v[26:29]
	v_mfma_f32_16x16x32_bf16 v[62:65], v[66:69], v[178:181], v[62:65]
	v_mfma_f32_16x16x32_bf16 v[62:65], v[70:73], v[184:187], v[62:65]
	v_mfma_f32_16x16x32_bf16 v[58:61], v[66:69], v[220:223], v[58:61]
	v_mfma_f32_16x16x32_bf16 v[58:61], v[70:73], v[224:227], v[58:61]
	v_mfma_f32_16x16x32_bf16 v[50:53], v[82:85], v[220:223], v[50:53]
	v_mfma_f32_16x16x32_bf16 v[50:53], v[142:145], v[224:227], v[50:53]
	v_mfma_f32_16x16x32_bf16 v[54:57], v[82:85], v[178:181], v[54:57]
	v_mfma_f32_16x16x32_bf16 v[54:57], v[142:145], v[184:187], v[54:57]
	v_mfma_f32_16x16x32_bf16 v[18:21], v[82:85], v[170:173], v[18:21]
	v_mfma_f32_16x16x32_bf16 v[18:21], v[142:145], v[174:177], v[18:21]
	v_mfma_f32_16x16x32_bf16 v[22:25], v[82:85], v[162:165], v[22:25]
	v_mfma_f32_16x16x32_bf16 v[22:25], v[142:145], v[166:169], v[22:25]
	v_mfma_f32_16x16x32_bf16 v[14:17], v[146:149], v[162:165], v[14:17]
	v_mfma_f32_16x16x32_bf16 v[14:17], v[150:153], v[166:169], v[14:17]
	v_mfma_f32_16x16x32_bf16 v[10:13], v[146:149], v[170:173], v[10:13]
	v_mfma_f32_16x16x32_bf16 v[10:13], v[150:153], v[174:177], v[10:13]
	v_mfma_f32_16x16x32_bf16 v[46:49], v[146:149], v[178:181], v[46:49]
	v_mfma_f32_16x16x32_bf16 v[46:49], v[150:153], v[184:187], v[46:49]
	v_mfma_f32_16x16x32_bf16 v[38:41], v[146:149], v[220:223], v[38:41]
	v_mfma_f32_16x16x32_bf16 v[38:41], v[150:153], v[224:227], v[38:41]
	v_mfma_f32_16x16x32_bf16 v[42:45], v[154:157], v[220:223], v[42:45]
	v_mfma_f32_16x16x32_bf16 v[42:45], v[158:161], v[224:227], v[42:45]
	v_mfma_f32_16x16x32_bf16 v[34:37], v[154:157], v[178:181], v[34:37]
	v_mfma_f32_16x16x32_bf16 v[34:37], v[158:161], v[184:187], v[34:37]
	v_mfma_f32_16x16x32_bf16 v[2:5], v[154:157], v[170:173], v[2:5]
	v_mfma_f32_16x16x32_bf16 v[2:5], v[158:161], v[174:177], v[2:5]
	v_mfma_f32_16x16x32_bf16 v[6:9], v[154:157], v[162:165], v[6:9]
	v_mfma_f32_16x16x32_bf16 v[6:9], v[158:161], v[166:169], v[6:9]
	s_barrier
	s_setprio 0
	s_add_i32 s0, s0, 2
	s_add_u32 s66, s66, 0x100
	s_addc_u32 s67, s67, 0
	s_cmp_gt_u32 s0, 29
	s_mov_b64 s[12:13], s[96:97]
	s_cbranch_scc0 .LBB0_1327
	s_branch .Lpeel_1327_x
.LBB0_1327:
	s_add_u32 s96, s12, 0x100
	s_addc_u32 s97, s13, 0
	s_add_i32 s51, 0, 0x10000
	s_cmp_eq_u32 s0, 28
	s_cselect_b32 s41, s59, s97
	s_cselect_b32 s40, s64, s96
	s_cselect_b32 vcc_hi, s65, s67
	s_cselect_b32 vcc_lo, s87, s66
	s_add_i32 s19, 0, 0x14000
	ds_read_b128 v[66:69], v200
	ds_read_b128 v[70:73], v200 offset:1024
	ds_read_b128 v[82:85], v200 offset:2048
	ds_read_b128 v[142:145], v200 offset:3072
	ds_read_b128 v[146:149], v200 offset:16384
	ds_read_b128 v[150:153], v200 offset:17408
	ds_read_b128 v[154:157], v200 offset:18432
	ds_read_b128 v[158:161], v200 offset:19456
	s_add_i32 m0, s95, 0xc000
	ds_read_b128 v[162:165], v219
	ds_read_b128 v[166:169], v219 offset:1024
	ds_read_b128 v[170:173], v219 offset:2048
	ds_read_b128 v[174:177], v219 offset:3072
	ds_read_b128 v[178:181], v219 offset:4096
	ds_read_b128 v[184:187], v219 offset:5120
	ds_read_b128 v[220:223], v219 offset:6144
	ds_read_b128 v[224:227], v219 offset:7168
	global_load_lds_dwordx4 v196, s[12:13]
	s_add_i32 m0, s95, 0xe000
	s_nop 0
	global_load_lds_dwordx4 v198, s[12:13]
	s_waitcnt vmcnt(8)
	s_waitcnt lgkmcnt(0)
	.p2align 3
	s_setprio 1
	s_barrier
; #define PG8_STAGE(bufoff, gbase, voff) do { _Pragma("unroll") for (int _i = 0; _i < 2; ++_i) \
;         __builtin_amdgcn_global_load_lds((const unsigned*)((const char*)(gbase) + (voff)[_i]), (PG8_LAS unsigned*)(lds + (bufoff) + ldsw + _i * 8192), 16, 0, 0); } while (0)
; #define PG8_LDA(dst, b, h) do { _Pragma("unroll") for (int m = 0; m < 4; ++m) _Pragma("unroll") for (int k = 0; k < 2; ++k) dst[m][k] = *(const PG8_LAS bf16x8*)(lds + PG8_SA(b, h) + aoff + m * 2048 + k * 1024); } while (0)
; #define PG8_LDB(dst, b, h) do { _Pragma("unroll") for (int n = 0; n < 2; ++n) _Pragma("unroll") for (int k = 0; k < 2; ++k) dst[n][k] = *(const PG8_LAS bf16x8*)(lds + PG8_SB(b, h) + boff + n * 2048 + k * 1024); } while (0)
; #define PG8_WAIT_V(n) asm volatile("s_waitcnt vmcnt(" #n ")" ::: "memory")
; #define PG8_WAIT_L(n) asm volatile("s_waitcnt lgkmcnt(" #n ")" ::: "memory")
; #define PG8_WAIT_V_SEL(sel) asm volatile("s_cmp_eq_u32 %0, 0\n\ts_cbranch_scc1 .Lw8_%=\n\ts_waitcnt vmcnt(22)\n\ts_branch .Lwd_%=\n.Lw8_%=:\n\ts_waitcnt vmcnt(8)\n.Lwd_%=:" :: "s"(sel) : "memory", "scc")
; #define PG8_BAR __builtin_amdgcn_s_barrier()
; #define PG8_SCHED __builtin_amdgcn_sched_barrier(0)
;     ...
;             PG8_LDB(B0, 0, 0); PG8_LDB(B1, 0, 1); PG8_SCHED; PG8_LDA(At, 0, 0); PG8_STAGE(PG8_SA(1, 1), a1 + hstep, voffA);
;             PG8_WAIT_V_SEL(relax);
;             PG8_WAIT_L(0); PG8_BAR; PG8_MMA(0, 0, At, B0); PG8_MMA(0, 1, At, B1); PG8_BAR; PG8_SCHED;
;             PG8_LDA(At, 0, 1); PG8_STAGE(PG8_SB(0, 0), b2, voffB); PG8_STAGE(PG8_SB(0, 1), b2 + hstep, voffB); PG8_STAGE(PG8_SA(0, 0), a2, voffA);
;             PG8_WAIT_V_SEL(relax);
;             PG8_WAIT_L(0); PG8_BAR; PG8_MMA(1, 0, At, B0); PG8_MMA(1, 1, At, B1); PG8_BAR; PG8_SCHED;
;             PG8_LDB(B0, 1, 0); PG8_LDB(B1, 1, 1); PG8_SCHED; PG8_LDA(At, 1, 0); PG8_STAGE(PG8_SA(0, 1), a2 + hstep, voffA);
;             PG8_WAIT_V(8); PG8_WAIT_L(0); PG8_BAR; PG8_MMA(0, 0, At, B0); PG8_MMA(0, 1, At, B1); PG8_BAR; PG8_SCHED;
	v_mfma_f32_16x16x32_bf16 v[114:117], v[66:69], v[162:165], v[114:117]
	v_mfma_f32_16x16x32_bf16 v[114:117], v[70:73], v[166:169], v[114:117]
	v_mfma_f32_16x16x32_bf16 v[110:113], v[66:69], v[170:173], v[110:113]
	v_mfma_f32_16x16x32_bf16 v[110:113], v[70:73], v[174:177], v[110:113]
	v_mfma_f32_16x16x32_bf16 v[78:81], v[66:69], v[178:181], v[78:81]
	v_mfma_f32_16x16x32_bf16 v[78:81], v[70:73], v[184:187], v[78:81]
	v_mfma_f32_16x16x32_bf16 v[74:77], v[66:69], v[220:223], v[74:77]
	v_mfma_f32_16x16x32_bf16 v[74:77], v[70:73], v[224:227], v[74:77]
	v_mfma_f32_16x16x32_bf16 v[134:137], v[82:85], v[220:223], v[134:137]
	v_mfma_f32_16x16x32_bf16 v[134:137], v[142:145], v[224:227], v[134:137]
	v_mfma_f32_16x16x32_bf16 v[138:141], v[82:85], v[178:181], v[138:141]
	v_mfma_f32_16x16x32_bf16 v[138:141], v[142:145], v[184:187], v[138:141]
	v_mfma_f32_16x16x32_bf16 v[102:105], v[82:85], v[170:173], v[102:105]
	v_mfma_f32_16x16x32_bf16 v[102:105], v[142:145], v[174:177], v[102:105]
	v_mfma_f32_16x16x32_bf16 v[106:109], v[82:85], v[162:165], v[106:109]
	v_mfma_f32_16x16x32_bf16 v[106:109], v[142:145], v[166:169], v[106:109]
	v_mfma_f32_16x16x32_bf16 v[98:101], v[146:149], v[162:165], v[98:101]
	v_mfma_f32_16x16x32_bf16 v[98:101], v[150:153], v[166:169], v[98:101]
	v_mfma_f32_16x16x32_bf16 v[94:97], v[146:149], v[170:173], v[94:97]
	v_mfma_f32_16x16x32_bf16 v[94:97], v[150:153], v[174:177], v[94:97]
	v_mfma_f32_16x16x32_bf16 v[130:133], v[146:149], v[178:181], v[130:133]
	v_mfma_f32_16x16x32_bf16 v[130:133], v[150:153], v[184:187], v[130:133]
	v_mfma_f32_16x16x32_bf16 v[126:129], v[146:149], v[220:223], v[126:129]
	v_mfma_f32_16x16x32_bf16 v[126:129], v[150:153], v[224:227], v[126:129]
	v_mfma_f32_16x16x32_bf16 v[118:121], v[154:157], v[220:223], v[118:121]
	v_mfma_f32_16x16x32_bf16 v[118:121], v[158:161], v[224:227], v[118:121]
	v_mfma_f32_16x16x32_bf16 v[122:125], v[154:157], v[178:181], v[122:125]
	v_mfma_f32_16x16x32_bf16 v[122:125], v[158:161], v[184:187], v[122:125]
	v_mfma_f32_16x16x32_bf16 v[86:89], v[154:157], v[170:173], v[86:89]
	v_mfma_f32_16x16x32_bf16 v[86:89], v[158:161], v[174:177], v[86:89]
	v_mfma_f32_16x16x32_bf16 v[90:93], v[154:157], v[162:165], v[90:93]
	v_mfma_f32_16x16x32_bf16 v[90:93], v[158:161], v[166:169], v[90:93]
	s_barrier
	s_setprio 0
	s_add_i32 s12, s51, s37
	s_mov_b32 m0, s12
	ds_read_b128 v[162:165], v219 offset:16384
	ds_read_b128 v[166:169], v219 offset:17408
	ds_read_b128 v[170:173], v219 offset:18432
	ds_read_b128 v[174:177], v219 offset:19456
	ds_read_b128 v[178:181], v219 offset:20480
	ds_read_b128 v[184:187], v219 offset:21504
	ds_read_b128 v[220:223], v219 offset:22528
	ds_read_b128 v[224:227], v219 offset:23552
	global_load_lds_dwordx4 v182, vcc
	s_add_i32 m0, s12, 0x2000
	s_add_u32 s12, vcc_lo, 0x80000
	s_addc_u32 s13, vcc_hi, 0
	s_add_i32 s19, s19, s37
	global_load_lds_dwordx4 v192, vcc
	s_mov_b32 m0, s19
	s_nop 0
	global_load_lds_dwordx4 v182, s[12:13]
	s_add_i32 m0, s19, 0x2000
	s_nop 0
	global_load_lds_dwordx4 v192, s[12:13]
	s_mov_b32 m0, s95
	s_nop 0
	global_load_lds_dwordx4 v188, s[40:41]
	s_mov_b32 m0, s20
	s_nop 0
	global_load_lds_dwordx4 v190, s[40:41]
	s_waitcnt vmcnt(8)
	s_waitcnt lgkmcnt(0)
	.p2align 3
	s_setprio 1
	s_barrier
	v_mfma_f32_16x16x32_bf16 v[30:33], v[66:69], v[162:165], v[30:33]
	v_mfma_f32_16x16x32_bf16 v[30:33], v[70:73], v[166:169], v[30:33]
	v_mfma_f32_16x16x32_bf16 v[26:29], v[66:69], v[170:173], v[26:29]
	v_mfma_f32_16x16x32_bf16 v[26:29], v[70:73], v[174:177], v[26:29]
	v_mfma_f32_16x16x32_bf16 v[62:65], v[66:69], v[178:181], v[62:65]
	v_mfma_f32_16x16x32_bf16 v[62:65], v[70:73], v[184:187], v[62:65]
	v_mfma_f32_16x16x32_bf16 v[58:61], v[66:69], v[220:223], v[58:61]
	v_mfma_f32_16x16x32_bf16 v[58:61], v[70:73], v[224:227], v[58:61]
	v_mfma_f32_16x16x32_bf16 v[50:53], v[82:85], v[220:223], v[50:53]
	v_mfma_f32_16x16x32_bf16 v[50:53], v[142:145], v[224:227], v[50:53]
	v_mfma_f32_16x16x32_bf16 v[54:57], v[82:85], v[178:181], v[54:57]
	v_mfma_f32_16x16x32_bf16 v[54:57], v[142:145], v[184:187], v[54:57]
	v_mfma_f32_16x16x32_bf16 v[18:21], v[82:85], v[170:173], v[18:21]
	v_mfma_f32_16x16x32_bf16 v[18:21], v[142:145], v[174:177], v[18:21]
	v_mfma_f32_16x16x32_bf16 v[22:25], v[82:85], v[162:165], v[22:25]
	v_mfma_f32_16x16x32_bf16 v[22:25], v[142:145], v[166:169], v[22:25]
	v_mfma_f32_16x16x32_bf16 v[14:17], v[146:149], v[162:165], v[14:17]
	v_mfma_f32_16x16x32_bf16 v[14:17], v[150:153], v[166:169], v[14:17]
	v_mfma_f32_16x16x32_bf16 v[10:13], v[146:149], v[170:173], v[10:13]
	v_mfma_f32_16x16x32_bf16 v[10:13], v[150:153], v[174:177], v[10:13]
	v_mfma_f32_16x16x32_bf16 v[46:49], v[146:149], v[178:181], v[46:49]
	v_mfma_f32_16x16x32_bf16 v[46:49], v[150:153], v[184:187], v[46:49]
	v_mfma_f32_16x16x32_bf16 v[38:41], v[146:149], v[220:223], v[38:41]
	v_mfma_f32_16x16x32_bf16 v[38:41], v[150:153], v[224:227], v[38:41]
	v_mfma_f32_16x16x32_bf16 v[42:45], v[154:157], v[220:223], v[42:45]
	v_mfma_f32_16x16x32_bf16 v[42:45], v[158:161], v[224:227], v[42:45]
	v_mfma_f32_16x16x32_bf16 v[34:37], v[154:157], v[178:181], v[34:37]
	v_mfma_f32_16x16x32_bf16 v[34:37], v[158:161], v[184:187], v[34:37]
	v_mfma_f32_16x16x32_bf16 v[2:5], v[154:157], v[170:173], v[2:5]
	v_mfma_f32_16x16x32_bf16 v[2:5], v[158:161], v[174:177], v[2:5]
	v_mfma_f32_16x16x32_bf16 v[6:9], v[154:157], v[162:165], v[6:9]
	v_mfma_f32_16x16x32_bf16 v[6:9], v[158:161], v[166:169], v[6:9]
	s_barrier
; #define PG8_STAGE(bufoff, gbase, voff) do { _Pragma("unroll") for (int _i = 0; _i < 2; ++_i) \
;         __builtin_amdgcn_global_load_lds((const unsigned*)((const char*)(gbase) + (voff)[_i]), (PG8_LAS unsigned*)(lds + (bufoff) + ldsw + _i * 8192), 16, 0, 0); } while (0)
; #define PG8_LDA(dst, b, h) do { _Pragma("unroll") for (int m = 0; m < 4; ++m) _Pragma("unroll") for (int k = 0; k < 2; ++k) dst[m][k] = *(const PG8_LAS bf16x8*)(lds + PG8_SA(b, h) + aoff + m * 2048 + k * 1024); } while (0)
; #define PG8_LDB(dst, b, h) do { _Pragma("unroll") for (int n = 0; n < 2; ++n) _Pragma("unroll") for (int k = 0; k < 2; ++k) dst[n][k] = *(const PG8_LAS bf16x8*)(lds + PG8_SB(b, h) + boff + n * 2048 + k * 1024); } while (0)
; #define PG8_WAIT_V(n) asm volatile("s_waitcnt vmcnt(" #n ")" ::: "memory")
; #define PG8_WAIT_L(n) asm volatile("s_waitcnt lgkmcnt(" #n ")" ::: "memory")
; #define PG8_BAR __builtin_amdgcn_s_barrier()
; #define PG8_SCHED __builtin_amdgcn_sched_barrier(0)
;     ...
;             PG8_LDB(B0, 1, 0); PG8_LDB(B1, 1, 1); PG8_SCHED; PG8_LDA(At, 1, 0); PG8_STAGE(PG8_SA(0, 1), a2 + hstep, voffA);
;             PG8_WAIT_V(8); PG8_WAIT_L(0); PG8_BAR; PG8_MMA(0, 0, At, B0); PG8_MMA(0, 1, At, B1); PG8_BAR; PG8_SCHED;
;             PG8_LDA(At, 1, 1); PG8_STAGE(PG8_SB(1, 0), b3, voffB); PG8_STAGE(PG8_SB(1, 1), b3 + hstep, voffB); PG8_STAGE(PG8_SA(1, 0), a3, voffA);
;             PG8_WAIT_V(8); PG8_WAIT_L(0); PG8_BAR; PG8_MMA(1, 0, At, B0); PG8_MMA(1, 1, At, B1); PG8_BAR; PG8_SCHED;
	s_setprio 0
	s_add_i32 s19, 0, 0x18000
	s_add_i32 s51, 0, 0x1c000
	ds_read_b128 v[66:69], v200 offset:32768
	ds_read_b128 v[70:73], v200 offset:33792
	ds_read_b128 v[82:85], v200 offset:34816
	ds_read_b128 v[142:145], v200 offset:35840
	ds_read_b128 v[146:149], v200 offset:49152
	ds_read_b128 v[150:153], v200 offset:50176
	ds_read_b128 v[154:157], v200 offset:51200
	ds_read_b128 v[158:161], v200 offset:52224
	s_add_u32 s12, s40, 0x80000
	s_addc_u32 s13, s41, 0
	s_mov_b32 m0, s44
	ds_read_b128 v[162:165], v219 offset:32768
	ds_read_b128 v[166:169], v219 offset:33792
	ds_read_b128 v[170:173], v219 offset:34816
	ds_read_b128 v[174:177], v219 offset:35840
	ds_read_b128 v[178:181], v219 offset:36864
	ds_read_b128 v[184:187], v219 offset:37888
	ds_read_b128 v[220:223], v219 offset:38912
	ds_read_b128 v[224:227], v219 offset:39936
	global_load_lds_dwordx4 v188, s[12:13]
	s_mov_b32 m0, s46
	s_nop 0
	global_load_lds_dwordx4 v190, s[12:13]
	s_waitcnt vmcnt(8)
	s_waitcnt lgkmcnt(0)
	.p2align 3
	s_setprio 1
	s_barrier
	v_mfma_f32_16x16x32_bf16 v[114:117], v[66:69], v[162:165], v[114:117]
	v_mfma_f32_16x16x32_bf16 v[114:117], v[70:73], v[166:169], v[114:117]
	v_mfma_f32_16x16x32_bf16 v[110:113], v[66:69], v[170:173], v[110:113]
	v_mfma_f32_16x16x32_bf16 v[110:113], v[70:73], v[174:177], v[110:113]
	v_mfma_f32_16x16x32_bf16 v[78:81], v[66:69], v[178:181], v[78:81]
	v_mfma_f32_16x16x32_bf16 v[78:81], v[70:73], v[184:187], v[78:81]
	v_mfma_f32_16x16x32_bf16 v[74:77], v[66:69], v[220:223], v[74:77]
	v_mfma_f32_16x16x32_bf16 v[74:77], v[70:73], v[224:227], v[74:77]
	v_mfma_f32_16x16x32_bf16 v[134:137], v[82:85], v[220:223], v[134:137]
	v_mfma_f32_16x16x32_bf16 v[134:137], v[142:145], v[224:227], v[134:137]
	v_mfma_f32_16x16x32_bf16 v[138:141], v[82:85], v[178:181], v[138:141]
	v_mfma_f32_16x16x32_bf16 v[138:141], v[142:145], v[184:187], v[138:141]
	v_mfma_f32_16x16x32_bf16 v[102:105], v[82:85], v[170:173], v[102:105]
	v_mfma_f32_16x16x32_bf16 v[102:105], v[142:145], v[174:177], v[102:105]
	v_mfma_f32_16x16x32_bf16 v[106:109], v[82:85], v[162:165], v[106:109]
	v_mfma_f32_16x16x32_bf16 v[106:109], v[142:145], v[166:169], v[106:109]
	v_mfma_f32_16x16x32_bf16 v[98:101], v[146:149], v[162:165], v[98:101]
	v_mfma_f32_16x16x32_bf16 v[98:101], v[150:153], v[166:169], v[98:101]
	v_mfma_f32_16x16x32_bf16 v[94:97], v[146:149], v[170:173], v[94:97]
	v_mfma_f32_16x16x32_bf16 v[94:97], v[150:153], v[174:177], v[94:97]
	v_mfma_f32_16x16x32_bf16 v[130:133], v[146:149], v[178:181], v[130:133]
	v_mfma_f32_16x16x32_bf16 v[130:133], v[150:153], v[184:187], v[130:133]
	v_mfma_f32_16x16x32_bf16 v[126:129], v[146:149], v[220:223], v[126:129]
	v_mfma_f32_16x16x32_bf16 v[126:129], v[150:153], v[224:227], v[126:129]
	v_mfma_f32_16x16x32_bf16 v[118:121], v[154:157], v[220:223], v[118:121]
	v_mfma_f32_16x16x32_bf16 v[118:121], v[158:161], v[224:227], v[118:121]
	v_mfma_f32_16x16x32_bf16 v[122:125], v[154:157], v[178:181], v[122:125]
	v_mfma_f32_16x16x32_bf16 v[122:125], v[158:161], v[184:187], v[122:125]
	v_mfma_f32_16x16x32_bf16 v[86:89], v[154:157], v[170:173], v[86:89]
	v_mfma_f32_16x16x32_bf16 v[86:89], v[158:161], v[174:177], v[86:89]
	v_mfma_f32_16x16x32_bf16 v[90:93], v[154:157], v[162:165], v[90:93]
	v_mfma_f32_16x16x32_bf16 v[90:93], v[158:161], v[166:169], v[90:93]
	s_barrier
	s_setprio 0
	s_add_i32 s12, s19, s37
	s_mov_b32 m0, s12
	ds_read_b128 v[162:165], v219 offset:49152
	ds_read_b128 v[166:169], v219 offset:50176
	ds_read_b128 v[170:173], v219 offset:51200
	ds_read_b128 v[174:177], v219 offset:52224
	ds_read_b128 v[178:181], v219 offset:53248
	ds_read_b128 v[184:187], v219 offset:54272
	ds_read_b128 v[220:223], v219 offset:55296
	ds_read_b128 v[224:227], v219 offset:56320
	s_add_u32 s100, vcc_lo, 0x80
	s_addc_u32 s101, vcc_hi, 0
	global_load_lds_dwordx4 v182, s[100:101]
	s_add_i32 m0, s12, 0x2000
	s_add_u32 s12, vcc_lo, 0x80080
	s_addc_u32 s13, vcc_hi, 0
	s_add_i32 s19, s51, s37
	global_load_lds_dwordx4 v192, s[100:101]
	s_mov_b32 m0, s19
	s_nop 0
	global_load_lds_dwordx4 v182, s[12:13]
	s_add_i32 m0, s19, 0x2000
	s_nop 0
	global_load_lds_dwordx4 v192, s[12:13]
	s_mov_b32 m0, s45
	s_nop 0
	s_add_u32 s100, s40, 0x80
	s_addc_u32 s101, s41, 0
	global_load_lds_dwordx4 v188, s[100:101]
	s_mov_b32 m0, s24
	s_nop 0
	global_load_lds_dwordx4 v190, s[100:101]
	s_waitcnt vmcnt(8)
	s_waitcnt lgkmcnt(0)
	.p2align 3
	s_setprio 1
	s_barrier
	v_mfma_f32_16x16x32_bf16 v[30:33], v[66:69], v[162:165], v[30:33]
	v_mfma_f32_16x16x32_bf16 v[30:33], v[70:73], v[166:169], v[30:33]
	v_mfma_f32_16x16x32_bf16 v[26:29], v[66:69], v[170:173], v[26:29]
	v_mfma_f32_16x16x32_bf16 v[26:29], v[70:73], v[174:177], v[26:29]
	v_mfma_f32_16x16x32_bf16 v[62:65], v[66:69], v[178:181], v[62:65]
	v_mfma_f32_16x16x32_bf16 v[62:65], v[70:73], v[184:187], v[62:65]
	v_mfma_f32_16x16x32_bf16 v[58:61], v[66:69], v[220:223], v[58:61]
	v_mfma_f32_16x16x32_bf16 v[58:61], v[70:73], v[224:227], v[58:61]
	v_mfma_f32_16x16x32_bf16 v[50:53], v[82:85], v[220:223], v[50:53]
	v_mfma_f32_16x16x32_bf16 v[50:53], v[142:145], v[224:227], v[50:53]
	v_mfma_f32_16x16x32_bf16 v[54:57], v[82:85], v[178:181], v[54:57]
	v_mfma_f32_16x16x32_bf16 v[54:57], v[142:145], v[184:187], v[54:57]
	v_mfma_f32_16x16x32_bf16 v[18:21], v[82:85], v[170:173], v[18:21]
	v_mfma_f32_16x16x32_bf16 v[18:21], v[142:145], v[174:177], v[18:21]
	v_mfma_f32_16x16x32_bf16 v[22:25], v[82:85], v[162:165], v[22:25]
	v_mfma_f32_16x16x32_bf16 v[22:25], v[142:145], v[166:169], v[22:25]
	v_mfma_f32_16x16x32_bf16 v[14:17], v[146:149], v[162:165], v[14:17]
	v_mfma_f32_16x16x32_bf16 v[14:17], v[150:153], v[166:169], v[14:17]
	v_mfma_f32_16x16x32_bf16 v[10:13], v[146:149], v[170:173], v[10:13]
	v_mfma_f32_16x16x32_bf16 v[10:13], v[150:153], v[174:177], v[10:13]
	v_mfma_f32_16x16x32_bf16 v[46:49], v[146:149], v[178:181], v[46:49]
	v_mfma_f32_16x16x32_bf16 v[46:49], v[150:153], v[184:187], v[46:49]
	v_mfma_f32_16x16x32_bf16 v[38:41], v[146:149], v[220:223], v[38:41]
	v_mfma_f32_16x16x32_bf16 v[38:41], v[150:153], v[224:227], v[38:41]
	v_mfma_f32_16x16x32_bf16 v[42:45], v[154:157], v[220:223], v[42:45]
	v_mfma_f32_16x16x32_bf16 v[42:45], v[158:161], v[224:227], v[42:45]
	v_mfma_f32_16x16x32_bf16 v[34:37], v[154:157], v[178:181], v[34:37]
	v_mfma_f32_16x16x32_bf16 v[34:37], v[158:161], v[184:187], v[34:37]
	v_mfma_f32_16x16x32_bf16 v[2:5], v[154:157], v[170:173], v[2:5]
	v_mfma_f32_16x16x32_bf16 v[2:5], v[158:161], v[174:177], v[2:5]
	v_mfma_f32_16x16x32_bf16 v[6:9], v[154:157], v[162:165], v[6:9]
	v_mfma_f32_16x16x32_bf16 v[6:9], v[158:161], v[166:169], v[6:9]
	s_barrier
	s_setprio 0
	s_add_i32 s0, s0, 2
	s_add_u32 s66, s66, 0x100
	s_addc_u32 s67, s67, 0
	s_cmp_gt_u32 s0, 29
	s_mov_b64 s[12:13], s[96:97]
	s_cbranch_scc0 .LBB0_1327
.Lpeel_1327_x:
	s_branch .Lrlx_f1_x
.Lrlx_f1_0:
	s_waitcnt vmcnt(22)
	s_branch .Lrlx_f1_0_b

;     __host__ __device__ bool next(int i, Unit& u) const { const long L = (long)i * G + c; if (L >= lim) return false; unit_of((int)L, u); return true; }
;     __device__ __forceinline__ bool next(int i, Unit& v) const { if (i != 0) return false; v = u; return true; }
; #define PG8_STAGE(bufoff, gbase, voff) do { _Pragma("unroll") for (int _i = 0; _i < 2; ++_i) \
;         __builtin_amdgcn_global_load_lds((const unsigned*)((const char*)(gbase) + (voff)[_i]), (PG8_LAS unsigned*)(lds + (bufoff) + ldsw + _i * 8192), 16, 0, 0); } while (0)
;     ...
;         const bool has_next = S.next(ui + 1, nxt);
;         if constexpr (TP == 3) { if (ui > 0) tp_acc += __builtin_amdgcn_s_memrealtime() - tp3; }
;         const char* nA = has_next ? (const char*)g.A + (size_t)nxt.pm * tstep : cA; const char* nB = has_next ? (const char*)g.Bt + (size_t)nxt.pn * tstep : cB;
;         for (int t = 0; t < nt * KREP; t += 2) {
;             const bool last = (t == nt * KREP - 2);
;             const int t1w = KREP > 1 ? ((t + 1) & (nt - 1)) : t + 1, t2w = KREP > 1 ? ((t + 2) & (nt - 1)) : t + 2;
;             const char* a1 = cA + (size_t)t1w * kstep;
;             const char* a2 = last ? nA : cA + (size_t)t2w * kstep; const char* b2 = last ? nB : cB + (size_t)t2w * kstep;
;             const char* a3 = a2 + kstep; const char* b3 = b2 + kstep;
;             if (last && has_next) S.a_ready(nxt);
;             const int relax = __builtin_amdgcn_readfirstlane((MK_RELAXW && t == 0 && ui > 0) ? 1 : 0);
;             if constexpr (SP2) {
;             PG8_LDB(B0, 0, 0); PG8_LDB(B1, 0, 1); PG8_SCHED; PG8_LDA(At, 0, 0); PG8_STAGE(PG8_SA(1, 1), a1 + hstep, voffA);
;             PG8_WAIT_V_SEL(relax);
;             PG8_WAIT_L(0); PG8_BAR; PG8_MMA(0, 0, At, B0); PG8_MMA(0, 1, At, B1); PG8_BAR; PG8_SCHED;
;             PG8_LDA(At, 0, 1); PG8_STAGE(PG8_SB(0, 0), b2, voffB); PG8_STAGE(PG8_SB(0, 1), b2 + hstep, voffB); PG8_STAGE(PG8_SA(0, 0), a2, voffA);
;             PG8_WAIT_V_SEL(relax);
;             PG8_WAIT_L(0); PG8_BAR; PG8_MMA(1, 0, At, B0); PG8_MMA(1, 1, At, B1); PG8_BAR; PG8_SCHED;
;     ...
; #pragma unroll
;         for (int a = 0; a < 2; ++a)
; #pragma unroll
;             for (int b = 0; b < 2; ++b)
; #pragma unroll
;                 for (int m = 0; m < 4; ++m)
; #pragma unroll
;                     for (int n = 0; n < 2; ++n) acc[a][b][m][n] = (f32x4){0.f, 0.f, 0.f, 0.f};
.LBB0_1647:
	s_add_u32 s37, s10, 0x100
	s_addc_u32 s44, s11, 0
	s_mov_b32 s45, -2
	s_waitcnt lgkmcnt(0)
	v_add_u32_e32 v206, 0x10000, v243
	s_add_u32 s10, s8, 0x100
	s_addc_u32 s11, s9, 0
	s_add_i32 s46, 0, 0x10000
	s_cmpk_eq_i32 s45, 0x52
	s_cselect_b32 s41, s1, s11
	s_cselect_b32 s40, s0, s10
	s_cselect_b32 s81, s79, s44
	s_cselect_b32 s80, s78, s37
	s_add_i32 s47, 0, 0x14000
	ds_read_b128 v[58:61], v206
	ds_read_b128 v[62:65], v206 offset:1024
	ds_read_b128 v[74:77], v206 offset:2048
	ds_read_b128 v[78:81], v206 offset:3072
	ds_read_b128 v[130:133], v206 offset:16384
	ds_read_b128 v[142:145], v206 offset:17408
	ds_read_b128 v[154:157], v206 offset:18432
	ds_read_b128 v[158:161], v206 offset:19456
	s_add_i32 m0, s91, 0xc000
	ds_read_b128 v[162:165], v246
	ds_read_b128 v[166:169], v246 offset:1024
	ds_read_b128 v[170:173], v246 offset:2048
	ds_read_b128 v[174:177], v246 offset:3072
	ds_read_b128 v[184:187], v246 offset:4096
	ds_read_b128 v[194:197], v246 offset:5120
	ds_read_b128 v[198:201], v246 offset:6144
	ds_read_b128 v[202:205], v246 offset:7168
	global_load_lds_dwordx4 v190, s[8:9]
	s_add_i32 m0, s91, 0xe000
	s_nop 0
	global_load_lds_dwordx4 v192, s[8:9]
	s_cmp_lg_u32 s35, 0
	s_cbranch_scc1 .Lrlx_f2_0
	s_waitcnt vmcnt(8)
.Lrlx_f2_0_b:
	s_waitcnt lgkmcnt(0)
	.p2align 3
	s_setprio 1
	s_barrier
	v_mfma_f32_16x16x32_bf16 v[150:153], v[58:61], v[162:165], 0
	v_mfma_f32_16x16x32_bf16 v[150:153], v[62:65], v[166:169], v[150:153]
	v_mfma_f32_16x16x32_bf16 v[126:129], v[58:61], v[170:173], 0
	v_mfma_f32_16x16x32_bf16 v[126:129], v[62:65], v[174:177], v[126:129]
	v_mfma_f32_16x16x32_bf16 v[110:113], v[58:61], v[184:187], 0
	v_mfma_f32_16x16x32_bf16 v[110:113], v[62:65], v[194:197], v[110:113]
	v_mfma_f32_16x16x32_bf16 v[94:97], v[58:61], v[198:201], 0
	v_mfma_f32_16x16x32_bf16 v[94:97], v[62:65], v[202:205], v[94:97]
	v_mfma_f32_16x16x32_bf16 v[90:93], v[74:77], v[198:201], 0
	v_mfma_f32_16x16x32_bf16 v[90:93], v[78:81], v[202:205], v[90:93]
	v_mfma_f32_16x16x32_bf16 v[106:109], v[74:77], v[184:187], 0
	v_mfma_f32_16x16x32_bf16 v[106:109], v[78:81], v[194:197], v[106:109]
	v_mfma_f32_16x16x32_bf16 v[122:125], v[74:77], v[170:173], 0
	v_mfma_f32_16x16x32_bf16 v[122:125], v[78:81], v[174:177], v[122:125]
	v_mfma_f32_16x16x32_bf16 v[146:149], v[74:77], v[162:165], 0
	v_mfma_f32_16x16x32_bf16 v[146:149], v[78:81], v[166:169], v[146:149]
	v_mfma_f32_16x16x32_bf16 v[138:141], v[130:133], v[162:165], 0
	v_mfma_f32_16x16x32_bf16 v[138:141], v[142:145], v[166:169], v[138:141]
	v_mfma_f32_16x16x32_bf16 v[118:121], v[130:133], v[170:173], 0
	v_mfma_f32_16x16x32_bf16 v[118:121], v[142:145], v[174:177], v[118:121]
	v_mfma_f32_16x16x32_bf16 v[102:105], v[130:133], v[184:187], 0
	v_mfma_f32_16x16x32_bf16 v[102:105], v[142:145], v[194:197], v[102:105]
	v_mfma_f32_16x16x32_bf16 v[86:89], v[130:133], v[198:201], 0
	v_mfma_f32_16x16x32_bf16 v[86:89], v[142:145], v[202:205], v[86:89]
	v_mfma_f32_16x16x32_bf16 v[82:85], v[154:157], v[198:201], 0
	v_mfma_f32_16x16x32_bf16 v[82:85], v[158:161], v[202:205], v[82:85]
	v_mfma_f32_16x16x32_bf16 v[98:101], v[154:157], v[184:187], 0
	v_mfma_f32_16x16x32_bf16 v[98:101], v[158:161], v[194:197], v[98:101]
	v_mfma_f32_16x16x32_bf16 v[114:117], v[154:157], v[170:173], 0
	v_mfma_f32_16x16x32_bf16 v[114:117], v[158:161], v[174:177], v[114:117]
	v_mfma_f32_16x16x32_bf16 v[134:137], v[154:157], v[162:165], 0
	v_mfma_f32_16x16x32_bf16 v[134:137], v[158:161], v[166:169], v[134:137]
	s_barrier
	s_setprio 0
	s_add_i32 s8, s46, s90
	s_mov_b32 m0, s8
	ds_read_b128 v[162:165], v246 offset:16384
	ds_read_b128 v[166:169], v246 offset:17408
	ds_read_b128 v[170:173], v246 offset:18432
	ds_read_b128 v[174:177], v246 offset:19456
	ds_read_b128 v[184:187], v246 offset:20480
	ds_read_b128 v[194:197], v246 offset:21504
	ds_read_b128 v[198:201], v246 offset:22528
	ds_read_b128 v[202:205], v246 offset:23552
	global_load_lds_dwordx4 v182, s[80:81]
	s_add_i32 m0, s8, 0x2000
	s_add_u32 s8, s80, 0x158000
	s_addc_u32 s9, s81, 0
	s_add_i32 s46, s47, s90
	global_load_lds_dwordx4 v188, s[80:81]
	s_mov_b32 m0, s46
	s_nop 0
	global_load_lds_dwordx4 v182, s[8:9]
	s_add_i32 m0, s46, 0x2000
	s_nop 0
	global_load_lds_dwordx4 v188, s[8:9]
	s_mov_b32 m0, s91
	s_nop 0
	global_load_lds_dwordx4 v178, s[40:41]
	s_mov_b32 m0, s92
	s_nop 0
	global_load_lds_dwordx4 v180, s[40:41]
	s_cmp_lg_u32 s35, 0
	s_cbranch_scc1 .Lrlx_f2_1
	s_waitcnt vmcnt(8)
; #define PG8_STAGE(bufoff, gbase, voff) do { _Pragma("unroll") for (int _i = 0; _i < 2; ++_i) \
;         __builtin_amdgcn_global_load_lds((const unsigned*)((const char*)(gbase) + (voff)[_i]), (PG8_LAS unsigned*)(lds + (bufoff) + ldsw + _i * 8192), 16, 0, 0); } while (0)
; #define PG8_LDA(dst, b, h) do { _Pragma("unroll") for (int m = 0; m < 4; ++m) _Pragma("unroll") for (int k = 0; k < 2; ++k) dst[m][k] = *(const PG8_LAS bf16x8*)(lds + PG8_SA(b, h) + aoff + m * 2048 + k * 1024); } while (0)
; #define PG8_LDB(dst, b, h) do { _Pragma("unroll") for (int n = 0; n < 2; ++n) _Pragma("unroll") for (int k = 0; k < 2; ++k) dst[n][k] = *(const PG8_LAS bf16x8*)(lds + PG8_SB(b, h) + boff + n * 2048 + k * 1024); } while (0)
; #define PG8_WAIT_V(n) asm volatile("s_waitcnt vmcnt(" #n ")" ::: "memory")
; #define PG8_WAIT_L(n) asm volatile("s_waitcnt lgkmcnt(" #n ")" ::: "memory")
; #define PG8_WAIT_V_SEL(sel) asm volatile("s_cmp_eq_u32 %0, 0\n\ts_cbranch_scc1 .Lw8_%=\n\ts_waitcnt vmcnt(22)\n\ts_branch .Lwd_%=\n.Lw8_%=:\n\ts_waitcnt vmcnt(8)\n.Lwd_%=:" :: "s"(sel) : "memory", "scc")
; #define PG8_BAR __builtin_amdgcn_s_barrier()
; #define PG8_SCHED __builtin_amdgcn_sched_barrier(0)
;     ...
;             PG8_WAIT_L(0); PG8_BAR; PG8_MMA(0, 0, At, B0); PG8_MMA(0, 1, At, B1); PG8_BAR; PG8_SCHED;
;             PG8_LDA(At, 0, 1); PG8_STAGE(PG8_SB(0, 0), b2, voffB); PG8_STAGE(PG8_SB(0, 1), b2 + hstep, voffB); PG8_STAGE(PG8_SA(0, 0), a2, voffA);
;             PG8_WAIT_V_SEL(relax);
;             PG8_WAIT_L(0); PG8_BAR; PG8_MMA(1, 0, At, B0); PG8_MMA(1, 1, At, B1); PG8_BAR; PG8_SCHED;
;             PG8_LDB(B0, 1, 0); PG8_LDB(B1, 1, 1); PG8_SCHED; PG8_LDA(At, 1, 0); PG8_STAGE(PG8_SA(0, 1), a2 + hstep, voffA);
;             PG8_WAIT_V(8); PG8_WAIT_L(0); PG8_BAR; PG8_MMA(0, 0, At, B0); PG8_MMA(0, 1, At, B1); PG8_BAR; PG8_SCHED;
;             PG8_LDA(At, 1, 1); PG8_STAGE(PG8_SB(1, 0), b3, voffB); PG8_STAGE(PG8_SB(1, 1), b3 + hstep, voffB); PG8_STAGE(PG8_SA(1, 0), a3, voffA);
;             PG8_WAIT_V(8); PG8_WAIT_L(0); PG8_BAR; PG8_MMA(1, 0, At, B0); PG8_MMA(1, 1, At, B1); PG8_BAR; PG8_SCHED;
.Lrlx_f2_1_b:
	s_waitcnt lgkmcnt(0)
	.p2align 3
	s_setprio 1
	s_barrier
	v_mfma_f32_16x16x32_bf16 v[70:73], v[58:61], v[162:165], 0
	v_mfma_f32_16x16x32_bf16 v[70:73], v[62:65], v[166:169], v[70:73]
	v_mfma_f32_16x16x32_bf16 v[46:49], v[58:61], v[170:173], 0
	v_mfma_f32_16x16x32_bf16 v[46:49], v[62:65], v[174:177], v[46:49]
	v_mfma_f32_16x16x32_bf16 v[30:33], v[58:61], v[184:187], 0
	v_mfma_f32_16x16x32_bf16 v[30:33], v[62:65], v[194:197], v[30:33]
	v_mfma_f32_16x16x32_bf16 v[14:17], v[58:61], v[198:201], 0
	v_mfma_f32_16x16x32_bf16 v[14:17], v[62:65], v[202:205], v[14:17]
	v_mfma_f32_16x16x32_bf16 v[10:13], v[74:77], v[198:201], 0
	v_mfma_f32_16x16x32_bf16 v[10:13], v[78:81], v[202:205], v[10:13]
	v_mfma_f32_16x16x32_bf16 v[26:29], v[74:77], v[184:187], 0
	v_mfma_f32_16x16x32_bf16 v[26:29], v[78:81], v[194:197], v[26:29]
	v_mfma_f32_16x16x32_bf16 v[42:45], v[74:77], v[170:173], 0
	v_mfma_f32_16x16x32_bf16 v[42:45], v[78:81], v[174:177], v[42:45]
	v_mfma_f32_16x16x32_bf16 v[66:69], v[74:77], v[162:165], 0
	v_mfma_f32_16x16x32_bf16 v[66:69], v[78:81], v[166:169], v[66:69]
	v_mfma_f32_16x16x32_bf16 v[54:57], v[130:133], v[162:165], 0
	v_mfma_f32_16x16x32_bf16 v[54:57], v[142:145], v[166:169], v[54:57]
	v_mfma_f32_16x16x32_bf16 v[38:41], v[130:133], v[170:173], 0
	v_mfma_f32_16x16x32_bf16 v[38:41], v[142:145], v[174:177], v[38:41]
	v_mfma_f32_16x16x32_bf16 v[22:25], v[130:133], v[184:187], 0
	v_mfma_f32_16x16x32_bf16 v[22:25], v[142:145], v[194:197], v[22:25]
	v_mfma_f32_16x16x32_bf16 v[6:9], v[130:133], v[198:201], 0
	v_mfma_f32_16x16x32_bf16 v[6:9], v[142:145], v[202:205], v[6:9]
	v_mfma_f32_16x16x32_bf16 v[2:5], v[154:157], v[198:201], 0
	v_mfma_f32_16x16x32_bf16 v[2:5], v[158:161], v[202:205], v[2:5]
	v_mfma_f32_16x16x32_bf16 v[18:21], v[154:157], v[184:187], 0
	v_mfma_f32_16x16x32_bf16 v[18:21], v[158:161], v[194:197], v[18:21]
	v_mfma_f32_16x16x32_bf16 v[34:37], v[154:157], v[170:173], 0
	v_mfma_f32_16x16x32_bf16 v[34:37], v[158:161], v[174:177], v[34:37]
	v_mfma_f32_16x16x32_bf16 v[50:53], v[154:157], v[162:165], 0
	v_mfma_f32_16x16x32_bf16 v[50:53], v[158:161], v[166:169], v[50:53]
	s_barrier
	s_setprio 0
	s_add_i32 s46, 0, 0x18000
	s_add_i32 s47, 0, 0x1c000
	ds_read_b128 v[58:61], v206 offset:32768
	ds_read_b128 v[62:65], v206 offset:33792
	ds_read_b128 v[74:77], v206 offset:34816
	ds_read_b128 v[78:81], v206 offset:35840
	ds_read_b128 v[130:133], v206 offset:49152
	ds_read_b128 v[142:145], v206 offset:50176
	ds_read_b128 v[154:157], v206 offset:51200
	ds_read_b128 v[158:161], v206 offset:52224
	s_add_u32 s8, s40, 0x158000
	s_addc_u32 s9, s41, 0
	s_mov_b32 m0, s93
	ds_read_b128 v[162:165], v246 offset:32768
	ds_read_b128 v[166:169], v246 offset:33792
	ds_read_b128 v[170:173], v246 offset:34816
	ds_read_b128 v[174:177], v246 offset:35840
	ds_read_b128 v[184:187], v246 offset:36864
	ds_read_b128 v[194:197], v246 offset:37888
	ds_read_b128 v[198:201], v246 offset:38912
	ds_read_b128 v[202:205], v246 offset:39936
	global_load_lds_dwordx4 v178, s[8:9]
	s_mov_b32 m0, s94
	s_nop 0
	global_load_lds_dwordx4 v180, s[8:9]
	s_waitcnt vmcnt(8)
	s_waitcnt lgkmcnt(0)
	.p2align 3
	s_setprio 1
	s_barrier
	v_mfma_f32_16x16x32_bf16 v[150:153], v[58:61], v[162:165], v[150:153]
	v_mfma_f32_16x16x32_bf16 v[150:153], v[62:65], v[166:169], v[150:153]
	v_mfma_f32_16x16x32_bf16 v[126:129], v[58:61], v[170:173], v[126:129]
	v_mfma_f32_16x16x32_bf16 v[126:129], v[62:65], v[174:177], v[126:129]
	v_mfma_f32_16x16x32_bf16 v[110:113], v[58:61], v[184:187], v[110:113]
	v_mfma_f32_16x16x32_bf16 v[110:113], v[62:65], v[194:197], v[110:113]
	v_mfma_f32_16x16x32_bf16 v[94:97], v[58:61], v[198:201], v[94:97]
	v_mfma_f32_16x16x32_bf16 v[94:97], v[62:65], v[202:205], v[94:97]
	v_mfma_f32_16x16x32_bf16 v[90:93], v[74:77], v[198:201], v[90:93]
	v_mfma_f32_16x16x32_bf16 v[90:93], v[78:81], v[202:205], v[90:93]
	v_mfma_f32_16x16x32_bf16 v[106:109], v[74:77], v[184:187], v[106:109]
	v_mfma_f32_16x16x32_bf16 v[106:109], v[78:81], v[194:197], v[106:109]
	v_mfma_f32_16x16x32_bf16 v[122:125], v[74:77], v[170:173], v[122:125]
	v_mfma_f32_16x16x32_bf16 v[122:125], v[78:81], v[174:177], v[122:125]
	v_mfma_f32_16x16x32_bf16 v[146:149], v[74:77], v[162:165], v[146:149]
	v_mfma_f32_16x16x32_bf16 v[146:149], v[78:81], v[166:169], v[146:149]
	v_mfma_f32_16x16x32_bf16 v[138:141], v[130:133], v[162:165], v[138:141]
	v_mfma_f32_16x16x32_bf16 v[138:141], v[142:145], v[166:169], v[138:141]
	v_mfma_f32_16x16x32_bf16 v[118:121], v[130:133], v[170:173], v[118:121]
	v_mfma_f32_16x16x32_bf16 v[118:121], v[142:145], v[174:177], v[118:121]
	v_mfma_f32_16x16x32_bf16 v[102:105], v[130:133], v[184:187], v[102:105]
	v_mfma_f32_16x16x32_bf16 v[102:105], v[142:145], v[194:197], v[102:105]
	v_mfma_f32_16x16x32_bf16 v[86:89], v[130:133], v[198:201], v[86:89]
	v_mfma_f32_16x16x32_bf16 v[86:89], v[142:145], v[202:205], v[86:89]
	v_mfma_f32_16x16x32_bf16 v[82:85], v[154:157], v[198:201], v[82:85]
	v_mfma_f32_16x16x32_bf16 v[82:85], v[158:161], v[202:205], v[82:85]
	v_mfma_f32_16x16x32_bf16 v[98:101], v[154:157], v[184:187], v[98:101]
	v_mfma_f32_16x16x32_bf16 v[98:101], v[158:161], v[194:197], v[98:101]
	v_mfma_f32_16x16x32_bf16 v[114:117], v[154:157], v[170:173], v[114:117]
	v_mfma_f32_16x16x32_bf16 v[114:117], v[158:161], v[174:177], v[114:117]
	v_mfma_f32_16x16x32_bf16 v[134:137], v[154:157], v[162:165], v[134:137]
	v_mfma_f32_16x16x32_bf16 v[134:137], v[158:161], v[166:169], v[134:137]
	s_barrier
; #define PG8_STAGE(bufoff, gbase, voff) do { _Pragma("unroll") for (int _i = 0; _i < 2; ++_i) \
;         __builtin_amdgcn_global_load_lds((const unsigned*)((const char*)(gbase) + (voff)[_i]), (PG8_LAS unsigned*)(lds + (bufoff) + ldsw + _i * 8192), 16, 0, 0); } while (0)
; #define PG8_LDA(dst, b, h) do { _Pragma("unroll") for (int m = 0; m < 4; ++m) _Pragma("unroll") for (int k = 0; k < 2; ++k) dst[m][k] = *(const PG8_LAS bf16x8*)(lds + PG8_SA(b, h) + aoff + m * 2048 + k * 1024); } while (0)
; #define PG8_WAIT_V(n) asm volatile("s_waitcnt vmcnt(" #n ")" ::: "memory")
; #define PG8_WAIT_L(n) asm volatile("s_waitcnt lgkmcnt(" #n ")" ::: "memory")
;     ...
;         for (int t = 0; t < nt * KREP; t += 2) {
;             const bool last = (t == nt * KREP - 2);
;             const int t1w = KREP > 1 ? ((t + 1) & (nt - 1)) : t + 1, t2w = KREP > 1 ? ((t + 2) & (nt - 1)) : t + 2;
;             const char* a1 = cA + (size_t)t1w * kstep;
;             const char* a2 = last ? nA : cA + (size_t)t2w * kstep; const char* b2 = last ? nB : cB + (size_t)t2w * kstep;
;             const char* a3 = a2 + kstep; const char* b3 = b2 + kstep;
;             if (last && has_next) S.a_ready(nxt);
;             const int relax = __builtin_amdgcn_readfirstlane((MK_RELAXW && t == 0 && ui > 0) ? 1 : 0);
;             if constexpr (SP2) {
;             PG8_LDB(B0, 0, 0); PG8_LDB(B1, 0, 1); PG8_SCHED; PG8_LDA(At, 0, 0); PG8_STAGE(PG8_SA(1, 1), a1 + hstep, voffA);
;             PG8_WAIT_V_SEL(relax);
;             PG8_WAIT_L(0); PG8_BAR; PG8_MMA(0, 0, At, B0); PG8_MMA(0, 1, At, B1); PG8_BAR; PG8_SCHED;
;             PG8_LDA(At, 0, 1); PG8_STAGE(PG8_SB(0, 0), b2, voffB); PG8_STAGE(PG8_SB(0, 1), b2 + hstep, voffB); PG8_STAGE(PG8_SA(0, 0), a2, voffA);
;             PG8_WAIT_V_SEL(relax);
;             PG8_WAIT_L(0); PG8_BAR; PG8_MMA(1, 0, At, B0); PG8_MMA(1, 1, At, B1); PG8_BAR; PG8_SCHED;
;             PG8_LDB(B0, 1, 0); PG8_LDB(B1, 1, 1); PG8_SCHED; PG8_LDA(At, 1, 0); PG8_STAGE(PG8_SA(0, 1), a2 + hstep, voffA);
;             PG8_WAIT_V(8); PG8_WAIT_L(0); PG8_BAR; PG8_MMA(0, 0, At, B0); PG8_MMA(0, 1, At, B1); PG8_BAR; PG8_SCHED;
;             PG8_LDA(At, 1, 1); PG8_STAGE(PG8_SB(1, 0), b3, voffB); PG8_STAGE(PG8_SB(1, 1), b3 + hstep, voffB); PG8_STAGE(PG8_SA(1, 0), a3, voffA);
;             PG8_WAIT_V(8); PG8_WAIT_L(0); PG8_BAR; PG8_MMA(1, 0, At, B0); PG8_MMA(1, 1, At, B1); PG8_BAR; PG8_SCHED;
	s_setprio 0
	s_add_i32 s8, s46, s90
	s_mov_b32 m0, s8
	ds_read_b128 v[162:165], v246 offset:49152
	ds_read_b128 v[166:169], v246 offset:50176
	ds_read_b128 v[170:173], v246 offset:51200
	ds_read_b128 v[174:177], v246 offset:52224
	ds_read_b128 v[184:187], v246 offset:53248
	ds_read_b128 v[194:197], v246 offset:54272
	ds_read_b128 v[198:201], v246 offset:55296
	ds_read_b128 v[202:205], v246 offset:56320
	s_add_u32 s100, s80, 0x80
	s_addc_u32 s101, s81, 0
	global_load_lds_dwordx4 v182, s[100:101]
	s_add_i32 m0, s8, 0x2000
	s_add_u32 s8, s80, 0x158080
	s_addc_u32 s9, s81, 0
	s_add_i32 vcc_lo, s47, s90
	global_load_lds_dwordx4 v188, s[100:101]
	s_mov_b32 m0, vcc_lo
	s_nop 0
	global_load_lds_dwordx4 v182, s[8:9]
	s_add_i32 m0, vcc_lo, 0x2000
	s_nop 0
	global_load_lds_dwordx4 v188, s[8:9]
	s_mov_b32 m0, s31
	s_nop 0
	s_add_u32 s100, s40, 0x80
	s_addc_u32 s101, s41, 0
	global_load_lds_dwordx4 v178, s[100:101]
	s_mov_b32 m0, s56
	s_nop 0
	global_load_lds_dwordx4 v180, s[100:101]
	s_waitcnt vmcnt(8)
	s_waitcnt lgkmcnt(0)
	.p2align 3
	s_setprio 1
	s_barrier
	v_mfma_f32_16x16x32_bf16 v[70:73], v[58:61], v[162:165], v[70:73]
	v_mfma_f32_16x16x32_bf16 v[70:73], v[62:65], v[166:169], v[70:73]
	v_mfma_f32_16x16x32_bf16 v[46:49], v[58:61], v[170:173], v[46:49]
	v_mfma_f32_16x16x32_bf16 v[46:49], v[62:65], v[174:177], v[46:49]
	v_mfma_f32_16x16x32_bf16 v[30:33], v[58:61], v[184:187], v[30:33]
	v_mfma_f32_16x16x32_bf16 v[30:33], v[62:65], v[194:197], v[30:33]
	v_mfma_f32_16x16x32_bf16 v[14:17], v[58:61], v[198:201], v[14:17]
	v_mfma_f32_16x16x32_bf16 v[14:17], v[62:65], v[202:205], v[14:17]
	v_mfma_f32_16x16x32_bf16 v[10:13], v[74:77], v[198:201], v[10:13]
	v_mfma_f32_16x16x32_bf16 v[10:13], v[78:81], v[202:205], v[10:13]
	v_mfma_f32_16x16x32_bf16 v[26:29], v[74:77], v[184:187], v[26:29]
	v_mfma_f32_16x16x32_bf16 v[26:29], v[78:81], v[194:197], v[26:29]
	v_mfma_f32_16x16x32_bf16 v[42:45], v[74:77], v[170:173], v[42:45]
	v_mfma_f32_16x16x32_bf16 v[42:45], v[78:81], v[174:177], v[42:45]
	v_mfma_f32_16x16x32_bf16 v[66:69], v[74:77], v[162:165], v[66:69]
	v_mfma_f32_16x16x32_bf16 v[66:69], v[78:81], v[166:169], v[66:69]
	v_mfma_f32_16x16x32_bf16 v[54:57], v[130:133], v[162:165], v[54:57]
	v_mfma_f32_16x16x32_bf16 v[54:57], v[142:145], v[166:169], v[54:57]
	v_mfma_f32_16x16x32_bf16 v[38:41], v[130:133], v[170:173], v[38:41]
	v_mfma_f32_16x16x32_bf16 v[38:41], v[142:145], v[174:177], v[38:41]
	v_mfma_f32_16x16x32_bf16 v[22:25], v[130:133], v[184:187], v[22:25]
	v_mfma_f32_16x16x32_bf16 v[22:25], v[142:145], v[194:197], v[22:25]
	v_mfma_f32_16x16x32_bf16 v[6:9], v[130:133], v[198:201], v[6:9]
	v_mfma_f32_16x16x32_bf16 v[6:9], v[142:145], v[202:205], v[6:9]
	v_mfma_f32_16x16x32_bf16 v[2:5], v[154:157], v[198:201], v[2:5]
	v_mfma_f32_16x16x32_bf16 v[2:5], v[158:161], v[202:205], v[2:5]
	v_mfma_f32_16x16x32_bf16 v[18:21], v[154:157], v[184:187], v[18:21]
	v_mfma_f32_16x16x32_bf16 v[18:21], v[158:161], v[194:197], v[18:21]
	v_mfma_f32_16x16x32_bf16 v[34:37], v[154:157], v[170:173], v[34:37]
	v_mfma_f32_16x16x32_bf16 v[34:37], v[158:161], v[174:177], v[34:37]
	v_mfma_f32_16x16x32_bf16 v[50:53], v[154:157], v[162:165], v[50:53]
	v_mfma_f32_16x16x32_bf16 v[50:53], v[158:161], v[166:169], v[50:53]
	s_barrier
	s_setprio 0
	s_add_i32 s45, s45, 2
	s_add_u32 s37, s37, 0x100
	s_addc_u32 s44, s44, 0
	s_cmpk_gt_u32 s45, 0x53
	s_mov_b64 s[8:9], s[10:11]
	s_cbranch_scc0 .LBB0_1648
	s_branch .Lpeel_1648_x
.LBB0_1648:
	s_add_u32 s10, s8, 0x100
	s_addc_u32 s11, s9, 0
	s_add_i32 s46, 0, 0x10000
	s_cmpk_eq_i32 s45, 0x52
	s_cselect_b32 s41, s1, s11
	s_cselect_b32 s40, s0, s10
	s_cselect_b32 s81, s79, s44
	s_cselect_b32 s80, s78, s37
	s_add_i32 s47, 0, 0x14000
	ds_read_b128 v[58:61], v206
	ds_read_b128 v[62:65], v206 offset:1024
	ds_read_b128 v[74:77], v206 offset:2048
	ds_read_b128 v[78:81], v206 offset:3072
	ds_read_b128 v[130:133], v206 offset:16384
	ds_read_b128 v[142:145], v206 offset:17408
	ds_read_b128 v[154:157], v206 offset:18432
	ds_read_b128 v[158:161], v206 offset:19456
	s_add_i32 m0, s91, 0xc000
	ds_read_b128 v[162:165], v246
	ds_read_b128 v[166:169], v246 offset:1024
	ds_read_b128 v[170:173], v246 offset:2048
	ds_read_b128 v[174:177], v246 offset:3072
	ds_read_b128 v[184:187], v246 offset:4096
	ds_read_b128 v[194:197], v246 offset:5120
	ds_read_b128 v[198:201], v246 offset:6144
	ds_read_b128 v[202:205], v246 offset:7168
	global_load_lds_dwordx4 v190, s[8:9]
	s_add_i32 m0, s91, 0xe000
	s_nop 0
	global_load_lds_dwordx4 v192, s[8:9]
	s_waitcnt vmcnt(8)
	s_waitcnt lgkmcnt(0)
	.p2align 3
	s_setprio 1
	s_barrier
; #define PG8_STAGE(bufoff, gbase, voff) do { _Pragma("unroll") for (int _i = 0; _i < 2; ++_i) \
;         __builtin_amdgcn_global_load_lds((const unsigned*)((const char*)(gbase) + (voff)[_i]), (PG8_LAS unsigned*)(lds + (bufoff) + ldsw + _i * 8192), 16, 0, 0); } while (0)
; #define PG8_LDA(dst, b, h) do { _Pragma("unroll") for (int m = 0; m < 4; ++m) _Pragma("unroll") for (int k = 0; k < 2; ++k) dst[m][k] = *(const PG8_LAS bf16x8*)(lds + PG8_SA(b, h) + aoff + m * 2048 + k * 1024); } while (0)
; #define PG8_LDB(dst, b, h) do { _Pragma("unroll") for (int n = 0; n < 2; ++n) _Pragma("unroll") for (int k = 0; k < 2; ++k) dst[n][k] = *(const PG8_LAS bf16x8*)(lds + PG8_SB(b, h) + boff + n * 2048 + k * 1024); } while (0)
; #define PG8_WAIT_V(n) asm volatile("s_waitcnt vmcnt(" #n ")" ::: "memory")
; #define PG8_WAIT_L(n) asm volatile("s_waitcnt lgkmcnt(" #n ")" ::: "memory")
; #define PG8_WAIT_V_SEL(sel) asm volatile("s_cmp_eq_u32 %0, 0\n\ts_cbranch_scc1 .Lw8_%=\n\ts_waitcnt vmcnt(22)\n\ts_branch .Lwd_%=\n.Lw8_%=:\n\ts_waitcnt vmcnt(8)\n.Lwd_%=:" :: "s"(sel) : "memory", "scc")
; #define PG8_BAR __builtin_amdgcn_s_barrier()
; #define PG8_SCHED __builtin_amdgcn_sched_barrier(0)
;     ...
;             PG8_LDB(B0, 0, 0); PG8_LDB(B1, 0, 1); PG8_SCHED; PG8_LDA(At, 0, 0); PG8_STAGE(PG8_SA(1, 1), a1 + hstep, voffA);
;             PG8_WAIT_V_SEL(relax);
;             PG8_WAIT_L(0); PG8_BAR; PG8_MMA(0, 0, At, B0); PG8_MMA(0, 1, At, B1); PG8_BAR; PG8_SCHED;
;             PG8_LDA(At, 0, 1); PG8_STAGE(PG8_SB(0, 0), b2, voffB); PG8_STAGE(PG8_SB(0, 1), b2 + hstep, voffB); PG8_STAGE(PG8_SA(0, 0), a2, voffA);
;             PG8_WAIT_V_SEL(relax);
;             PG8_WAIT_L(0); PG8_BAR; PG8_MMA(1, 0, At, B0); PG8_MMA(1, 1, At, B1); PG8_BAR; PG8_SCHED;
;             PG8_LDB(B0, 1, 0); PG8_LDB(B1, 1, 1); PG8_SCHED; PG8_LDA(At, 1, 0); PG8_STAGE(PG8_SA(0, 1), a2 + hstep, voffA);
;             PG8_WAIT_V(8); PG8_WAIT_L(0); PG8_BAR; PG8_MMA(0, 0, At, B0); PG8_MMA(0, 1, At, B1); PG8_BAR; PG8_SCHED;
	v_mfma_f32_16x16x32_bf16 v[150:153], v[58:61], v[162:165], v[150:153]
	v_mfma_f32_16x16x32_bf16 v[150:153], v[62:65], v[166:169], v[150:153]
	v_mfma_f32_16x16x32_bf16 v[126:129], v[58:61], v[170:173], v[126:129]
	v_mfma_f32_16x16x32_bf16 v[126:129], v[62:65], v[174:177], v[126:129]
	v_mfma_f32_16x16x32_bf16 v[110:113], v[58:61], v[184:187], v[110:113]
	v_mfma_f32_16x16x32_bf16 v[110:113], v[62:65], v[194:197], v[110:113]
	v_mfma_f32_16x16x32_bf16 v[94:97], v[58:61], v[198:201], v[94:97]
	v_mfma_f32_16x16x32_bf16 v[94:97], v[62:65], v[202:205], v[94:97]
	v_mfma_f32_16x16x32_bf16 v[90:93], v[74:77], v[198:201], v[90:93]
	v_mfma_f32_16x16x32_bf16 v[90:93], v[78:81], v[202:205], v[90:93]
	v_mfma_f32_16x16x32_bf16 v[106:109], v[74:77], v[184:187], v[106:109]
	v_mfma_f32_16x16x32_bf16 v[106:109], v[78:81], v[194:197], v[106:109]
	v_mfma_f32_16x16x32_bf16 v[122:125], v[74:77], v[170:173], v[122:125]
	v_mfma_f32_16x16x32_bf16 v[122:125], v[78:81], v[174:177], v[122:125]
	v_mfma_f32_16x16x32_bf16 v[146:149], v[74:77], v[162:165], v[146:149]
	v_mfma_f32_16x16x32_bf16 v[146:149], v[78:81], v[166:169], v[146:149]
	v_mfma_f32_16x16x32_bf16 v[138:141], v[130:133], v[162:165], v[138:141]
	v_mfma_f32_16x16x32_bf16 v[138:141], v[142:145], v[166:169], v[138:141]
	v_mfma_f32_16x16x32_bf16 v[118:121], v[130:133], v[170:173], v[118:121]
	v_mfma_f32_16x16x32_bf16 v[118:121], v[142:145], v[174:177], v[118:121]
	v_mfma_f32_16x16x32_bf16 v[102:105], v[130:133], v[184:187], v[102:105]
	v_mfma_f32_16x16x32_bf16 v[102:105], v[142:145], v[194:197], v[102:105]
	v_mfma_f32_16x16x32_bf16 v[86:89], v[130:133], v[198:201], v[86:89]
	v_mfma_f32_16x16x32_bf16 v[86:89], v[142:145], v[202:205], v[86:89]
	v_mfma_f32_16x16x32_bf16 v[82:85], v[154:157], v[198:201], v[82:85]
	v_mfma_f32_16x16x32_bf16 v[82:85], v[158:161], v[202:205], v[82:85]
	v_mfma_f32_16x16x32_bf16 v[98:101], v[154:157], v[184:187], v[98:101]
	v_mfma_f32_16x16x32_bf16 v[98:101], v[158:161], v[194:197], v[98:101]
	v_mfma_f32_16x16x32_bf16 v[114:117], v[154:157], v[170:173], v[114:117]
	v_mfma_f32_16x16x32_bf16 v[114:117], v[158:161], v[174:177], v[114:117]
	v_mfma_f32_16x16x32_bf16 v[134:137], v[154:157], v[162:165], v[134:137]
	v_mfma_f32_16x16x32_bf16 v[134:137], v[158:161], v[166:169], v[134:137]
	s_barrier
	s_setprio 0
	s_add_i32 s8, s46, s90
	s_mov_b32 m0, s8
	ds_read_b128 v[162:165], v246 offset:16384
	ds_read_b128 v[166:169], v246 offset:17408
	ds_read_b128 v[170:173], v246 offset:18432
	ds_read_b128 v[174:177], v246 offset:19456
	ds_read_b128 v[184:187], v246 offset:20480
	ds_read_b128 v[194:197], v246 offset:21504
	ds_read_b128 v[198:201], v246 offset:22528
	ds_read_b128 v[202:205], v246 offset:23552
	global_load_lds_dwordx4 v182, s[80:81]
	s_add_i32 m0, s8, 0x2000
	s_add_u32 s8, s80, 0x158000
	s_addc_u32 s9, s81, 0
	s_add_i32 s46, s47, s90
	global_load_lds_dwordx4 v188, s[80:81]
	s_mov_b32 m0, s46
	s_nop 0
	global_load_lds_dwordx4 v182, s[8:9]
	s_add_i32 m0, s46, 0x2000
	s_nop 0
	global_load_lds_dwordx4 v188, s[8:9]
	s_mov_b32 m0, s91
	s_nop 0
	global_load_lds_dwordx4 v178, s[40:41]
	s_mov_b32 m0, s92
	s_nop 0
	global_load_lds_dwordx4 v180, s[40:41]
	s_waitcnt vmcnt(8)
	s_waitcnt lgkmcnt(0)
	.p2align 3
	s_setprio 1
	s_barrier
	v_mfma_f32_16x16x32_bf16 v[70:73], v[58:61], v[162:165], v[70:73]
	v_mfma_f32_16x16x32_bf16 v[70:73], v[62:65], v[166:169], v[70:73]
	v_mfma_f32_16x16x32_bf16 v[46:49], v[58:61], v[170:173], v[46:49]
	v_mfma_f32_16x16x32_bf16 v[46:49], v[62:65], v[174:177], v[46:49]
	v_mfma_f32_16x16x32_bf16 v[30:33], v[58:61], v[184:187], v[30:33]
	v_mfma_f32_16x16x32_bf16 v[30:33], v[62:65], v[194:197], v[30:33]
	v_mfma_f32_16x16x32_bf16 v[14:17], v[58:61], v[198:201], v[14:17]
	v_mfma_f32_16x16x32_bf16 v[14:17], v[62:65], v[202:205], v[14:17]
	v_mfma_f32_16x16x32_bf16 v[10:13], v[74:77], v[198:201], v[10:13]
	v_mfma_f32_16x16x32_bf16 v[10:13], v[78:81], v[202:205], v[10:13]
	v_mfma_f32_16x16x32_bf16 v[26:29], v[74:77], v[184:187], v[26:29]
	v_mfma_f32_16x16x32_bf16 v[26:29], v[78:81], v[194:197], v[26:29]
	v_mfma_f32_16x16x32_bf16 v[42:45], v[74:77], v[170:173], v[42:45]
	v_mfma_f32_16x16x32_bf16 v[42:45], v[78:81], v[174:177], v[42:45]
	v_mfma_f32_16x16x32_bf16 v[66:69], v[74:77], v[162:165], v[66:69]
	v_mfma_f32_16x16x32_bf16 v[66:69], v[78:81], v[166:169], v[66:69]
	v_mfma_f32_16x16x32_bf16 v[54:57], v[130:133], v[162:165], v[54:57]
	v_mfma_f32_16x16x32_bf16 v[54:57], v[142:145], v[166:169], v[54:57]
	v_mfma_f32_16x16x32_bf16 v[38:41], v[130:133], v[170:173], v[38:41]
	v_mfma_f32_16x16x32_bf16 v[38:41], v[142:145], v[174:177], v[38:41]
	v_mfma_f32_16x16x32_bf16 v[22:25], v[130:133], v[184:187], v[22:25]
	v_mfma_f32_16x16x32_bf16 v[22:25], v[142:145], v[194:197], v[22:25]
	v_mfma_f32_16x16x32_bf16 v[6:9], v[130:133], v[198:201], v[6:9]
	v_mfma_f32_16x16x32_bf16 v[6:9], v[142:145], v[202:205], v[6:9]
	v_mfma_f32_16x16x32_bf16 v[2:5], v[154:157], v[198:201], v[2:5]
	v_mfma_f32_16x16x32_bf16 v[2:5], v[158:161], v[202:205], v[2:5]
	v_mfma_f32_16x16x32_bf16 v[18:21], v[154:157], v[184:187], v[18:21]
	v_mfma_f32_16x16x32_bf16 v[18:21], v[158:161], v[194:197], v[18:21]
	v_mfma_f32_16x16x32_bf16 v[34:37], v[154:157], v[170:173], v[34:37]
	v_mfma_f32_16x16x32_bf16 v[34:37], v[158:161], v[174:177], v[34:37]
	v_mfma_f32_16x16x32_bf16 v[50:53], v[154:157], v[162:165], v[50:53]
	v_mfma_f32_16x16x32_bf16 v[50:53], v[158:161], v[166:169], v[50:53]
	s_barrier
; #define PG8_STAGE(bufoff, gbase, voff) do { _Pragma("unroll") for (int _i = 0; _i < 2; ++_i) \
;         __builtin_amdgcn_global_load_lds((const unsigned*)((const char*)(gbase) + (voff)[_i]), (PG8_LAS unsigned*)(lds + (bufoff) + ldsw + _i * 8192), 16, 0, 0); } while (0)
; #define PG8_LDA(dst, b, h) do { _Pragma("unroll") for (int m = 0; m < 4; ++m) _Pragma("unroll") for (int k = 0; k < 2; ++k) dst[m][k] = *(const PG8_LAS bf16x8*)(lds + PG8_SA(b, h) + aoff + m * 2048 + k * 1024); } while (0)
; #define PG8_LDB(dst, b, h) do { _Pragma("unroll") for (int n = 0; n < 2; ++n) _Pragma("unroll") for (int k = 0; k < 2; ++k) dst[n][k] = *(const PG8_LAS bf16x8*)(lds + PG8_SB(b, h) + boff + n * 2048 + k * 1024); } while (0)
; #define PG8_WAIT_V(n) asm volatile("s_waitcnt vmcnt(" #n ")" ::: "memory")
; #define PG8_WAIT_L(n) asm volatile("s_waitcnt lgkmcnt(" #n ")" ::: "memory")
; #define PG8_BAR __builtin_amdgcn_s_barrier()
; #define PG8_SCHED __builtin_amdgcn_sched_barrier(0)
;     ...
;             PG8_LDB(B0, 1, 0); PG8_LDB(B1, 1, 1); PG8_SCHED; PG8_LDA(At, 1, 0); PG8_STAGE(PG8_SA(0, 1), a2 + hstep, voffA);
;             PG8_WAIT_V(8); PG8_WAIT_L(0); PG8_BAR; PG8_MMA(0, 0, At, B0); PG8_MMA(0, 1, At, B1); PG8_BAR; PG8_SCHED;
;             PG8_LDA(At, 1, 1); PG8_STAGE(PG8_SB(1, 0), b3, voffB); PG8_STAGE(PG8_SB(1, 1), b3 + hstep, voffB); PG8_STAGE(PG8_SA(1, 0), a3, voffA);
;             PG8_WAIT_V(8); PG8_WAIT_L(0); PG8_BAR; PG8_MMA(1, 0, At, B0); PG8_MMA(1, 1, At, B1); PG8_BAR; PG8_SCHED;
	s_setprio 0
	s_add_i32 s46, 0, 0x18000
	s_add_i32 s47, 0, 0x1c000
	ds_read_b128 v[58:61], v206 offset:32768
	ds_read_b128 v[62:65], v206 offset:33792
	ds_read_b128 v[74:77], v206 offset:34816
	ds_read_b128 v[78:81], v206 offset:35840
	ds_read_b128 v[130:133], v206 offset:49152
	ds_read_b128 v[142:145], v206 offset:50176
	ds_read_b128 v[154:157], v206 offset:51200
	ds_read_b128 v[158:161], v206 offset:52224
	s_add_u32 s8, s40, 0x158000
	s_addc_u32 s9, s41, 0
	s_mov_b32 m0, s93
	ds_read_b128 v[162:165], v246 offset:32768
	ds_read_b128 v[166:169], v246 offset:33792
	ds_read_b128 v[170:173], v246 offset:34816
	ds_read_b128 v[174:177], v246 offset:35840
	ds_read_b128 v[184:187], v246 offset:36864
	ds_read_b128 v[194:197], v246 offset:37888
	ds_read_b128 v[198:201], v246 offset:38912
	ds_read_b128 v[202:205], v246 offset:39936
	global_load_lds_dwordx4 v178, s[8:9]
	s_mov_b32 m0, s94
	s_nop 0
	global_load_lds_dwordx4 v180, s[8:9]
	s_waitcnt vmcnt(8)
	s_waitcnt lgkmcnt(0)
	.p2align 3
	s_setprio 1
	s_barrier
	v_mfma_f32_16x16x32_bf16 v[150:153], v[58:61], v[162:165], v[150:153]
	v_mfma_f32_16x16x32_bf16 v[150:153], v[62:65], v[166:169], v[150:153]
	v_mfma_f32_16x16x32_bf16 v[126:129], v[58:61], v[170:173], v[126:129]
	v_mfma_f32_16x16x32_bf16 v[126:129], v[62:65], v[174:177], v[126:129]
	v_mfma_f32_16x16x32_bf16 v[110:113], v[58:61], v[184:187], v[110:113]
	v_mfma_f32_16x16x32_bf16 v[110:113], v[62:65], v[194:197], v[110:113]
	v_mfma_f32_16x16x32_bf16 v[94:97], v[58:61], v[198:201], v[94:97]
	v_mfma_f32_16x16x32_bf16 v[94:97], v[62:65], v[202:205], v[94:97]
	v_mfma_f32_16x16x32_bf16 v[90:93], v[74:77], v[198:201], v[90:93]
	v_mfma_f32_16x16x32_bf16 v[90:93], v[78:81], v[202:205], v[90:93]
	v_mfma_f32_16x16x32_bf16 v[106:109], v[74:77], v[184:187], v[106:109]
	v_mfma_f32_16x16x32_bf16 v[106:109], v[78:81], v[194:197], v[106:109]
	v_mfma_f32_16x16x32_bf16 v[122:125], v[74:77], v[170:173], v[122:125]
	v_mfma_f32_16x16x32_bf16 v[122:125], v[78:81], v[174:177], v[122:125]
	v_mfma_f32_16x16x32_bf16 v[146:149], v[74:77], v[162:165], v[146:149]
	v_mfma_f32_16x16x32_bf16 v[146:149], v[78:81], v[166:169], v[146:149]
	v_mfma_f32_16x16x32_bf16 v[138:141], v[130:133], v[162:165], v[138:141]
	v_mfma_f32_16x16x32_bf16 v[138:141], v[142:145], v[166:169], v[138:141]
	v_mfma_f32_16x16x32_bf16 v[118:121], v[130:133], v[170:173], v[118:121]
	v_mfma_f32_16x16x32_bf16 v[118:121], v[142:145], v[174:177], v[118:121]
	v_mfma_f32_16x16x32_bf16 v[102:105], v[130:133], v[184:187], v[102:105]
	v_mfma_f32_16x16x32_bf16 v[102:105], v[142:145], v[194:197], v[102:105]
	v_mfma_f32_16x16x32_bf16 v[86:89], v[130:133], v[198:201], v[86:89]
	v_mfma_f32_16x16x32_bf16 v[86:89], v[142:145], v[202:205], v[86:89]
	v_mfma_f32_16x16x32_bf16 v[82:85], v[154:157], v[198:201], v[82:85]
	v_mfma_f32_16x16x32_bf16 v[82:85], v[158:161], v[202:205], v[82:85]
	v_mfma_f32_16x16x32_bf16 v[98:101], v[154:157], v[184:187], v[98:101]
	v_mfma_f32_16x16x32_bf16 v[98:101], v[158:161], v[194:197], v[98:101]
	v_mfma_f32_16x16x32_bf16 v[114:117], v[154:157], v[170:173], v[114:117]
	v_mfma_f32_16x16x32_bf16 v[114:117], v[158:161], v[174:177], v[114:117]
	v_mfma_f32_16x16x32_bf16 v[134:137], v[154:157], v[162:165], v[134:137]
	v_mfma_f32_16x16x32_bf16 v[134:137], v[158:161], v[166:169], v[134:137]
	s_barrier
	s_setprio 0
	s_add_i32 s8, s46, s90
	s_mov_b32 m0, s8
	ds_read_b128 v[162:165], v246 offset:49152
	ds_read_b128 v[166:169], v246 offset:50176
	ds_read_b128 v[170:173], v246 offset:51200
	ds_read_b128 v[174:177], v246 offset:52224
	ds_read_b128 v[184:187], v246 offset:53248
	ds_read_b128 v[194:197], v246 offset:54272
	ds_read_b128 v[198:201], v246 offset:55296
	ds_read_b128 v[202:205], v246 offset:56320
	s_add_u32 s100, s80, 0x80
	s_addc_u32 s101, s81, 0
	global_load_lds_dwordx4 v182, s[100:101]
	s_add_i32 m0, s8, 0x2000
	s_add_u32 s8, s80, 0x158080
	s_addc_u32 s9, s81, 0
	s_add_i32 vcc_lo, s47, s90
	global_load_lds_dwordx4 v188, s[100:101]
	s_mov_b32 m0, vcc_lo
	s_nop 0
	global_load_lds_dwordx4 v182, s[8:9]
	s_add_i32 m0, vcc_lo, 0x2000
	s_nop 0
	global_load_lds_dwordx4 v188, s[8:9]
	s_mov_b32 m0, s31
	s_nop 0
	s_add_u32 s100, s40, 0x80
	s_addc_u32 s101, s41, 0
	global_load_lds_dwordx4 v178, s[100:101]
	s_mov_b32 m0, s56
	s_nop 0
	global_load_lds_dwordx4 v180, s[100:101]
	s_waitcnt vmcnt(8)
	s_waitcnt lgkmcnt(0)
	.p2align 3
	s_setprio 1
	s_barrier
	v_mfma_f32_16x16x32_bf16 v[70:73], v[58:61], v[162:165], v[70:73]
	v_mfma_f32_16x16x32_bf16 v[70:73], v[62:65], v[166:169], v[70:73]
	v_mfma_f32_16x16x32_bf16 v[46:49], v[58:61], v[170:173], v[46:49]
	v_mfma_f32_16x16x32_bf16 v[46:49], v[62:65], v[174:177], v[46:49]
	v_mfma_f32_16x16x32_bf16 v[30:33], v[58:61], v[184:187], v[30:33]
	v_mfma_f32_16x16x32_bf16 v[30:33], v[62:65], v[194:197], v[30:33]
	v_mfma_f32_16x16x32_bf16 v[14:17], v[58:61], v[198:201], v[14:17]
	v_mfma_f32_16x16x32_bf16 v[14:17], v[62:65], v[202:205], v[14:17]
	v_mfma_f32_16x16x32_bf16 v[10:13], v[74:77], v[198:201], v[10:13]
	v_mfma_f32_16x16x32_bf16 v[10:13], v[78:81], v[202:205], v[10:13]
	v_mfma_f32_16x16x32_bf16 v[26:29], v[74:77], v[184:187], v[26:29]
	v_mfma_f32_16x16x32_bf16 v[26:29], v[78:81], v[194:197], v[26:29]
	v_mfma_f32_16x16x32_bf16 v[42:45], v[74:77], v[170:173], v[42:45]
	v_mfma_f32_16x16x32_bf16 v[42:45], v[78:81], v[174:177], v[42:45]
	v_mfma_f32_16x16x32_bf16 v[66:69], v[74:77], v[162:165], v[66:69]
	v_mfma_f32_16x16x32_bf16 v[66:69], v[78:81], v[166:169], v[66:69]
	v_mfma_f32_16x16x32_bf16 v[54:57], v[130:133], v[162:165], v[54:57]
	v_mfma_f32_16x16x32_bf16 v[54:57], v[142:145], v[166:169], v[54:57]
	v_mfma_f32_16x16x32_bf16 v[38:41], v[130:133], v[170:173], v[38:41]
	v_mfma_f32_16x16x32_bf16 v[38:41], v[142:145], v[174:177], v[38:41]
	v_mfma_f32_16x16x32_bf16 v[22:25], v[130:133], v[184:187], v[22:25]
	v_mfma_f32_16x16x32_bf16 v[22:25], v[142:145], v[194:197], v[22:25]
	v_mfma_f32_16x16x32_bf16 v[6:9], v[130:133], v[198:201], v[6:9]
	v_mfma_f32_16x16x32_bf16 v[6:9], v[142:145], v[202:205], v[6:9]
	v_mfma_f32_16x16x32_bf16 v[2:5], v[154:157], v[198:201], v[2:5]
	v_mfma_f32_16x16x32_bf16 v[2:5], v[158:161], v[202:205], v[2:5]
	v_mfma_f32_16x16x32_bf16 v[18:21], v[154:157], v[184:187], v[18:21]
	v_mfma_f32_16x16x32_bf16 v[18:21], v[158:161], v[194:197], v[18:21]
	v_mfma_f32_16x16x32_bf16 v[34:37], v[154:157], v[170:173], v[34:37]
	v_mfma_f32_16x16x32_bf16 v[34:37], v[158:161], v[174:177], v[34:37]
	v_mfma_f32_16x16x32_bf16 v[50:53], v[154:157], v[162:165], v[50:53]
	v_mfma_f32_16x16x32_bf16 v[50:53], v[158:161], v[166:169], v[50:53]
	s_barrier
	s_setprio 0
	s_add_i32 s45, s45, 2
	s_add_u32 s37, s37, 0x100
	s_addc_u32 s44, s44, 0
	s_cmpk_gt_u32 s45, 0x53
	s_mov_b64 s[8:9], s[10:11]
	s_cbranch_scc0 .LBB0_1648
.Lpeel_1648_x:
	s_branch .Lrlx_f2_x
.Lrlx_f2_0:
	s_waitcnt vmcnt(22)
	s_branch .Lrlx_f2_0_b
